# fused LayerNorm int8 quantisation: round-to-nearest-even via add of 1.5*2^23 and byte packing with two v_perm + v_or (7 VALU per dword instead of 13, bit-identical)
# speedup vs baseline: 1.0163x; 1.0163x over previous
.LBB0_469:
	s_mov_b32 s100, 0x4b400000
	s_mov_b32 s101, 0xc04000c
	s_waitcnt vmcnt(0) lgkmcnt(0)
	s_barrier
	ds_read_b32 v32, v231 offset:10240
	s_and_saveexec_b64 s[10:11], s[8:9]
	s_cbranch_execz .LBB0_471
	v_readlane_b32 s8, v254, 5
	v_lshlrev_b64 v[2:3], 5, v[0:1]
	v_readlane_b32 s9, v254, 6
	s_nop 1
	v_lshl_add_u64 v[2:3], s[8:9], 0, v[2:3]
	global_load_dwordx2 v[6:7], v[2:3], off sc1
	global_load_dwordx2 v[34:35], v[2:3], off offset:8 sc1
	global_load_dwordx2 v[36:37], v[2:3], off offset:16 sc1
	global_load_dwordx2 v[38:39], v[2:3], off offset:24 sc1
	s_waitcnt vmcnt(0)
	v_add_f32_e32 v5, 0, v6
	v_add_f32_e32 v5, v5, v34
	v_add_f32_e32 v5, v5, v36
	v_add_f32_e32 v3, v5, v38
	v_fmamk_f32 v5, v3, 0xbe800000, v6
	v_mul_f32_e32 v6, 0x43800000, v5
	v_fmac_f32_e32 v7, v5, v6
	v_fmamk_f32 v6, v3, 0xbe800000, v34
	v_add_f32_e32 v5, 0, v7
	v_mul_f32_e32 v7, 0x43800000, v6
	v_fmac_f32_e32 v35, v6, v7
	v_fmamk_f32 v6, v3, 0xbe800000, v36
	v_mul_f32_e32 v2, 0x3e800000, v3
	v_mul_f32_e32 v7, 0x43800000, v6
	v_fmamk_f32 v3, v3, 0xbe800000, v38
	v_add_f32_e32 v5, v35, v5
	v_fmac_f32_e32 v37, v6, v7
	v_mul_f32_e32 v6, 0x43800000, v3
	v_add_f32_e32 v5, v37, v5
	v_fmac_f32_e32 v39, v3, v6
	v_add_f32_e32 v3, v39, v5
	v_fmamk_f32 v3, v3, 0x3a800000, v217
	v_cmp_gt_f32_e32 vcc, s79, v3
	v_mul_f32_e32 v5, 0x4f800000, v3
	s_nop 0
	v_cndmask_b32_e32 v3, v3, v5, vcc
	v_sqrt_f32_e32 v5, v3
	s_nop 0
	v_add_u32_e32 v6, -1, v5
	v_fma_f32 v7, -v6, v5, v3
	v_cmp_ge_f32_e64 s[8:9], 0, v7
	v_add_u32_e32 v7, 1, v5
	s_nop 0
	v_cndmask_b32_e64 v6, v5, v6, s[8:9]
	v_fma_f32 v5, -v7, v5, v3
	v_cmp_lt_f32_e64 s[8:9], 0, v5
	s_nop 1
	v_cndmask_b32_e64 v5, v6, v7, s[8:9]
	v_mul_f32_e32 v6, 0x37800000, v5
	v_cndmask_b32_e32 v5, v5, v6, vcc
	v_cmp_class_f32_e32 vcc, v3, v215
	s_nop 1
	v_cndmask_b32_e32 v3, v5, v3, vcc
	v_div_scale_f32 v5, s[8:9], v3, v3, 1.0
	v_rcp_f32_e32 v6, v5
	v_readlane_b32 s8, v253, 49
	v_readlane_b32 s9, v253, 50
	v_fma_f32 v7, -v5, v6, 1.0
	v_fmac_f32_e32 v6, v7, v6
	v_div_scale_f32 v7, vcc, 1.0, v3, 1.0
	v_mul_f32_e32 v33, v7, v6
	v_fma_f32 v34, -v5, v33, v7
	v_fmac_f32_e32 v33, v34, v6
	v_fma_f32 v5, -v5, v33, v7
	v_div_fmas_f32 v5, v5, v6, v33
	v_div_fixup_f32 v3, v5, v3, 1.0
	v_lshl_add_u32 v5, v4, 3, 0
	ds_write_b64 v5, v[2:3] offset:8192
	v_lshl_add_u64 v[0:1], v[0:1], 4, s[8:9]
	global_load_dword v6, v[0:1], off sc1
	global_load_dword v7, v[0:1], off offset:4 sc1
	s_waitcnt vmcnt(0)
	v_max3_f32 v6, v6, 0, v7
	global_load_dword v7, v[0:1], off offset:8 sc1
	s_nop 0
	global_load_dword v0, v[0:1], off offset:12 sc1
	v_mul_f32_e32 v1, s30, v3
	s_waitcnt vmcnt(0)
	v_max3_f32 v0, v6, v7, v0
	v_add_f32_e64 v0, |v2|, v0
	v_fma_f32 v0, v0, v1, s31
	v_lshlrev_b32_e32 v1, 2, v4
	v_sub_u32_e32 v1, v5, v1
	ds_write_b32 v1, v0 offset:12288

.LBB0_475:
	s_or_b64 exec, exec, s[12:13]
	v_sub_f32_e32 v113, v149, v32
	v_sub_f32_e32 v112, v148, v32
	v_pk_mul_f32 v[112:113], v[32:33], v[112:113] op_sel:[1,0]
	v_div_scale_f32 v97, s[12:13], v44, v44, s57
	s_waitcnt vmcnt(0)
	v_pk_fma_f32 v[112:113], v[0:1], v[112:113], v[4:5]
	v_sub_f32_e32 v99, v151, v32
	v_cndmask_b32_e64 v159, v113, v232, s[8:9]
	v_rcp_f32_e32 v113, v97
	v_cndmask_b32_e64 v158, v112, v232, s[8:9]
	v_sub_f32_e32 v98, v150, v32
	v_pk_mul_f32 v[98:99], v[32:33], v[98:99] op_sel:[1,0]
	v_fma_f32 v112, -v97, v113, 1.0
	v_fmac_f32_e32 v113, v112, v113
	v_div_scale_f32 v112, vcc, s57, v44, s57
	v_mul_f32_e32 v114, v112, v113
	v_fma_f32 v148, -v97, v114, v112
	v_fmac_f32_e32 v114, v148, v113
	v_fma_f32 v97, -v97, v114, v112
	v_div_fmas_f32 v97, v97, v113, v114
	v_pk_fma_f32 v[98:99], v[2:3], v[98:99], v[6:7]
	v_div_fixup_f32 v44, v97, v44, s57
	v_cndmask_b32_e64 v99, v99, v232, s[8:9]
	v_cndmask_b32_e64 v98, v98, v232, s[8:9]
	v_pk_mul_f32 v[148:149], v[44:45], v[158:159] op_sel_hi:[0,1]
	v_pk_mul_f32 v[112:113], v[44:45], v[98:99] op_sel_hi:[0,1]
	v_add_f32_e32 v114, s100, v149
	v_add_f32_e32 v97, s100, v148
	v_add_f32_e32 v112, s100, v112
	v_add_f32_e32 v113, s100, v113
	v_readlane_b32 s3, v254, 17
	v_perm_b32 v97, v113, v97, s56
	s_add_i32 s3, s3, s33
	v_perm_b32 v161, v112, v114, s101
	v_or_b32_e32 v161, v97, v161
	v_or_b32_e32 v149, s3, v96
	v_and_b32_e32 v96, -8, v179
	v_div_scale_f32 v114, s[12:13], v47, v47, s57
	v_ashrrev_i32_e32 v97, 31, v96
	s_mov_b32 s21, s1
	v_rcp_f32_e32 v148, v114
	v_lshl_add_u64 v[112:113], s[20:21], 0, v[96:97]
	v_sub_f32_e32 v97, v153, v38
	v_sub_f32_e32 v96, v152, v38
	v_pk_mul_f32 v[96:97], v[38:39], v[96:97] op_sel:[1,0]
	v_sub_f32_e32 v151, v155, v38
	v_pk_fma_f32 v[96:97], v[2:3], v[96:97], v[6:7]
	v_sub_f32_e32 v150, v154, v38
	v_cndmask_b32_e64 v152, v96, v232, s[8:9]
	v_fma_f32 v96, -v114, v148, 1.0
	v_pk_mul_f32 v[150:151], v[38:39], v[150:151] op_sel:[1,0]
	v_fmac_f32_e32 v148, v96, v148
	v_div_scale_f32 v96, vcc, s57, v47, s57
	v_pk_fma_f32 v[150:151], v[0:1], v[150:151], v[4:5]
	v_cndmask_b32_e64 v153, v97, v232, s[8:9]
	v_mul_f32_e32 v97, v96, v148
	v_cndmask_b32_e64 v154, v150, v232, s[8:9]
	v_fma_f32 v150, -v114, v97, v96
	v_fmac_f32_e32 v97, v150, v148
	v_fma_f32 v96, -v114, v97, v96
	v_div_fmas_f32 v96, v96, v148, v97
	v_cndmask_b32_e64 v155, v151, v232, s[8:9]
	v_div_fixup_f32 v114, v96, v47, s57
	v_pk_mul_f32 v[150:151], v[114:115], v[154:155] op_sel_hi:[0,1]
	v_pk_mul_f32 v[96:97], v[114:115], v[152:153] op_sel_hi:[0,1]
	v_add_f32_e32 v148, s100, v151
	v_add_f32_e32 v47, s100, v150
	v_add_f32_e32 v96, s100, v96
	v_add_f32_e32 v97, s100, v97
	v_perm_b32 v47, v97, v47, s56
	v_and_b32_e32 v151, 16, v178
	v_perm_b32 v160, v96, v148, s101
	v_or_b32_e32 v160, v47, v160
	v_or_b32_e32 v96, v149, v151
	v_ashrrev_i32_e32 v97, 31, v96
	v_lshlrev_b64 v[96:97], 10, v[96:97]
	v_lshl_add_u64 v[162:163], v[96:97], 0, v[112:113]
	v_cvt_pk_f16_f32 v153, v152, v153
	v_cvt_pk_f16_f32 v152, v154, v155
	v_cvt_pk_f16_f32 v155, v98, v99
	v_cvt_pk_f16_f32 v154, v158, v159
	s_nop 1
	v_permlane16_swap_b32_e32 v152, v154
	v_permlane16_swap_b32_e32 v153, v155
	v_lshl_add_u64 v[98:99], v[162:163], 1, s[60:61]
	global_store_dwordx4 v[98:99], v[152:155], off
	v_add_u32_e32 v47, v46, v115
	v_add_u32_e32 v46, v47, v156
	ds_read_b64 v[98:99], v47 offset:8448
	ds_read_b32 v47, v46 offset:12416
	v_permlane16_swap_b32_e32 v160, v161
	v_lshl_add_u64 v[152:153], s[72:73], 0, v[162:163]
	global_store_dwordx2 v[152:153], v[160:161], off
	s_waitcnt lgkmcnt(0)
	v_max_f32_e32 v47, v47, v47
	v_max_f32_e32 v148, 0xda24260, v47
	s_and_saveexec_b64 s[12:13], s[10:11]
	s_cbranch_execz .LBB0_477
	v_readlane_b32 s3, v254, 17
	v_mul_f32_e32 v47, 0x3c010204, v148
	v_cndmask_b32_e64 v47, v47, v232, s[8:9]
	v_add3_u32 v152, s3, v45, 32
	v_ashrrev_i32_e32 v153, 31, v152
	v_lshl_add_u64 v[152:153], v[152:153], 2, s[54:55]
	global_store_dword v[152:153], v47, off

.LBB0_479:
	s_or_b64 exec, exec, s[12:13]
	s_waitcnt lgkmcnt(0)
	v_sub_f32_e32 v109, v109, v46
	v_sub_f32_e32 v108, v108, v46
	v_pk_mul_f32 v[108:109], v[46:47], v[108:109] op_sel:[1,0]
	v_sub_f32_e32 v111, v111, v46
	v_pk_fma_f32 v[108:109], v[0:1], v[108:109], v[4:5]
	v_sub_f32_e32 v110, v110, v46
	v_cndmask_b32_e64 v159, v109, v232, s[8:9]
	v_div_scale_f32 v109, s[12:13], v152, v152, s57
	v_rcp_f32_e32 v153, v109
	v_cndmask_b32_e64 v158, v108, v232, s[8:9]
	v_pk_mul_f32 v[110:111], v[46:47], v[110:111] op_sel:[1,0]
	v_sub_f32_e32 v125, v125, v98
	v_fma_f32 v108, -v109, v153, 1.0
	v_fmac_f32_e32 v153, v108, v153
	v_div_scale_f32 v108, vcc, s57, v152, s57
	v_mul_f32_e32 v154, v108, v153
	v_fma_f32 v155, -v109, v154, v108
	v_fmac_f32_e32 v154, v155, v153
	v_fma_f32 v108, -v109, v154, v108
	v_div_fmas_f32 v108, v108, v153, v154
	v_pk_fma_f32 v[110:111], v[2:3], v[110:111], v[6:7]
	v_div_fixup_f32 v108, v108, v152, s57
	v_cndmask_b32_e64 v111, v111, v232, s[8:9]
	v_cndmask_b32_e64 v110, v110, v232, s[8:9]
	v_pk_mul_f32 v[154:155], v[108:109], v[158:159] op_sel_hi:[0,1]
	v_pk_mul_f32 v[152:153], v[108:109], v[110:111] op_sel_hi:[0,1]
	v_add_f32_e32 v109, s100, v154
	v_add_f32_e32 v154, s100, v155
	v_add_f32_e32 v152, s100, v152
	v_add_f32_e32 v153, s100, v153
	v_sub_f32_e32 v124, v124, v98
	v_perm_b32 v109, v153, v109, s56
	v_pk_mul_f32 v[124:125], v[98:99], v[124:125] op_sel:[1,0]
	v_perm_b32 v161, v152, v154, s101
	v_or_b32_e32 v161, v109, v161
	v_pk_fma_f32 v[124:125], v[0:1], v[124:125], v[4:5]
	v_div_scale_f32 v109, s[12:13], v148, v148, s57
	v_cndmask_b32_e64 v155, v125, v232, s[8:9]
	v_rcp_f32_e32 v125, v109
	v_cndmask_b32_e64 v154, v124, v232, s[8:9]
	v_sub_f32_e32 v127, v127, v98
	v_sub_f32_e32 v126, v126, v98
	v_fma_f32 v124, -v109, v125, 1.0
	v_fmac_f32_e32 v125, v124, v125
	v_div_scale_f32 v124, vcc, s57, v148, s57
	v_mul_f32_e32 v152, v124, v125
	v_fma_f32 v153, -v109, v152, v124
	v_fmac_f32_e32 v152, v153, v125
	v_fma_f32 v109, -v109, v152, v124
	v_pk_mul_f32 v[126:127], v[98:99], v[126:127] op_sel:[1,0]
	v_div_fmas_f32 v109, v109, v125, v152
	v_pk_fma_f32 v[126:127], v[2:3], v[126:127], v[6:7]
	v_div_fixup_f32 v148, v109, v148, s57
	v_cndmask_b32_e64 v127, v127, v232, s[8:9]
	v_cndmask_b32_e64 v126, v126, v232, s[8:9]
	v_pk_mul_f32 v[152:153], v[148:149], v[154:155] op_sel_hi:[0,1]
	v_pk_mul_f32 v[124:125], v[148:149], v[126:127] op_sel_hi:[0,1]
	v_add_f32_e32 v109, s100, v152
	v_add_f32_e32 v152, s100, v153
	v_add_f32_e32 v124, s100, v124
	v_add_f32_e32 v125, s100, v125
	v_perm_b32 v109, v125, v109, s56
	v_perm_b32 v160, v124, v152, s101
	v_or_b32_e32 v160, v109, v160
	v_or_b32_e32 v109, 32, v151
	v_or_b32_e32 v124, v149, v109
	v_ashrrev_i32_e32 v125, 31, v124
	v_lshlrev_b64 v[124:125], 10, v[124:125]
	v_lshl_add_u64 v[162:163], v[124:125], 0, v[112:113]
	v_cvt_pk_f16_f32 v153, v126, v127
	v_cvt_pk_f16_f32 v152, v154, v155
	v_cvt_pk_f16_f32 v155, v110, v111
	v_cvt_pk_f16_f32 v154, v158, v159
	s_nop 1
	v_permlane16_swap_b32_e32 v152, v154
	v_permlane16_swap_b32_e32 v153, v155
	v_lshl_add_u64 v[110:111], v[162:163], 1, s[60:61]
	global_store_dwordx4 v[110:111], v[152:155], off
	v_add_u32_e32 v111, v150, v115
	v_add_u32_e32 v110, v111, v156
	ds_read_b32 v150, v110 offset:12800
	ds_read_b64 v[126:127], v111 offset:9216
	v_permlane16_swap_b32_e32 v160, v161
	v_lshl_add_u64 v[152:153], s[72:73], 0, v[162:163]
	s_waitcnt lgkmcnt(1)
	v_max_f32_e32 v111, v150, v150
	v_max_f32_e32 v150, 0xda24260, v111
	global_store_dwordx2 v[152:153], v[160:161], off
	s_and_saveexec_b64 s[12:13], s[10:11]
	s_cbranch_execz .LBB0_481
	v_readlane_b32 s3, v254, 14
	v_mul_f32_e32 v111, 0x3c010204, v150
	v_cndmask_b32_e64 v111, v111, v232, s[8:9]
	v_add_u32_e32 v152, s3, v45
	v_ashrrev_i32_e32 v153, 31, v152
	v_lshl_add_u64 v[152:153], v[152:153], 2, s[54:55]
	global_store_dword v[152:153], v111, off

.LBB0_483:
	s_or_b64 exec, exec, s[12:13]
	s_waitcnt lgkmcnt(0)
	v_sub_f32_e32 v77, v77, v110
	v_sub_f32_e32 v76, v76, v110
	v_pk_mul_f32 v[76:77], v[110:111], v[76:77] op_sel:[1,0]
	v_sub_f32_e32 v79, v79, v110
	v_pk_fma_f32 v[76:77], v[0:1], v[76:77], v[4:5]
	v_sub_f32_e32 v78, v78, v110
	v_cndmask_b32_e64 v155, v77, v232, s[8:9]
	v_div_scale_f32 v77, s[12:13], v153, v153, s57
	v_rcp_f32_e32 v157, v77
	v_cndmask_b32_e64 v154, v76, v232, s[8:9]
	v_pk_mul_f32 v[78:79], v[110:111], v[78:79] op_sel:[1,0]
	v_sub_f32_e32 v93, v93, v126
	v_fma_f32 v76, -v77, v157, 1.0
	v_fmac_f32_e32 v157, v76, v157
	v_div_scale_f32 v76, vcc, s57, v153, s57
	v_mul_f32_e32 v158, v76, v157
	v_fma_f32 v159, -v77, v158, v76
	v_fmac_f32_e32 v158, v159, v157
	v_fma_f32 v76, -v77, v158, v76
	v_div_fmas_f32 v76, v76, v157, v158
	v_pk_fma_f32 v[78:79], v[2:3], v[78:79], v[6:7]
	v_div_fixup_f32 v76, v76, v153, s57
	v_cndmask_b32_e64 v79, v79, v232, s[8:9]
	v_cndmask_b32_e64 v78, v78, v232, s[8:9]
	v_pk_mul_f32 v[160:161], v[76:77], v[154:155] op_sel_hi:[0,1]
	v_pk_mul_f32 v[158:159], v[76:77], v[78:79] op_sel_hi:[0,1]
	v_add_f32_e32 v153, s100, v161
	v_add_f32_e32 v77, s100, v160
	v_add_f32_e32 v157, s100, v158
	v_add_f32_e32 v158, s100, v159
	v_sub_f32_e32 v92, v92, v126
	v_pk_mul_f32 v[92:93], v[126:127], v[92:93] op_sel:[1,0]
	v_pk_fma_f32 v[92:93], v[0:1], v[92:93], v[4:5]
	v_perm_b32 v77, v158, v77, s56
	v_cndmask_b32_e64 v161, v93, v232, s[8:9]
	v_div_scale_f32 v93, s[12:13], v150, v150, s57
	v_perm_b32 v163, v157, v153, s101
	v_or_b32_e32 v163, v77, v163
	v_add_u32_e32 v77, 0x80, v149
	v_rcp_f32_e32 v149, v93
	v_cndmask_b32_e64 v160, v92, v232, s[8:9]
	v_sub_f32_e32 v95, v95, v126
	v_sub_f32_e32 v94, v94, v126
	v_fma_f32 v92, -v93, v149, 1.0
	v_fmac_f32_e32 v149, v92, v149
	v_div_scale_f32 v92, vcc, s57, v150, s57
	v_mul_f32_e32 v153, v92, v149
	v_fma_f32 v157, -v93, v153, v92
	v_fmac_f32_e32 v153, v157, v149
	v_fma_f32 v92, -v93, v153, v92
	v_pk_mul_f32 v[94:95], v[126:127], v[94:95] op_sel:[1,0]
	v_div_fmas_f32 v92, v92, v149, v153
	v_pk_fma_f32 v[94:95], v[2:3], v[94:95], v[6:7]
	v_div_fixup_f32 v150, v92, v150, s57
	v_cndmask_b32_e64 v95, v95, v232, s[8:9]
	v_cndmask_b32_e64 v94, v94, v232, s[8:9]
	v_pk_mul_f32 v[158:159], v[150:151], v[160:161] op_sel_hi:[0,1]
	v_pk_mul_f32 v[92:93], v[150:151], v[94:95] op_sel_hi:[0,1]
	v_add_f32_e32 v153, s100, v159
	v_add_f32_e32 v149, s100, v158
	v_add_f32_e32 v92, s100, v92
	v_add_f32_e32 v93, s100, v93
	v_perm_b32 v93, v93, v149, s56
	v_perm_b32 v162, v92, v153, s101
	v_or_b32_e32 v162, v93, v162
	v_or_b32_e32 v92, v77, v151
	v_ashrrev_i32_e32 v93, 31, v92
	v_lshlrev_b64 v[92:93], 10, v[92:93]
	v_lshl_add_u64 v[164:165], v[92:93], 0, v[112:113]
	v_cvt_pk_f16_f32 v159, v94, v95
	v_cvt_pk_f16_f32 v158, v160, v161
	v_cvt_pk_f16_f32 v161, v78, v79
	v_cvt_pk_f16_f32 v160, v154, v155
	s_nop 1
	v_permlane16_swap_b32_e32 v158, v160
	v_permlane16_swap_b32_e32 v159, v161
	v_lshl_add_u64 v[78:79], v[164:165], 1, s[60:61]
	global_store_dwordx4 v[78:79], v[158:161], off
	v_add_u32_e32 v78, v152, v115
	v_add_u32_e32 v94, v78, v156
	ds_read_b32 v95, v94 offset:12928
	ds_read_b64 v[78:79], v78 offset:9472
	v_permlane16_swap_b32_e32 v162, v163
	v_lshl_add_u64 v[152:153], s[72:73], 0, v[164:165]
	s_waitcnt lgkmcnt(1)
	v_max_f32_e32 v95, v95, v95
	v_max_f32_e32 v149, 0xda24260, v95
	global_store_dwordx2 v[152:153], v[162:163], off
	s_and_saveexec_b64 s[12:13], s[10:11]
	s_cbranch_execz .LBB0_485
	v_readlane_b32 s3, v254, 16
	v_mul_f32_e32 v95, 0x3c010204, v149
	v_cndmask_b32_e64 v95, v95, v232, s[8:9]
	v_add_u32_e32 v152, s3, v45
	v_ashrrev_i32_e32 v153, 31, v152
	v_lshl_add_u64 v[152:153], v[152:153], 2, s[54:55]
	global_store_dword v[152:153], v95, off

.LBB0_487:
	s_or_b64 exec, exec, s[12:13]
	s_waitcnt lgkmcnt(0)
	v_sub_f32_e32 v129, v129, v94
	v_sub_f32_e32 v128, v128, v94
	v_pk_mul_f32 v[128:129], v[94:95], v[128:129] op_sel:[1,0]
	v_div_scale_f32 v45, s[10:11], v115, v115, s57
	v_pk_fma_f32 v[128:129], v[2:3], v[128:129], v[6:7]
	v_sub_f32_e32 v131, v131, v94
	v_cndmask_b32_e64 v153, v129, v232, s[8:9]
	v_rcp_f32_e32 v129, v45
	v_cndmask_b32_e64 v152, v128, v232, s[8:9]
	v_sub_f32_e32 v130, v130, v94
	v_pk_mul_f32 v[130:131], v[94:95], v[130:131] op_sel:[1,0]
	v_fma_f32 v128, -v45, v129, 1.0
	v_fmac_f32_e32 v129, v128, v129
	v_div_scale_f32 v128, vcc, s57, v115, s57
	v_mul_f32_e32 v151, v128, v129
	v_fma_f32 v154, -v45, v151, v128
	v_fmac_f32_e32 v151, v154, v129
	v_fma_f32 v45, -v45, v151, v128
	v_pk_fma_f32 v[130:131], v[0:1], v[130:131], v[4:5]
	v_div_fmas_f32 v45, v45, v129, v151
	v_sub_f32_e32 v63, v63, v78
	v_sub_f32_e32 v62, v62, v78
	v_cndmask_b32_e64 v131, v131, v232, s[8:9]
	v_cndmask_b32_e64 v130, v130, v232, s[8:9]
	v_div_fixup_f32 v128, v45, v115, s57
	v_pk_mul_f32 v[62:63], v[78:79], v[62:63] op_sel:[1,0]
	v_pk_mul_f32 v[154:155], v[128:129], v[130:131] op_sel_hi:[0,1]
	v_pk_fma_f32 v[2:3], v[2:3], v[62:63], v[6:7]
	v_div_scale_f32 v6, s[10:11], v149, v149, s57
	v_pk_mul_f32 v[156:157], v[128:129], v[152:153] op_sel_hi:[0,1]
	v_add_f32_e32 v129, s100, v155
	v_rcp_f32_e32 v7, v6
	v_add_f32_e32 v45, s100, v157
	v_add_f32_e32 v115, s100, v156
	v_add_f32_e32 v151, s100, v154
	v_sub_f32_e32 v61, v61, v78
	v_sub_f32_e32 v60, v60, v78
	v_pk_mul_f32 v[60:61], v[78:79], v[60:61] op_sel:[1,0]
	v_pk_fma_f32 v[0:1], v[0:1], v[60:61], v[4:5]
	v_cndmask_b32_e64 v4, v0, v232, s[8:9]
	v_fma_f32 v0, -v6, v7, 1.0
	v_fmac_f32_e32 v7, v0, v7
	v_div_scale_f32 v0, vcc, s57, v149, s57
	v_perm_b32 v45, v45, v151, s56
	v_cndmask_b32_e64 v5, v1, v232, s[8:9]
	v_mul_f32_e32 v1, v0, v7
	v_perm_b32 v155, v115, v129, s101
	v_or_b32_e32 v155, v45, v155
	v_fma_f32 v45, -v6, v1, v0
	v_fmac_f32_e32 v1, v45, v7
	v_fma_f32 v0, -v6, v1, v0
	v_div_fmas_f32 v0, v0, v7, v1
	v_div_fixup_f32 v60, v0, v149, s57
	v_cndmask_b32_e64 v3, v3, v232, s[8:9]
	v_cndmask_b32_e64 v2, v2, v232, s[8:9]
	v_pk_mul_f32 v[0:1], v[60:61], v[4:5] op_sel_hi:[0,1]
	v_pk_mul_f32 v[6:7], v[60:61], v[2:3] op_sel_hi:[0,1]
	v_add_f32_e32 v1, s100, v1
	v_add_f32_e32 v7, s100, v7
	v_add_f32_e32 v6, s100, v6
	v_add_f32_e32 v0, s100, v0
	v_perm_b32 v0, v7, v0, s56
	v_perm_b32 v154, v6, v1, s101
	v_or_b32_e32 v154, v0, v154
	v_or_b32_e32 v0, v77, v109
	v_ashrrev_i32_e32 v1, 31, v0
	v_lshlrev_b64 v[62:63], 10, v[0:1]
	v_lshl_add_u64 v[6:7], v[62:63], 0, v[112:113]
	v_cvt_pk_f16_f32 v1, v2, v3
	v_cvt_pk_f16_f32 v0, v4, v5
	v_cvt_pk_f16_f32 v3, v152, v153
	v_cvt_pk_f16_f32 v2, v130, v131
	s_nop 1
	v_permlane16_swap_b32_e32 v0, v2
	v_permlane16_swap_b32_e32 v1, v3
	v_lshl_add_u64 v[4:5], v[6:7], 1, s[60:61]
	global_store_dwordx4 v[4:5], v[0:3], off
	v_permlane16_swap_b32_e32 v154, v155
	s_nop 0
	v_lshl_add_u64 v[0:1], s[72:73], 0, v[6:7]
	global_store_dwordx2 v[0:1], v[154:155], off
	v_mov_b32_e32 v0, v180
	v_mov_b32_e32 v1, v181
	v_mov_b32_e32 v2, v182
	v_mov_b32_e32 v3, v183
	v_mov_b32_e32 v4, v184
	v_mov_b32_e32 v5, v185
	v_mov_b32_e32 v6, v186
	v_mov_b32_e32 v7, v187
	v_mov_b32_e32 v160, v39
	v_mov_b32_e32 v161, v39
	v_sub_f32_e32 v165, v141, v38
	v_sub_f32_e32 v164, v140, v38
	v_sub_f32_e32 v141, v143, v38
	v_sub_f32_e32 v140, v142, v38
	v_pk_mul_f32 v[142:143], v[160:161], v[140:141]
	v_mov_b32_e32 v140, v39
	v_mov_b32_e32 v141, v39
	v_pk_mul_f32 v[164:165], v[140:141], v[164:165]
	v_mov_b32_e32 v115, v114
	v_mov_b32_e32 v158, v33
	v_mov_b32_e32 v159, v33
	v_sub_f32_e32 v147, v147, v32
	v_sub_f32_e32 v146, v146, v32
	v_pk_mul_f32 v[146:147], v[158:159], v[146:147]
	v_mov_b32_e32 v45, v44
	v_lshl_add_u64 v[162:163], v[112:113], 0, 16
	v_mov_b32_e32 v156, v99
	v_mov_b32_e32 v157, v99
	v_sub_f32_e32 v121, v121, v98
	v_sub_f32_e32 v120, v120, v98
	v_sub_f32_e32 v123, v123, v98
	v_sub_f32_e32 v122, v122, v98
	v_mov_b32_e32 v149, v148
	v_mov_b32_e32 v154, v47
	v_mov_b32_e32 v155, v47
	v_sub_f32_e32 v107, v107, v46
	v_sub_f32_e32 v106, v106, v46
	v_mov_b32_e32 v109, v108
	v_mov_b32_e32 v152, v127
	v_mov_b32_e32 v153, v127
	v_sub_f32_e32 v89, v89, v126
	v_sub_f32_e32 v88, v88, v126
	v_sub_f32_e32 v91, v91, v126
	v_sub_f32_e32 v90, v90, v126
	v_mov_b32_e32 v151, v150
	v_mov_b32_e32 v130, v111
	v_mov_b32_e32 v131, v111
	v_sub_f32_e32 v75, v75, v110
	v_sub_f32_e32 v74, v74, v110
	v_mov_b32_e32 v77, v76
	v_sub_f32_e32 v57, v57, v78
	v_sub_f32_e32 v56, v56, v78
	v_sub_f32_e32 v41, v41, v94
	v_sub_f32_e32 v40, v40, v94
	v_sub_f32_e32 v59, v59, v78
	v_sub_f32_e32 v58, v58, v78
	v_pk_mul_f32 v[56:57], v[78:79], v[56:57] op_sel:[1,0]
	v_sub_f32_e32 v43, v43, v94
	v_sub_f32_e32 v42, v42, v94
	v_pk_mul_f32 v[40:41], v[94:95], v[40:41] op_sel:[1,0]
	v_pk_mul_f32 v[58:59], v[78:79], v[58:59] op_sel:[1,0]
	v_pk_mul_f32 v[42:43], v[94:95], v[42:43] op_sel:[1,0]
	v_sub_f32_e32 v53, v53, v78
	v_sub_f32_e32 v52, v52, v78
	v_sub_f32_e32 v13, v13, v94
	v_sub_f32_e32 v12, v12, v94
	v_pk_mul_f32 v[52:53], v[78:79], v[52:53] op_sel:[1,0]
	v_sub_f32_e32 v15, v15, v94
	v_sub_f32_e32 v14, v14, v94
	v_pk_mul_f32 v[12:13], v[94:95], v[12:13] op_sel:[1,0]
	v_pk_mul_f32 v[14:15], v[94:95], v[14:15] op_sel:[1,0]
	v_sub_f32_e32 v23, v23, v32
	v_sub_f32_e32 v22, v22, v32
	v_sub_f32_e32 v21, v21, v32
	v_sub_f32_e32 v20, v20, v32
	v_pk_mul_f32 v[22:23], v[158:159], v[22:23]
	s_mov_b64 s[10:11], 0x90
	v_sub_f32_e32 v9, v9, v94
	v_sub_f32_e32 v8, v8, v94
	v_sub_f32_e32 v11, v11, v94
	v_sub_f32_e32 v10, v10, v94
	v_pk_mul_f32 v[8:9], v[94:95], v[8:9] op_sel:[1,0]
	v_pk_mul_f32 v[10:11], v[94:95], v[10:11] op_sel:[1,0]
	v_pk_fma_f32 v[142:143], v[142:143], v[0:1], v[4:5]
	v_pk_fma_f32 v[164:165], v[164:165], v[2:3], v[6:7]
	v_cndmask_b32_e64 v167, v143, v232, s[8:9]
	v_cndmask_b32_e64 v166, v142, v232, s[8:9]
	v_cndmask_b32_e64 v165, v165, v232, s[8:9]
	v_cndmask_b32_e64 v164, v164, v232, s[8:9]
	v_mov_b32_e32 v142, v114
	v_mov_b32_e32 v143, v114
	v_pk_mul_f32 v[170:171], v[114:115], v[166:167]
	v_pk_mul_f32 v[168:169], v[142:143], v[164:165]
	v_add_f32_e32 v61, s100, v171
	v_add_f32_e32 v39, s100, v170
	v_add_f32_e32 v129, s100, v168
	v_add_f32_e32 v168, s100, v169
	v_sub_f32_e32 v171, v145, v32
	v_sub_f32_e32 v170, v144, v32
	v_mov_b32_e32 v144, v33
	v_mov_b32_e32 v145, v33
	v_pk_mul_f32 v[170:171], v[144:145], v[170:171]
	v_pk_fma_f32 v[146:147], v[146:147], v[0:1], v[4:5]
	v_pk_fma_f32 v[170:171], v[170:171], v[2:3], v[6:7]
	v_cndmask_b32_e64 v173, v147, v232, s[8:9]
	v_cndmask_b32_e64 v172, v146, v232, s[8:9]
	v_perm_b32 v39, v168, v39, s56
	v_cndmask_b32_e64 v171, v171, v232, s[8:9]
	v_cndmask_b32_e64 v170, v170, v232, s[8:9]
	v_pk_mul_f32 v[174:175], v[44:45], v[172:173]
	v_mov_b32_e32 v146, v44
	v_mov_b32_e32 v147, v44
	v_perm_b32 v168, v129, v61, s101
	v_or_b32_e32 v168, v39, v168
	v_pk_mul_f32 v[176:177], v[146:147], v[170:171]
	v_add_f32_e32 v61, s100, v175
	v_add_f32_e32 v33, s100, v177
	v_add_f32_e32 v39, s100, v176
	v_add_f32_e32 v129, s100, v174
	v_perm_b32 v33, v33, v129, s56
	v_lshl_add_u64 v[174:175], v[96:97], 0, v[162:163]
	v_cvt_pk_f16_f32 v165, v164, v165
	v_cvt_pk_f16_f32 v164, v166, v167
	v_cvt_pk_f16_f32 v167, v170, v171
	v_cvt_pk_f16_f32 v166, v172, v173
	v_perm_b32 v169, v39, v61, s101
	v_or_b32_e32 v169, v33, v169
	s_nop 0
	v_permlane16_swap_b32_e32 v164, v166
	v_permlane16_swap_b32_e32 v165, v167
	v_lshl_add_u64 v[170:171], v[174:175], 1, s[60:61]
	global_store_dwordx4 v[170:171], v[164:167], off
	v_permlane16_swap_b32_e32 v168, v169
	s_nop 0
	v_lshl_add_u64 v[164:165], s[72:73], 0, v[174:175]
	global_store_dwordx2 v[164:165], v[168:169], off
	v_pk_mul_f32 v[164:165], v[156:157], v[120:121]
	v_mov_b32_e32 v120, v99
	v_mov_b32_e32 v121, v99
	v_pk_mul_f32 v[122:123], v[120:121], v[122:123]
	v_pk_fma_f32 v[164:165], v[164:165], v[0:1], v[4:5]
	v_pk_fma_f32 v[122:123], v[122:123], v[2:3], v[6:7]
	v_cndmask_b32_e64 v167, v165, v232, s[8:9]
	v_cndmask_b32_e64 v166, v164, v232, s[8:9]
	v_cndmask_b32_e64 v165, v123, v232, s[8:9]
	v_cndmask_b32_e64 v164, v122, v232, s[8:9]
	v_mov_b32_e32 v122, v148
	v_mov_b32_e32 v123, v148
	v_pk_mul_f32 v[170:171], v[148:149], v[166:167]
	v_pk_mul_f32 v[168:169], v[122:123], v[164:165]
	v_add_f32_e32 v39, s100, v171
	v_add_f32_e32 v33, s100, v170
	v_add_f32_e32 v61, s100, v168
	v_add_f32_e32 v99, s100, v169
	v_sub_f32_e32 v171, v105, v46
	v_sub_f32_e32 v170, v104, v46
	v_mov_b32_e32 v104, v47
	v_mov_b32_e32 v105, v47
	v_pk_mul_f32 v[170:171], v[154:155], v[170:171]
	v_pk_mul_f32 v[106:107], v[104:105], v[106:107]
	v_pk_fma_f32 v[170:171], v[170:171], v[0:1], v[4:5]
	v_pk_fma_f32 v[106:107], v[106:107], v[2:3], v[6:7]
	v_cndmask_b32_e64 v171, v171, v232, s[8:9]
	v_cndmask_b32_e64 v170, v170, v232, s[8:9]
	v_cndmask_b32_e64 v173, v107, v232, s[8:9]
	v_cndmask_b32_e64 v172, v106, v232, s[8:9]
	v_pk_mul_f32 v[174:175], v[108:109], v[170:171]
	v_mov_b32_e32 v106, v108
	v_mov_b32_e32 v107, v108
	v_perm_b32 v33, v99, v33, s56
	v_pk_mul_f32 v[176:177], v[106:107], v[172:173]
	v_add_f32_e32 v47, s100, v175
	v_perm_b32 v168, v61, v39, s101
	v_or_b32_e32 v168, v33, v168
	v_add_f32_e32 v33, s100, v177
	v_add_f32_e32 v39, s100, v176
	v_add_f32_e32 v61, s100, v174
	v_perm_b32 v33, v33, v61, s56
	v_lshl_add_u64 v[174:175], v[124:125], 0, v[162:163]
	v_cvt_pk_f16_f32 v165, v164, v165
	v_cvt_pk_f16_f32 v164, v166, v167
	v_cvt_pk_f16_f32 v167, v172, v173
	v_cvt_pk_f16_f32 v166, v170, v171
	v_perm_b32 v169, v39, v47, s101
	v_or_b32_e32 v169, v33, v169
	s_nop 0
	v_permlane16_swap_b32_e32 v164, v166
	v_permlane16_swap_b32_e32 v165, v167
	v_lshl_add_u64 v[170:171], v[174:175], 1, s[60:61]
	global_store_dwordx4 v[170:171], v[164:167], off
	v_permlane16_swap_b32_e32 v168, v169
	s_nop 0
	v_lshl_add_u64 v[164:165], s[72:73], 0, v[174:175]
	global_store_dwordx2 v[164:165], v[168:169], off
	v_pk_mul_f32 v[164:165], v[152:153], v[88:89]
	v_mov_b32_e32 v88, v127
	v_mov_b32_e32 v89, v127
	v_pk_mul_f32 v[90:91], v[88:89], v[90:91]
	v_pk_fma_f32 v[164:165], v[164:165], v[0:1], v[4:5]
	v_pk_fma_f32 v[90:91], v[90:91], v[2:3], v[6:7]
	v_cndmask_b32_e64 v167, v165, v232, s[8:9]
	v_cndmask_b32_e64 v166, v164, v232, s[8:9]
	v_cndmask_b32_e64 v165, v91, v232, s[8:9]
	v_cndmask_b32_e64 v164, v90, v232, s[8:9]
	v_mov_b32_e32 v90, v150
	v_mov_b32_e32 v91, v150
	v_pk_mul_f32 v[170:171], v[150:151], v[166:167]
	v_pk_mul_f32 v[168:169], v[90:91], v[164:165]
	v_add_f32_e32 v39, s100, v171
	v_add_f32_e32 v33, s100, v170
	v_add_f32_e32 v47, s100, v168
	v_add_f32_e32 v61, s100, v169
	v_sub_f32_e32 v171, v73, v110
	v_sub_f32_e32 v170, v72, v110
	v_mov_b32_e32 v72, v111
	v_mov_b32_e32 v73, v111
	v_pk_mul_f32 v[170:171], v[130:131], v[170:171]
	v_pk_mul_f32 v[74:75], v[72:73], v[74:75]
	v_pk_fma_f32 v[170:171], v[170:171], v[0:1], v[4:5]
	v_pk_fma_f32 v[74:75], v[74:75], v[2:3], v[6:7]
	v_cndmask_b32_e64 v171, v171, v232, s[8:9]
	v_cndmask_b32_e64 v170, v170, v232, s[8:9]
	v_perm_b32 v33, v61, v33, s56
	v_cndmask_b32_e64 v173, v75, v232, s[8:9]
	v_cndmask_b32_e64 v172, v74, v232, s[8:9]
	v_pk_mul_f32 v[174:175], v[76:77], v[170:171]
	v_mov_b32_e32 v74, v76
	v_mov_b32_e32 v75, v76
	v_perm_b32 v168, v47, v39, s101
	v_or_b32_e32 v168, v33, v168
	v_pk_mul_f32 v[176:177], v[74:75], v[172:173]
	v_add_f32_e32 v47, s100, v175
	v_add_f32_e32 v33, s100, v177
	v_add_f32_e32 v39, s100, v176
	v_add_f32_e32 v61, s100, v174
	v_pk_fma_f32 v[56:57], v[56:57], v[0:1], v[4:5]
	v_pk_fma_f32 v[0:1], v[40:41], v[0:1], v[4:5]
	v_perm_b32 v33, v33, v61, s56
	v_lshl_add_u64 v[174:175], v[92:93], 0, v[162:163]
	v_cvt_pk_f16_f32 v165, v164, v165
	v_cvt_pk_f16_f32 v164, v166, v167
	v_cvt_pk_f16_f32 v167, v172, v173
	v_cvt_pk_f16_f32 v166, v170, v171
	v_pk_fma_f32 v[58:59], v[58:59], v[2:3], v[6:7]
	v_pk_fma_f32 v[2:3], v[42:43], v[2:3], v[6:7]
	v_cndmask_b32_e64 v5, v1, v232, s[8:9]
	v_cndmask_b32_e64 v4, v0, v232, s[8:9]
	v_perm_b32 v169, v39, v47, s101
	v_or_b32_e32 v169, v33, v169
	v_permlane16_swap_b32_e32 v164, v166
	v_permlane16_swap_b32_e32 v165, v167
	v_lshl_add_u64 v[170:171], v[174:175], 1, s[60:61]
	v_cndmask_b32_e64 v57, v57, v232, s[8:9]
	v_cndmask_b32_e64 v56, v56, v232, s[8:9]
	v_cndmask_b32_e64 v3, v3, v232, s[8:9]
	v_cndmask_b32_e64 v2, v2, v232, s[8:9]
	v_pk_mul_f32 v[0:1], v[128:129], v[4:5] op_sel_hi:[0,1]
	global_store_dwordx4 v[170:171], v[164:167], off
	v_permlane16_swap_b32_e32 v168, v169
	s_nop 0
	v_lshl_add_u64 v[164:165], s[72:73], 0, v[174:175]
	v_cndmask_b32_e64 v59, v59, v232, s[8:9]
	v_cndmask_b32_e64 v58, v58, v232, s[8:9]
	v_pk_mul_f32 v[166:167], v[60:61], v[56:57] op_sel_hi:[0,1]
	v_pk_mul_f32 v[6:7], v[128:129], v[2:3] op_sel_hi:[0,1]
	v_add_f32_e32 v1, s100, v1
	global_store_dwordx2 v[164:165], v[168:169], off
	v_pk_mul_f32 v[164:165], v[60:61], v[58:59] op_sel_hi:[0,1]
	v_add_f32_e32 v39, s100, v167
	v_add_f32_e32 v7, s100, v7
	v_add_f32_e32 v6, s100, v6
	v_add_f32_e32 v0, s100, v0
	v_add_f32_e32 v33, s100, v166
	v_add_f32_e32 v47, s100, v164
	v_add_f32_e32 v61, s100, v165
	v_perm_b32 v0, v7, v0, s56
	v_perm_b32 v33, v61, v33, s56
	v_perm_b32 v165, v6, v1, s101
	v_or_b32_e32 v165, v0, v165
	v_lshl_add_u64 v[6:7], v[62:63], 0, v[162:163]
	v_cvt_pk_f16_f32 v1, v58, v59
	v_cvt_pk_f16_f32 v0, v56, v57
	v_cvt_pk_f16_f32 v3, v2, v3
	v_cvt_pk_f16_f32 v2, v4, v5
	v_perm_b32 v164, v47, v39, s101
	v_or_b32_e32 v164, v33, v164
	s_nop 0
	v_permlane16_swap_b32_e32 v0, v2
	v_permlane16_swap_b32_e32 v1, v3
	v_lshl_add_u64 v[4:5], v[6:7], 1, s[60:61]
	global_store_dwordx4 v[4:5], v[0:3], off
	v_permlane16_swap_b32_e32 v164, v165
	s_nop 0
	v_lshl_add_u64 v[0:1], s[72:73], 0, v[6:7]
	global_store_dwordx2 v[0:1], v[164:165], off
	v_mov_b32_e32 v0, v188
	v_mov_b32_e32 v1, v189
	v_mov_b32_e32 v2, v190
	v_mov_b32_e32 v3, v191
	v_mov_b32_e32 v4, v192
	v_mov_b32_e32 v5, v193
	v_mov_b32_e32 v6, v194
	v_mov_b32_e32 v7, v195
	v_sub_f32_e32 v43, v137, v38
	v_sub_f32_e32 v42, v136, v38
	v_sub_f32_e32 v57, v139, v38
	v_sub_f32_e32 v56, v138, v38
	v_pk_mul_f32 v[56:57], v[160:161], v[56:57]
	v_pk_mul_f32 v[42:43], v[140:141], v[42:43]
	v_lshl_add_u64 v[40:41], v[112:113], 0, s[96:97]
	v_pk_mul_f32 v[20:21], v[144:145], v[20:21]
	v_pk_fma_f32 v[42:43], v[42:43], v[2:3], v[6:7]
	v_pk_fma_f32 v[56:57], v[56:57], v[0:1], v[4:5]
	v_cndmask_b32_e64 v43, v43, v232, s[8:9]
	v_cndmask_b32_e64 v59, v57, v232, s[8:9]
	v_cndmask_b32_e64 v58, v56, v232, s[8:9]
	v_cndmask_b32_e64 v42, v42, v232, s[8:9]
	v_pk_mul_f32 v[56:57], v[142:143], v[42:43]
	v_pk_mul_f32 v[136:137], v[114:115], v[58:59]
	v_add_f32_e32 v47, s100, v56
	v_add_f32_e32 v33, s100, v136
	v_add_f32_e32 v56, s100, v57
	v_add_f32_e32 v39, s100, v137
	v_perm_b32 v33, v56, v33, s56
	v_sub_f32_e32 v57, v133, v32
	v_sub_f32_e32 v56, v132, v32
	v_sub_f32_e32 v133, v135, v32
	v_sub_f32_e32 v132, v134, v32
	v_pk_mul_f32 v[56:57], v[158:159], v[56:57]
	v_pk_mul_f32 v[132:133], v[144:145], v[132:133]
	v_pk_fma_f32 v[56:57], v[56:57], v[0:1], v[4:5]
	v_pk_fma_f32 v[132:133], v[132:133], v[2:3], v[6:7]
	v_cndmask_b32_e64 v135, v57, v232, s[8:9]
	v_cndmask_b32_e64 v134, v56, v232, s[8:9]
	v_cndmask_b32_e64 v133, v133, v232, s[8:9]
	v_cndmask_b32_e64 v132, v132, v232, s[8:9]
	v_pk_mul_f32 v[56:57], v[44:45], v[134:135]
	v_perm_b32 v136, v47, v39, s101
	v_or_b32_e32 v136, v33, v136
	v_pk_mul_f32 v[138:139], v[146:147], v[132:133]
	v_add_f32_e32 v47, s100, v57
	v_add_f32_e32 v33, s100, v139
	v_add_f32_e32 v39, s100, v138
	v_add_f32_e32 v56, s100, v56
	v_perm_b32 v33, v33, v56, s56
	v_lshl_add_u64 v[138:139], v[96:97], 0, v[40:41]
	v_cvt_pk_f16_f32 v57, v42, v43
	v_cvt_pk_f16_f32 v56, v58, v59
	v_cvt_pk_f16_f32 v59, v132, v133
	v_cvt_pk_f16_f32 v58, v134, v135
	v_perm_b32 v137, v39, v47, s101
	v_or_b32_e32 v137, v33, v137
	s_nop 0
	v_permlane16_swap_b32_e32 v56, v58
	v_permlane16_swap_b32_e32 v57, v59
	v_lshl_add_u64 v[42:43], v[138:139], 1, s[60:61]
	global_store_dwordx4 v[42:43], v[56:59], off
	v_permlane16_swap_b32_e32 v136, v137
	v_lshl_add_u64 v[42:43], s[72:73], 0, v[138:139]
	global_store_dwordx2 v[42:43], v[136:137], off
	v_sub_f32_e32 v43, v119, v98
	v_sub_f32_e32 v42, v118, v98
	v_sub_f32_e32 v57, v117, v98
	v_sub_f32_e32 v56, v116, v98
	v_pk_mul_f32 v[56:57], v[156:157], v[56:57]
	v_pk_mul_f32 v[42:43], v[120:121], v[42:43]
	v_pk_fma_f32 v[56:57], v[56:57], v[0:1], v[4:5]
	v_pk_fma_f32 v[42:43], v[42:43], v[2:3], v[6:7]
	v_cndmask_b32_e64 v59, v57, v232, s[8:9]
	v_cndmask_b32_e64 v58, v56, v232, s[8:9]
	v_cndmask_b32_e64 v43, v43, v232, s[8:9]
	v_cndmask_b32_e64 v42, v42, v232, s[8:9]
	v_pk_mul_f32 v[56:57], v[122:123], v[42:43]
	v_pk_mul_f32 v[116:117], v[148:149], v[58:59]
	v_add_f32_e32 v47, s100, v56
	v_add_f32_e32 v33, s100, v116
	v_add_f32_e32 v56, s100, v57
	v_add_f32_e32 v39, s100, v117
	v_perm_b32 v33, v56, v33, s56
	v_sub_f32_e32 v57, v101, v46
	v_sub_f32_e32 v56, v100, v46
	v_sub_f32_e32 v101, v103, v46
	v_sub_f32_e32 v100, v102, v46
	v_pk_mul_f32 v[56:57], v[154:155], v[56:57]
	v_pk_mul_f32 v[100:101], v[104:105], v[100:101]
	v_pk_fma_f32 v[56:57], v[56:57], v[0:1], v[4:5]
	v_pk_fma_f32 v[100:101], v[100:101], v[2:3], v[6:7]
	v_cndmask_b32_e64 v103, v57, v232, s[8:9]
	v_cndmask_b32_e64 v102, v56, v232, s[8:9]
	v_cndmask_b32_e64 v101, v101, v232, s[8:9]
	v_cndmask_b32_e64 v100, v100, v232, s[8:9]
	v_pk_mul_f32 v[56:57], v[108:109], v[102:103]
	v_perm_b32 v116, v47, v39, s101
	v_or_b32_e32 v116, v33, v116
	v_pk_mul_f32 v[118:119], v[106:107], v[100:101]
	v_add_f32_e32 v47, s100, v57
	v_add_f32_e32 v33, s100, v119
	v_add_f32_e32 v39, s100, v118
	v_add_f32_e32 v56, s100, v56
	v_perm_b32 v33, v33, v56, s56
	v_lshl_add_u64 v[118:119], v[124:125], 0, v[40:41]
	v_cvt_pk_f16_f32 v57, v42, v43
	v_cvt_pk_f16_f32 v56, v58, v59
	v_cvt_pk_f16_f32 v59, v100, v101
	v_cvt_pk_f16_f32 v58, v102, v103
	v_perm_b32 v117, v39, v47, s101
	v_or_b32_e32 v117, v33, v117
	s_nop 0
	v_permlane16_swap_b32_e32 v56, v58
	v_permlane16_swap_b32_e32 v57, v59
	v_lshl_add_u64 v[42:43], v[118:119], 1, s[60:61]
	global_store_dwordx4 v[42:43], v[56:59], off
	v_permlane16_swap_b32_e32 v116, v117
	v_lshl_add_u64 v[42:43], s[72:73], 0, v[118:119]
	global_store_dwordx2 v[42:43], v[116:117], off
	v_sub_f32_e32 v43, v87, v126
	v_sub_f32_e32 v42, v86, v126
	v_sub_f32_e32 v57, v85, v126
	v_sub_f32_e32 v56, v84, v126
	v_pk_mul_f32 v[56:57], v[152:153], v[56:57]
	v_pk_mul_f32 v[42:43], v[88:89], v[42:43]
	v_pk_fma_f32 v[56:57], v[56:57], v[0:1], v[4:5]
	v_pk_fma_f32 v[42:43], v[42:43], v[2:3], v[6:7]
	v_cndmask_b32_e64 v59, v57, v232, s[8:9]
	v_cndmask_b32_e64 v58, v56, v232, s[8:9]
	v_cndmask_b32_e64 v43, v43, v232, s[8:9]
	v_cndmask_b32_e64 v42, v42, v232, s[8:9]
	v_pk_mul_f32 v[56:57], v[90:91], v[42:43]
	v_pk_mul_f32 v[84:85], v[150:151], v[58:59]
	v_add_f32_e32 v47, s100, v56
	v_add_f32_e32 v33, s100, v84
	v_add_f32_e32 v56, s100, v57
	v_add_f32_e32 v39, s100, v85
	v_perm_b32 v33, v56, v33, s56
	v_sub_f32_e32 v57, v69, v110
	v_sub_f32_e32 v56, v68, v110
	v_sub_f32_e32 v69, v71, v110
	v_sub_f32_e32 v68, v70, v110
	v_pk_mul_f32 v[56:57], v[130:131], v[56:57]
	v_pk_mul_f32 v[68:69], v[72:73], v[68:69]
	v_pk_fma_f32 v[56:57], v[56:57], v[0:1], v[4:5]
	v_pk_fma_f32 v[68:69], v[68:69], v[2:3], v[6:7]
	v_cndmask_b32_e64 v71, v57, v232, s[8:9]
	v_cndmask_b32_e64 v70, v56, v232, s[8:9]
	v_cndmask_b32_e64 v69, v69, v232, s[8:9]
	v_cndmask_b32_e64 v68, v68, v232, s[8:9]
	v_pk_mul_f32 v[56:57], v[76:77], v[70:71]
	v_perm_b32 v84, v47, v39, s101
	v_or_b32_e32 v84, v33, v84
	v_pk_mul_f32 v[86:87], v[74:75], v[68:69]
	v_add_f32_e32 v47, s100, v57
	v_add_f32_e32 v33, s100, v87
	v_add_f32_e32 v39, s100, v86
	v_add_f32_e32 v56, s100, v56
	v_perm_b32 v33, v33, v56, s56
	v_lshl_add_u64 v[86:87], v[92:93], 0, v[40:41]
	v_cvt_pk_f16_f32 v57, v42, v43
	v_cvt_pk_f16_f32 v56, v58, v59
	v_cvt_pk_f16_f32 v59, v68, v69
	v_cvt_pk_f16_f32 v58, v70, v71
	v_perm_b32 v85, v39, v47, s101
	v_or_b32_e32 v85, v33, v85
	s_nop 0
	v_permlane16_swap_b32_e32 v56, v58
	v_permlane16_swap_b32_e32 v57, v59
	v_lshl_add_u64 v[42:43], v[86:87], 1, s[60:61]
	global_store_dwordx4 v[42:43], v[56:59], off
	v_permlane16_swap_b32_e32 v84, v85
	v_lshl_add_u64 v[42:43], s[72:73], 0, v[86:87]
	global_store_dwordx2 v[42:43], v[84:85], off
	v_sub_f32_e32 v43, v55, v78
	v_sub_f32_e32 v42, v54, v78
	v_pk_mul_f32 v[42:43], v[78:79], v[42:43] op_sel:[1,0]
	v_pk_fma_f32 v[52:53], v[52:53], v[0:1], v[4:5]
	v_pk_fma_f32 v[0:1], v[12:13], v[0:1], v[4:5]
	v_pk_fma_f32 v[42:43], v[42:43], v[2:3], v[6:7]
	v_pk_fma_f32 v[2:3], v[14:15], v[2:3], v[6:7]
	v_cndmask_b32_e64 v5, v1, v232, s[8:9]
	v_cndmask_b32_e64 v4, v0, v232, s[8:9]
	v_cndmask_b32_e64 v53, v53, v232, s[8:9]
	v_cndmask_b32_e64 v52, v52, v232, s[8:9]
	v_cndmask_b32_e64 v3, v3, v232, s[8:9]
	v_cndmask_b32_e64 v2, v2, v232, s[8:9]
	v_pk_mul_f32 v[0:1], v[128:129], v[4:5] op_sel_hi:[0,1]
	v_cndmask_b32_e64 v43, v43, v232, s[8:9]
	v_cndmask_b32_e64 v42, v42, v232, s[8:9]
	v_pk_mul_f32 v[56:57], v[60:61], v[52:53] op_sel_hi:[0,1]
	v_pk_mul_f32 v[6:7], v[128:129], v[2:3] op_sel_hi:[0,1]
	v_add_f32_e32 v1, s100, v1
	v_pk_mul_f32 v[54:55], v[60:61], v[42:43] op_sel_hi:[0,1]
	v_add_f32_e32 v39, s100, v57
	v_add_f32_e32 v7, s100, v7
	v_add_f32_e32 v6, s100, v6
	v_add_f32_e32 v0, s100, v0
	v_add_f32_e32 v33, s100, v56
	v_add_f32_e32 v47, s100, v54
	v_add_f32_e32 v54, s100, v55
	v_perm_b32 v0, v7, v0, s56
	v_perm_b32 v33, v54, v33, s56
	v_perm_b32 v55, v6, v1, s101
	v_or_b32_e32 v55, v0, v55
	v_lshl_add_u64 v[6:7], v[62:63], 0, v[40:41]
	v_cvt_pk_f16_f32 v1, v42, v43
	v_cvt_pk_f16_f32 v0, v52, v53
	v_cvt_pk_f16_f32 v3, v2, v3
	v_cvt_pk_f16_f32 v2, v4, v5
	v_perm_b32 v54, v47, v39, s101
	v_or_b32_e32 v54, v33, v54
	s_nop 0
	v_permlane16_swap_b32_e32 v0, v2
	v_permlane16_swap_b32_e32 v1, v3
	v_lshl_add_u64 v[4:5], v[6:7], 1, s[60:61]
	global_store_dwordx4 v[4:5], v[0:3], off
	v_permlane16_swap_b32_e32 v54, v55
	s_nop 0
	v_lshl_add_u64 v[0:1], s[72:73], 0, v[6:7]
	global_store_dwordx2 v[0:1], v[54:55], off
	v_mov_b32_e32 v0, v196
	v_mov_b32_e32 v1, v197
	v_mov_b32_e32 v2, v198
	v_mov_b32_e32 v3, v199
	v_mov_b32_e32 v4, v200
	v_mov_b32_e32 v5, v201
	v_mov_b32_e32 v6, v202
	v_mov_b32_e32 v7, v203
	v_sub_f32_e32 v15, v17, v38
	v_sub_f32_e32 v14, v16, v38
	v_sub_f32_e32 v17, v19, v38
	v_sub_f32_e32 v16, v18, v38
	v_pk_mul_f32 v[16:17], v[160:161], v[16:17]
	v_pk_mul_f32 v[14:15], v[140:141], v[14:15]
	v_lshl_add_u64 v[12:13], v[112:113], 0, s[10:11]
	v_pk_fma_f32 v[16:17], v[16:17], v[0:1], v[4:5]
	v_pk_fma_f32 v[14:15], v[14:15], v[2:3], v[6:7]
	v_cndmask_b32_e64 v17, v17, v232, s[8:9]
	v_cndmask_b32_e64 v16, v16, v232, s[8:9]
	v_cndmask_b32_e64 v15, v15, v232, s[8:9]
	v_cndmask_b32_e64 v14, v14, v232, s[8:9]
	v_pk_mul_f32 v[34:35], v[114:115], v[16:17]
	v_pk_mul_f32 v[18:19], v[142:143], v[14:15]
	v_add_f32_e32 v33, s100, v34
	v_add_f32_e32 v34, s100, v35
	v_add_f32_e32 v18, s100, v18
	v_add_f32_e32 v19, s100, v19
	v_pk_fma_f32 v[22:23], v[22:23], v[0:1], v[4:5]
	v_pk_fma_f32 v[20:21], v[20:21], v[2:3], v[6:7]
	v_cndmask_b32_e64 v23, v23, v232, s[8:9]
	v_cndmask_b32_e64 v22, v22, v232, s[8:9]
	v_perm_b32 v19, v19, v33, s56
	v_cndmask_b32_e64 v21, v21, v232, s[8:9]
	v_cndmask_b32_e64 v20, v20, v232, s[8:9]
	v_pk_mul_f32 v[32:33], v[44:45], v[22:23]
	v_perm_b32 v18, v18, v34, s101
	v_or_b32_e32 v18, v19, v18
	v_pk_mul_f32 v[34:35], v[146:147], v[20:21]
	v_add_f32_e32 v33, s100, v33
	v_add_f32_e32 v19, s100, v35
	v_add_f32_e32 v34, s100, v34
	v_add_f32_e32 v32, s100, v32
	v_perm_b32 v19, v19, v32, s56
	v_perm_b32 v33, v34, v33, s101
	v_or_b32_e32 v19, v19, v33
	v_lshl_add_u64 v[32:33], v[96:97], 0, v[12:13]
	v_cvt_pk_f16_f32 v15, v14, v15
	v_cvt_pk_f16_f32 v14, v16, v17
	v_cvt_pk_f16_f32 v17, v20, v21
	v_cvt_pk_f16_f32 v16, v22, v23
	s_nop 1
	v_permlane16_swap_b32_e32 v14, v16
	v_permlane16_swap_b32_e32 v15, v17
	v_lshl_add_u64 v[20:21], v[32:33], 1, s[60:61]
	global_store_dwordx4 v[20:21], v[14:17], off
	v_permlane16_swap_b32_e32 v18, v19
	s_nop 0
	v_lshl_add_u64 v[14:15], s[72:73], 0, v[32:33]
	v_sub_f32_e32 v17, v25, v98
	v_sub_f32_e32 v16, v24, v98
	global_store_dwordx2 v[14:15], v[18:19], off
	v_sub_f32_e32 v15, v27, v98
	v_sub_f32_e32 v14, v26, v98
	v_pk_mul_f32 v[16:17], v[156:157], v[16:17]
	v_pk_mul_f32 v[14:15], v[120:121], v[14:15]
	v_pk_fma_f32 v[16:17], v[16:17], v[0:1], v[4:5]
	v_pk_fma_f32 v[14:15], v[14:15], v[2:3], v[6:7]
	v_cndmask_b32_e64 v17, v17, v232, s[8:9]
	v_cndmask_b32_e64 v16, v16, v232, s[8:9]
	v_cndmask_b32_e64 v15, v15, v232, s[8:9]
	v_cndmask_b32_e64 v14, v14, v232, s[8:9]
	v_pk_mul_f32 v[20:21], v[148:149], v[16:17]
	v_pk_mul_f32 v[18:19], v[122:123], v[14:15]
	v_add_f32_e32 v21, s100, v21
	v_add_f32_e32 v20, s100, v20
	v_add_f32_e32 v18, s100, v18
	v_add_f32_e32 v19, s100, v19
	v_perm_b32 v19, v19, v20, s56
	v_perm_b32 v18, v18, v21, s101
	v_or_b32_e32 v18, v19, v18
	v_sub_f32_e32 v21, v31, v46
	v_sub_f32_e32 v20, v30, v46
	v_sub_f32_e32 v23, v29, v46
	v_sub_f32_e32 v22, v28, v46
	v_pk_mul_f32 v[20:21], v[154:155], v[20:21]
	v_pk_mul_f32 v[22:23], v[104:105], v[22:23]
	v_pk_fma_f32 v[20:21], v[20:21], v[0:1], v[4:5]
	v_pk_fma_f32 v[22:23], v[22:23], v[2:3], v[6:7]
	v_cndmask_b32_e64 v21, v21, v232, s[8:9]
	v_cndmask_b32_e64 v20, v20, v232, s[8:9]
	v_cndmask_b32_e64 v23, v23, v232, s[8:9]
	v_cndmask_b32_e64 v22, v22, v232, s[8:9]
	v_pk_mul_f32 v[24:25], v[108:109], v[20:21]
	v_pk_mul_f32 v[26:27], v[106:107], v[22:23]
	v_add_f32_e32 v25, s100, v25
	v_add_f32_e32 v19, s100, v27
	v_add_f32_e32 v26, s100, v26
	v_add_f32_e32 v24, s100, v24
	v_perm_b32 v19, v19, v24, s56
	v_perm_b32 v25, v26, v25, s101
	v_or_b32_e32 v19, v19, v25
	v_lshl_add_u64 v[24:25], v[124:125], 0, v[12:13]
	v_cvt_pk_f16_f32 v15, v14, v15
	v_cvt_pk_f16_f32 v14, v16, v17
	v_cvt_pk_f16_f32 v17, v22, v23
	v_cvt_pk_f16_f32 v16, v20, v21
	s_nop 1
	v_permlane16_swap_b32_e32 v14, v16
	v_permlane16_swap_b32_e32 v15, v17
	v_lshl_add_u64 v[20:21], v[24:25], 1, s[60:61]
	global_store_dwordx4 v[20:21], v[14:17], off
	v_permlane16_swap_b32_e32 v18, v19
	s_nop 0
	v_lshl_add_u64 v[14:15], s[72:73], 0, v[24:25]
	v_sub_f32_e32 v17, v81, v126
	v_sub_f32_e32 v16, v80, v126
	global_store_dwordx2 v[14:15], v[18:19], off
	v_sub_f32_e32 v15, v83, v126
	v_sub_f32_e32 v14, v82, v126
	v_pk_mul_f32 v[16:17], v[152:153], v[16:17]
	v_pk_mul_f32 v[14:15], v[88:89], v[14:15]
	v_pk_fma_f32 v[16:17], v[16:17], v[0:1], v[4:5]
	v_pk_fma_f32 v[14:15], v[14:15], v[2:3], v[6:7]
	v_cndmask_b32_e64 v17, v17, v232, s[8:9]
	v_cndmask_b32_e64 v16, v16, v232, s[8:9]
	v_cndmask_b32_e64 v15, v15, v232, s[8:9]
	v_cndmask_b32_e64 v14, v14, v232, s[8:9]
	v_pk_mul_f32 v[20:21], v[150:151], v[16:17]
	v_pk_mul_f32 v[18:19], v[90:91], v[14:15]
	v_add_f32_e32 v21, s100, v21
	v_add_f32_e32 v20, s100, v20
	v_add_f32_e32 v18, s100, v18
	v_add_f32_e32 v19, s100, v19
	v_perm_b32 v19, v19, v20, s56
	v_perm_b32 v18, v18, v21, s101
	v_or_b32_e32 v18, v19, v18
	v_sub_f32_e32 v21, v65, v110
	v_sub_f32_e32 v20, v64, v110
	v_sub_f32_e32 v23, v67, v110
	v_sub_f32_e32 v22, v66, v110
	v_pk_mul_f32 v[20:21], v[130:131], v[20:21]
	v_pk_mul_f32 v[22:23], v[72:73], v[22:23]
	v_pk_fma_f32 v[20:21], v[20:21], v[0:1], v[4:5]
	v_pk_fma_f32 v[22:23], v[22:23], v[2:3], v[6:7]
	v_cndmask_b32_e64 v21, v21, v232, s[8:9]
	v_cndmask_b32_e64 v20, v20, v232, s[8:9]
	v_cndmask_b32_e64 v23, v23, v232, s[8:9]
	v_cndmask_b32_e64 v22, v22, v232, s[8:9]
	v_pk_mul_f32 v[24:25], v[76:77], v[20:21]
	v_pk_mul_f32 v[26:27], v[74:75], v[22:23]
	v_add_f32_e32 v25, s100, v25
	v_add_f32_e32 v19, s100, v27
	v_add_f32_e32 v26, s100, v26
	v_add_f32_e32 v24, s100, v24
	v_perm_b32 v19, v19, v24, s56
	v_perm_b32 v25, v26, v25, s101
	v_or_b32_e32 v19, v19, v25
	v_lshl_add_u64 v[24:25], v[92:93], 0, v[12:13]
	v_cvt_pk_f16_f32 v15, v14, v15
	v_cvt_pk_f16_f32 v14, v16, v17
	v_cvt_pk_f16_f32 v17, v22, v23
	v_cvt_pk_f16_f32 v16, v20, v21
	s_nop 1
	v_permlane16_swap_b32_e32 v14, v16
	v_permlane16_swap_b32_e32 v15, v17
	v_lshl_add_u64 v[20:21], v[24:25], 1, s[60:61]
	v_pk_fma_f32 v[8:9], v[8:9], v[0:1], v[4:5]
	global_store_dwordx4 v[20:21], v[14:17], off
	v_permlane16_swap_b32_e32 v18, v19
	s_nop 0
	v_lshl_add_u64 v[14:15], s[72:73], 0, v[24:25]
	v_pk_fma_f32 v[10:11], v[10:11], v[2:3], v[6:7]
	v_cndmask_b32_e64 v9, v9, v232, s[8:9]
	v_cndmask_b32_e64 v8, v8, v232, s[8:9]
	global_store_dwordx2 v[14:15], v[18:19], off
	v_cndmask_b32_e64 v11, v11, v232, s[8:9]
	v_cndmask_b32_e64 v10, v10, v232, s[8:9]
	v_pk_mul_f32 v[14:15], v[128:129], v[8:9] op_sel_hi:[0,1]
	v_pk_mul_f32 v[16:17], v[128:129], v[10:11] op_sel_hi:[0,1]
	v_add_f32_e32 v15, s100, v15
	v_add_f32_e32 v17, s100, v17
	v_add_f32_e32 v16, s100, v16
	v_add_f32_e32 v14, s100, v14
	v_perm_b32 v14, v17, v14, s56
	v_perm_b32 v15, v16, v15, s101
	v_or_b32_e32 v15, v14, v15
	v_sub_f32_e32 v17, v49, v78
	v_sub_f32_e32 v16, v48, v78
	v_sub_f32_e32 v19, v51, v78
	v_sub_f32_e32 v18, v50, v78
	v_pk_mul_f32 v[16:17], v[78:79], v[16:17] op_sel:[1,0]
	v_pk_mul_f32 v[18:19], v[78:79], v[18:19] op_sel:[1,0]
	v_pk_fma_f32 v[0:1], v[16:17], v[0:1], v[4:5]
	v_pk_fma_f32 v[2:3], v[18:19], v[2:3], v[6:7]
	v_cndmask_b32_e64 v5, v1, v232, s[8:9]
	v_cndmask_b32_e64 v4, v0, v232, s[8:9]
	v_cndmask_b32_e64 v3, v3, v232, s[8:9]
	v_cndmask_b32_e64 v2, v2, v232, s[8:9]
	v_pk_mul_f32 v[0:1], v[60:61], v[4:5] op_sel_hi:[0,1]
	v_pk_mul_f32 v[6:7], v[60:61], v[2:3] op_sel_hi:[0,1]
	v_add_f32_e32 v1, s100, v1
	v_add_f32_e32 v7, s100, v7
	v_add_f32_e32 v6, s100, v6
	v_add_f32_e32 v0, s100, v0
	v_perm_b32 v0, v7, v0, s56
	v_perm_b32 v14, v6, v1, s101
	v_or_b32_e32 v14, v0, v14
	v_lshl_add_u64 v[6:7], v[62:63], 0, v[12:13]
	v_cvt_pk_f16_f32 v1, v2, v3
	v_cvt_pk_f16_f32 v0, v4, v5
	v_cvt_pk_f16_f32 v3, v10, v11
	v_cvt_pk_f16_f32 v2, v8, v9
	s_nop 1
	v_permlane16_swap_b32_e32 v0, v2
	v_permlane16_swap_b32_e32 v1, v3
	v_lshl_add_u64 v[4:5], v[6:7], 1, s[60:61]
	global_store_dwordx4 v[4:5], v[0:3], off
	v_permlane16_swap_b32_e32 v14, v15
	s_nop 0
	v_lshl_add_u64 v[0:1], s[72:73], 0, v[6:7]
	s_mov_b64 s[8:9], 0
	global_store_dwordx2 v[0:1], v[14:15], off

.LBB0_549:
	s_mov_b32 s100, 0x4b400000
	s_mov_b32 s101, 0xc04000c
	s_waitcnt vmcnt(0) lgkmcnt(0)
	s_barrier
	ds_read_b32 v100, v231 offset:10240
	s_and_saveexec_b64 s[10:11], s[8:9]
	s_cbranch_execz .LBB0_551
	v_readlane_b32 s8, v254, 5
	v_lshlrev_b64 v[2:3], 5, v[0:1]
	v_readlane_b32 s9, v254, 6
	s_nop 1
	v_lshl_add_u64 v[2:3], s[8:9], 0, v[2:3]
	global_load_dwordx2 v[6:7], v[2:3], off sc1
	global_load_dwordx2 v[102:103], v[2:3], off offset:8 sc1
	global_load_dwordx2 v[112:113], v[2:3], off offset:16 sc1
	global_load_dwordx2 v[114:115], v[2:3], off offset:24 sc1
	s_waitcnt vmcnt(0)
	v_add_f32_e32 v5, 0, v6
	v_add_f32_e32 v5, v5, v102
	v_add_f32_e32 v5, v5, v112
	v_add_f32_e32 v3, v5, v114
	v_fmamk_f32 v5, v3, 0xbe800000, v6
	v_mul_f32_e32 v6, 0x43800000, v5
	v_fmac_f32_e32 v7, v5, v6
	v_fmamk_f32 v6, v3, 0xbe800000, v102
	v_add_f32_e32 v5, 0, v7
	v_mul_f32_e32 v7, 0x43800000, v6
	v_fmac_f32_e32 v103, v6, v7
	v_fmamk_f32 v6, v3, 0xbe800000, v112
	v_mul_f32_e32 v2, 0x3e800000, v3
	v_mul_f32_e32 v7, 0x43800000, v6
	v_fmamk_f32 v3, v3, 0xbe800000, v114
	v_add_f32_e32 v5, v103, v5
	v_fmac_f32_e32 v113, v6, v7
	v_mul_f32_e32 v6, 0x43800000, v3
	v_add_f32_e32 v5, v113, v5
	v_fmac_f32_e32 v115, v3, v6
	v_add_f32_e32 v3, v115, v5
	v_fmamk_f32 v3, v3, 0x3a800000, v217
	v_cmp_gt_f32_e32 vcc, s79, v3
	v_mul_f32_e32 v5, 0x4f800000, v3
	s_nop 0
	v_cndmask_b32_e32 v3, v3, v5, vcc
	v_sqrt_f32_e32 v5, v3
	s_nop 0
	v_add_u32_e32 v6, -1, v5
	v_fma_f32 v7, -v6, v5, v3
	v_cmp_ge_f32_e64 s[8:9], 0, v7
	v_add_u32_e32 v7, 1, v5
	s_nop 0
	v_cndmask_b32_e64 v6, v5, v6, s[8:9]
	v_fma_f32 v5, -v7, v5, v3
	v_cmp_lt_f32_e64 s[8:9], 0, v5
	s_nop 1
	v_cndmask_b32_e64 v5, v6, v7, s[8:9]
	v_mul_f32_e32 v6, 0x37800000, v5
	v_cndmask_b32_e32 v5, v5, v6, vcc
	v_cmp_class_f32_e32 vcc, v3, v215
	s_nop 1
	v_cndmask_b32_e32 v3, v5, v3, vcc
	v_div_scale_f32 v5, s[8:9], v3, v3, 1.0
	v_rcp_f32_e32 v6, v5
	v_readlane_b32 s8, v253, 49
	v_readlane_b32 s9, v253, 50
	v_fma_f32 v7, -v5, v6, 1.0
	v_fmac_f32_e32 v6, v7, v6
	v_div_scale_f32 v7, vcc, 1.0, v3, 1.0
	v_mul_f32_e32 v101, v7, v6
	v_fma_f32 v102, -v5, v101, v7
	v_fmac_f32_e32 v101, v102, v6
	v_fma_f32 v5, -v5, v101, v7
	v_div_fmas_f32 v5, v5, v6, v101
	v_div_fixup_f32 v3, v5, v3, 1.0
	v_lshl_add_u32 v5, v4, 3, 0
	ds_write_b64 v5, v[2:3] offset:8192
	v_lshl_add_u64 v[0:1], v[0:1], 4, s[8:9]
	global_load_dword v6, v[0:1], off sc1
	global_load_dword v7, v[0:1], off offset:4 sc1
	s_waitcnt vmcnt(0)
	v_max3_f32 v6, v6, 0, v7
	global_load_dword v7, v[0:1], off offset:8 sc1
	s_nop 0
	global_load_dword v0, v[0:1], off offset:12 sc1
	v_mul_f32_e32 v1, s30, v3
	s_waitcnt vmcnt(0)
	v_max3_f32 v0, v6, v7, v0
	v_add_f32_e64 v0, |v2|, v0
	v_fma_f32 v0, v0, v1, s31
	v_lshlrev_b32_e32 v1, 2, v4
	v_sub_u32_e32 v1, v5, v1
	ds_write_b32 v1, v0 offset:12288

.LBB0_555:
	s_or_b64 exec, exec, s[10:11]
	v_div_scale_f32 v153, s[10:11], v128, v128, s57
	v_rcp_f32_e32 v156, v153
	v_sub_f32_e32 v139, v139, v100
	v_sub_f32_e32 v138, v138, v100
	v_pk_mul_f32 v[138:139], v[100:101], v[138:139] op_sel:[1,0]
	v_sub_f32_e32 v137, v137, v100
	s_waitcnt vmcnt(0)
	v_pk_fma_f32 v[138:139], v[2:3], v[138:139], v[6:7]
	v_sub_f32_e32 v136, v136, v100
	v_cndmask_b32_e64 v154, v138, v232, s[6:7]
	v_fma_f32 v138, -v153, v156, 1.0
	v_fmac_f32_e32 v156, v138, v156
	v_div_scale_f32 v138, vcc, s57, v128, s57
	v_cndmask_b32_e64 v155, v139, v232, s[6:7]
	v_mul_f32_e32 v139, v138, v156
	v_fma_f32 v157, -v153, v139, v138
	v_fmac_f32_e32 v139, v157, v156
	v_pk_mul_f32 v[136:137], v[100:101], v[136:137] op_sel:[1,0]
	v_fma_f32 v138, -v153, v139, v138
	v_pk_fma_f32 v[136:137], v[0:1], v[136:137], v[4:5]
	v_div_fmas_f32 v138, v138, v156, v139
	v_cndmask_b32_e64 v137, v137, v232, s[6:7]
	v_cndmask_b32_e64 v136, v136, v232, s[6:7]
	v_div_fixup_f32 v128, v138, v128, s57
	v_pk_mul_f32 v[156:157], v[128:129], v[136:137] op_sel_hi:[0,1]
	v_pk_mul_f32 v[138:139], v[128:129], v[154:155] op_sel_hi:[0,1]
	v_add_f32_e32 v153, s100, v156
	v_add_f32_e32 v156, s100, v157
	v_add_f32_e32 v138, s100, v138
	v_add_f32_e32 v139, s100, v139
	v_perm_b32 v139, v139, v153, s56
	v_readlane_b32 s3, v254, 17
	v_perm_b32 v157, v138, v156, s101
	v_or_b32_e32 v157, v139, v157
	s_add_i32 s3, s3, s4
	v_div_scale_f32 v156, s[4:5], v142, v142, s57
	v_rcp_f32_e32 v158, v156
	v_sub_f32_e32 v135, v135, v114
	v_sub_f32_e32 v134, v134, v114
	v_pk_mul_f32 v[134:135], v[114:115], v[134:135] op_sel:[1,0]
	v_and_b32_e32 v138, -8, v152
	v_pk_fma_f32 v[134:135], v[2:3], v[134:135], v[6:7]
	v_sub_f32_e32 v133, v133, v114
	v_cndmask_b32_e64 v152, v134, v232, s[6:7]
	v_fma_f32 v134, -v156, v158, 1.0
	v_fmac_f32_e32 v158, v134, v158
	v_div_scale_f32 v134, vcc, s57, v142, s57
	v_cndmask_b32_e64 v153, v135, v232, s[6:7]
	v_mul_f32_e32 v135, v134, v158
	v_fma_f32 v159, -v156, v135, v134
	v_sub_f32_e32 v132, v132, v114
	v_fmac_f32_e32 v135, v159, v158
	v_pk_mul_f32 v[132:133], v[114:115], v[132:133] op_sel:[1,0]
	v_fma_f32 v134, -v156, v135, v134
	v_pk_fma_f32 v[132:133], v[0:1], v[132:133], v[4:5]
	v_div_fmas_f32 v134, v134, v158, v135
	v_cndmask_b32_e64 v133, v133, v232, s[6:7]
	v_cndmask_b32_e64 v132, v132, v232, s[6:7]
	v_div_fixup_f32 v142, v134, v142, s57
	v_pk_mul_f32 v[158:159], v[142:143], v[132:133] op_sel_hi:[0,1]
	v_pk_mul_f32 v[134:135], v[142:143], v[152:153] op_sel_hi:[0,1]
	v_add_f32_e32 v156, s100, v158
	v_add_f32_e32 v158, s100, v159
	v_add_f32_e32 v134, s100, v134
	v_add_f32_e32 v135, s100, v135
	v_or_b32_e32 v150, s3, v150
	v_perm_b32 v135, v135, v156, s56
	v_and_b32_e32 v143, 16, v143
	v_perm_b32 v156, v134, v158, s101
	v_or_b32_e32 v156, v135, v156
	v_or_b32_e32 v134, v150, v143
	v_ashrrev_i32_e32 v139, 31, v138
	v_ashrrev_i32_e32 v135, 31, v134
	v_lshl_add_u64 v[138:139], s[0:1], 0, v[138:139]
	v_lshlrev_b64 v[134:135], 10, v[134:135]
	v_lshl_add_u64 v[158:159], v[134:135], 0, v[138:139]
	v_cvt_pk_f16_f32 v153, v152, v153
	v_cvt_pk_f16_f32 v152, v132, v133
	v_cvt_pk_f16_f32 v155, v154, v155
	v_cvt_pk_f16_f32 v154, v136, v137
	s_nop 1
	v_permlane16_swap_b32_e32 v152, v154
	v_permlane16_swap_b32_e32 v153, v155
	v_lshl_add_u64 v[132:133], v[158:159], 1, s[60:61]
	global_store_dwordx4 v[132:133], v[152:155], off
	v_add_u32_e32 v133, v148, v149
	v_add_u32_e32 v132, v133, v151
	ds_read_b64 v[136:137], v133 offset:8448
	ds_read_b32 v133, v132 offset:12416
	v_permlane16_swap_b32_e32 v156, v157
	v_lshl_add_u64 v[152:153], s[72:73], 0, v[158:159]
	global_store_dwordx2 v[152:153], v[156:157], off
	s_waitcnt lgkmcnt(0)
	v_max_f32_e32 v133, v133, v133
	v_max_f32_e32 v148, 0xda24260, v133
	s_and_saveexec_b64 s[10:11], s[8:9]
	s_cbranch_execz .LBB0_557
	v_readlane_b32 s3, v254, 17
	v_mul_f32_e32 v133, 0x3c010204, v148
	v_cndmask_b32_e64 v133, v133, v232, s[6:7]
	v_add3_u32 v152, s3, v129, 32
	v_ashrrev_i32_e32 v153, 31, v152
	v_lshl_add_u64 v[152:153], v[152:153], 2, s[54:55]
	global_store_dword v[152:153], v133, off

.LBB0_559:
	s_or_b64 exec, exec, s[10:11]
	s_waitcnt lgkmcnt(0)
	v_sub_f32_e32 v109, v109, v132
	v_sub_f32_e32 v108, v108, v132
	v_pk_mul_f32 v[108:109], v[132:133], v[108:109] op_sel:[1,0]
	v_sub_f32_e32 v111, v111, v132
	v_pk_fma_f32 v[108:109], v[0:1], v[108:109], v[4:5]
	v_sub_f32_e32 v110, v110, v132
	v_cndmask_b32_e64 v159, v109, v232, s[6:7]
	v_div_scale_f32 v109, s[4:5], v153, v153, s57
	v_rcp_f32_e32 v154, v109
	v_cndmask_b32_e64 v158, v108, v232, s[6:7]
	v_pk_mul_f32 v[110:111], v[132:133], v[110:111] op_sel:[1,0]
	v_sub_f32_e32 v117, v117, v136
	v_fma_f32 v108, -v109, v154, 1.0
	v_fmac_f32_e32 v154, v108, v154
	v_div_scale_f32 v108, vcc, s57, v153, s57
	v_mul_f32_e32 v155, v108, v154
	v_fma_f32 v156, -v109, v155, v108
	v_fmac_f32_e32 v155, v156, v154
	v_fma_f32 v108, -v109, v155, v108
	v_div_fmas_f32 v108, v108, v154, v155
	v_pk_fma_f32 v[110:111], v[2:3], v[110:111], v[6:7]
	v_div_fixup_f32 v108, v108, v153, s57
	v_cndmask_b32_e64 v111, v111, v232, s[6:7]
	v_cndmask_b32_e64 v110, v110, v232, s[6:7]
	v_pk_mul_f32 v[156:157], v[108:109], v[158:159] op_sel_hi:[0,1]
	v_pk_mul_f32 v[154:155], v[108:109], v[110:111] op_sel_hi:[0,1]
	v_add_f32_e32 v153, s100, v157
	v_add_f32_e32 v109, s100, v156
	v_add_f32_e32 v154, s100, v154
	v_add_f32_e32 v155, s100, v155
	v_sub_f32_e32 v116, v116, v136
	v_perm_b32 v109, v155, v109, s56
	v_pk_mul_f32 v[116:117], v[136:137], v[116:117] op_sel:[1,0]
	v_perm_b32 v161, v154, v153, s101
	v_or_b32_e32 v161, v109, v161
	v_pk_fma_f32 v[116:117], v[0:1], v[116:117], v[4:5]
	v_div_scale_f32 v109, s[4:5], v148, v148, s57
	v_cndmask_b32_e64 v157, v117, v232, s[6:7]
	v_rcp_f32_e32 v117, v109
	v_cndmask_b32_e64 v156, v116, v232, s[6:7]
	v_sub_f32_e32 v119, v119, v136
	v_sub_f32_e32 v118, v118, v136
	v_fma_f32 v116, -v109, v117, 1.0
	v_fmac_f32_e32 v117, v116, v117
	v_div_scale_f32 v116, vcc, s57, v148, s57
	v_mul_f32_e32 v153, v116, v117
	v_fma_f32 v154, -v109, v153, v116
	v_fmac_f32_e32 v153, v154, v117
	v_fma_f32 v109, -v109, v153, v116
	v_pk_mul_f32 v[118:119], v[136:137], v[118:119] op_sel:[1,0]
	v_div_fmas_f32 v109, v109, v117, v153
	v_pk_fma_f32 v[118:119], v[2:3], v[118:119], v[6:7]
	v_div_fixup_f32 v148, v109, v148, s57
	v_cndmask_b32_e64 v119, v119, v232, s[6:7]
	v_cndmask_b32_e64 v118, v118, v232, s[6:7]
	v_pk_mul_f32 v[154:155], v[148:149], v[156:157] op_sel_hi:[0,1]
	v_pk_mul_f32 v[116:117], v[148:149], v[118:119] op_sel_hi:[0,1]
	v_add_f32_e32 v153, s100, v155
	v_add_f32_e32 v109, s100, v154
	v_add_f32_e32 v116, s100, v116
	v_add_f32_e32 v117, s100, v117
	v_perm_b32 v109, v117, v109, s56
	v_perm_b32 v160, v116, v153, s101
	v_or_b32_e32 v160, v109, v160
	v_or_b32_e32 v109, 32, v143
	v_or_b32_e32 v116, v150, v109
	v_ashrrev_i32_e32 v117, 31, v116
	v_lshlrev_b64 v[116:117], 10, v[116:117]
	v_lshl_add_u64 v[162:163], v[116:117], 0, v[138:139]
	v_cvt_pk_f16_f32 v155, v118, v119
	v_cvt_pk_f16_f32 v154, v156, v157
	v_cvt_pk_f16_f32 v157, v110, v111
	v_cvt_pk_f16_f32 v156, v158, v159
	s_nop 1
	v_permlane16_swap_b32_e32 v154, v156
	v_permlane16_swap_b32_e32 v155, v157
	v_lshl_add_u64 v[110:111], v[162:163], 1, s[60:61]
	global_store_dwordx4 v[110:111], v[154:157], off
	v_add_u32_e32 v111, v152, v149
	v_add_u32_e32 v110, v111, v151
	ds_read_b32 v154, v110 offset:12800
	ds_read_b64 v[118:119], v111 offset:9216
	v_permlane16_swap_b32_e32 v160, v161
	v_lshl_add_u64 v[152:153], s[72:73], 0, v[162:163]
	s_waitcnt lgkmcnt(1)
	v_max_f32_e32 v111, v154, v154
	global_store_dwordx2 v[152:153], v[160:161], off
	v_max_f32_e32 v153, 0xda24260, v111
	s_and_saveexec_b64 s[10:11], s[8:9]
	s_cbranch_execz .LBB0_561
	v_readlane_b32 s3, v254, 14
	v_mul_f32_e32 v111, 0x3c010204, v153
	v_cndmask_b32_e64 v111, v111, v232, s[6:7]
	v_add_u32_e32 v154, s3, v129
	v_ashrrev_i32_e32 v155, 31, v154
	v_lshl_add_u64 v[154:155], v[154:155], 2, s[54:55]
	global_store_dword v[154:155], v111, off

.LBB0_563:
	s_or_b64 exec, exec, s[10:11]
	s_waitcnt lgkmcnt(0)
	v_sub_f32_e32 v131, v131, v110
	v_sub_f32_e32 v130, v130, v110
	v_pk_mul_f32 v[130:131], v[110:111], v[130:131] op_sel:[1,0]
	v_sub_f32_e32 v141, v141, v110
	v_pk_fma_f32 v[130:131], v[0:1], v[130:131], v[4:5]
	v_sub_f32_e32 v140, v140, v110
	v_cndmask_b32_e64 v159, v131, v232, s[6:7]
	v_div_scale_f32 v131, s[4:5], v154, v154, s57
	v_rcp_f32_e32 v155, v131
	v_cndmask_b32_e64 v158, v130, v232, s[6:7]
	v_pk_mul_f32 v[140:141], v[110:111], v[140:141] op_sel:[1,0]
	v_sub_f32_e32 v63, v63, v118
	v_fma_f32 v130, -v131, v155, 1.0
	v_fmac_f32_e32 v155, v130, v155
	v_div_scale_f32 v130, vcc, s57, v154, s57
	v_mul_f32_e32 v156, v130, v155
	v_fma_f32 v157, -v131, v156, v130
	v_fmac_f32_e32 v156, v157, v155
	v_fma_f32 v130, -v131, v156, v130
	v_div_fmas_f32 v130, v130, v155, v156
	v_pk_fma_f32 v[140:141], v[2:3], v[140:141], v[6:7]
	v_div_fixup_f32 v130, v130, v154, s57
	v_cndmask_b32_e64 v141, v141, v232, s[6:7]
	v_cndmask_b32_e64 v140, v140, v232, s[6:7]
	v_pk_mul_f32 v[156:157], v[130:131], v[158:159] op_sel_hi:[0,1]
	v_pk_mul_f32 v[154:155], v[130:131], v[140:141] op_sel_hi:[0,1]
	v_add_f32_e32 v131, s100, v156
	v_add_f32_e32 v156, s100, v157
	v_add_f32_e32 v154, s100, v154
	v_add_f32_e32 v155, s100, v155
	v_perm_b32 v131, v155, v131, s56
	v_perm_b32 v161, v154, v156, s101
	v_or_b32_e32 v161, v131, v161
	v_add_u32_e32 v131, 0x80, v150
	v_div_scale_f32 v150, s[4:5], v153, v153, s57
	v_rcp_f32_e32 v156, v150
	v_sub_f32_e32 v62, v62, v118
	v_pk_mul_f32 v[62:63], v[118:119], v[62:63] op_sel:[1,0]
	v_sub_f32_e32 v61, v61, v118
	v_pk_fma_f32 v[62:63], v[2:3], v[62:63], v[6:7]
	v_sub_f32_e32 v60, v60, v118
	v_cndmask_b32_e64 v154, v62, v232, s[6:7]
	v_fma_f32 v62, -v150, v156, 1.0
	v_fmac_f32_e32 v156, v62, v156
	v_div_scale_f32 v62, vcc, s57, v153, s57
	v_cndmask_b32_e64 v155, v63, v232, s[6:7]
	v_mul_f32_e32 v63, v62, v156
	v_fma_f32 v157, -v150, v63, v62
	v_fmac_f32_e32 v63, v157, v156
	v_pk_mul_f32 v[60:61], v[118:119], v[60:61] op_sel:[1,0]
	v_fma_f32 v62, -v150, v63, v62
	v_pk_fma_f32 v[60:61], v[0:1], v[60:61], v[4:5]
	v_div_fmas_f32 v62, v62, v156, v63
	v_cndmask_b32_e64 v61, v61, v232, s[6:7]
	v_cndmask_b32_e64 v60, v60, v232, s[6:7]
	v_div_fixup_f32 v150, v62, v153, s57
	v_pk_mul_f32 v[156:157], v[150:151], v[60:61] op_sel_hi:[0,1]
	v_pk_mul_f32 v[62:63], v[150:151], v[154:155] op_sel_hi:[0,1]
	v_add_f32_e32 v153, s100, v156
	v_add_f32_e32 v156, s100, v157
	v_add_f32_e32 v62, s100, v62
	v_add_f32_e32 v63, s100, v63
	v_perm_b32 v63, v63, v153, s56
	v_perm_b32 v160, v62, v156, s101
	v_or_b32_e32 v160, v63, v160
	v_or_b32_e32 v62, v131, v143
	v_ashrrev_i32_e32 v63, 31, v62
	v_lshlrev_b64 v[62:63], 10, v[62:63]
	v_lshl_add_u64 v[162:163], v[62:63], 0, v[138:139]
	v_cvt_pk_f16_f32 v155, v154, v155
	v_cvt_pk_f16_f32 v154, v60, v61
	v_cvt_pk_f16_f32 v157, v140, v141
	v_cvt_pk_f16_f32 v156, v158, v159
	s_nop 1
	v_permlane16_swap_b32_e32 v154, v156
	v_permlane16_swap_b32_e32 v155, v157
	v_lshl_add_u64 v[60:61], v[162:163], 1, s[60:61]
	global_store_dwordx4 v[60:61], v[154:157], off
	v_add_u32_e32 v60, v152, v149
	v_add_u32_e32 v140, v60, v151
	ds_read_b32 v141, v140 offset:12928
	ds_read_b64 v[60:61], v60 offset:9472
	v_permlane16_swap_b32_e32 v160, v161
	v_lshl_add_u64 v[152:153], s[72:73], 0, v[162:163]
	s_waitcnt lgkmcnt(1)
	v_max_f32_e32 v141, v141, v141
	v_max_f32_e32 v143, 0xda24260, v141
	global_store_dwordx2 v[152:153], v[160:161], off
	s_and_saveexec_b64 s[10:11], s[8:9]
	s_cbranch_execz .LBB0_565
	v_readlane_b32 s3, v254, 16
	v_mul_f32_e32 v141, 0x3c010204, v143
	v_cndmask_b32_e64 v141, v141, v232, s[6:7]
	v_add_u32_e32 v152, s3, v129
	v_ashrrev_i32_e32 v153, 31, v152
	v_lshl_add_u64 v[152:153], v[152:153], 2, s[54:55]
	global_store_dword v[152:153], v141, off

.LBB0_567:
	s_or_b64 exec, exec, s[10:11]
	s_waitcnt lgkmcnt(0)
	v_sub_f32_e32 v145, v145, v140
	v_sub_f32_e32 v144, v144, v140
	v_pk_mul_f32 v[144:145], v[140:141], v[144:145] op_sel:[1,0]
	v_div_scale_f32 v129, s[4:5], v149, v149, s57
	v_pk_fma_f32 v[144:145], v[2:3], v[144:145], v[6:7]
	v_sub_f32_e32 v45, v45, v60
	v_cndmask_b32_e64 v153, v145, v232, s[6:7]
	v_rcp_f32_e32 v145, v129
	v_sub_f32_e32 v44, v44, v60
	v_pk_mul_f32 v[44:45], v[60:61], v[44:45] op_sel:[1,0]
	v_cndmask_b32_e64 v152, v144, v232, s[6:7]
	v_fma_f32 v144, -v129, v145, 1.0
	v_pk_fma_f32 v[2:3], v[2:3], v[44:45], v[6:7]
	v_div_scale_f32 v6, s[4:5], v143, v143, s57
	v_fmac_f32_e32 v145, v144, v145
	v_div_scale_f32 v144, vcc, s57, v149, s57
	v_rcp_f32_e32 v7, v6
	v_sub_f32_e32 v147, v147, v140
	v_sub_f32_e32 v146, v146, v140
	v_mul_f32_e32 v151, v144, v145
	v_sub_f32_e32 v47, v47, v60
	v_sub_f32_e32 v46, v46, v60
	v_pk_mul_f32 v[146:147], v[140:141], v[146:147] op_sel:[1,0]
	v_fma_f32 v154, -v129, v151, v144
	v_pk_mul_f32 v[46:47], v[60:61], v[46:47] op_sel:[1,0]
	v_pk_fma_f32 v[146:147], v[0:1], v[146:147], v[4:5]
	v_fmac_f32_e32 v151, v154, v145
	v_pk_fma_f32 v[0:1], v[0:1], v[46:47], v[4:5]
	v_fma_f32 v129, -v129, v151, v144
	v_cndmask_b32_e64 v4, v0, v232, s[6:7]
	v_fma_f32 v0, -v6, v7, 1.0
	v_div_fmas_f32 v129, v129, v145, v151
	v_fmac_f32_e32 v7, v0, v7
	v_div_scale_f32 v0, vcc, s57, v143, s57
	v_cndmask_b32_e64 v5, v1, v232, s[6:7]
	v_mul_f32_e32 v1, v0, v7
	v_fma_f32 v44, -v6, v1, v0
	v_fmac_f32_e32 v1, v44, v7
	v_fma_f32 v0, -v6, v1, v0
	v_div_fmas_f32 v0, v0, v7, v1
	v_div_fixup_f32 v44, v0, v143, s57
	v_cndmask_b32_e64 v3, v3, v232, s[6:7]
	v_cndmask_b32_e64 v2, v2, v232, s[6:7]
	v_pk_mul_f32 v[0:1], v[44:45], v[4:5] op_sel_hi:[0,1]
	v_pk_mul_f32 v[6:7], v[44:45], v[2:3] op_sel_hi:[0,1]
	v_add_f32_e32 v1, s100, v1
	v_add_f32_e32 v7, s100, v7
	v_add_f32_e32 v6, s100, v6
	v_add_f32_e32 v0, s100, v0
	v_cndmask_b32_e64 v147, v147, v232, s[6:7]
	v_cndmask_b32_e64 v146, v146, v232, s[6:7]
	v_div_fixup_f32 v144, v129, v149, s57
	v_pk_mul_f32 v[154:155], v[144:145], v[146:147] op_sel_hi:[0,1]
	v_pk_mul_f32 v[156:157], v[144:145], v[152:153] op_sel_hi:[0,1]
	v_add_f32_e32 v149, s100, v155
	v_add_f32_e32 v129, s100, v157
	v_add_f32_e32 v145, s100, v156
	v_add_f32_e32 v151, s100, v154
	v_perm_b32 v0, v7, v0, s56
	v_perm_b32 v154, v6, v1, s101
	v_or_b32_e32 v154, v0, v154
	v_or_b32_e32 v0, v131, v109
	v_ashrrev_i32_e32 v1, 31, v0
	v_lshlrev_b64 v[46:47], 10, v[0:1]
	v_perm_b32 v129, v129, v151, s56
	v_lshl_add_u64 v[6:7], v[46:47], 0, v[138:139]
	v_cvt_pk_f16_f32 v1, v2, v3
	v_cvt_pk_f16_f32 v0, v4, v5
	v_cvt_pk_f16_f32 v3, v152, v153
	v_cvt_pk_f16_f32 v2, v146, v147
	v_perm_b32 v155, v145, v149, s101
	v_or_b32_e32 v155, v129, v155
	s_nop 0
	v_permlane16_swap_b32_e32 v0, v2
	v_permlane16_swap_b32_e32 v1, v3
	v_lshl_add_u64 v[4:5], v[6:7], 1, s[60:61]
	global_store_dwordx4 v[4:5], v[0:3], off
	v_permlane16_swap_b32_e32 v154, v155
	s_nop 0
	v_lshl_add_u64 v[0:1], s[72:73], 0, v[6:7]
	global_store_dwordx2 v[0:1], v[154:155], off
	v_mov_b32_e32 v0, v180
	v_mov_b32_e32 v1, v181
	v_mov_b32_e32 v2, v182
	v_mov_b32_e32 v3, v183
	v_mov_b32_e32 v4, v184
	v_mov_b32_e32 v5, v185
	v_mov_b32_e32 v6, v186
	v_mov_b32_e32 v7, v187
	v_mov_b32_e32 v160, v115
	v_mov_b32_e32 v161, v115
	v_sub_f32_e32 v125, v125, v114
	v_sub_f32_e32 v124, v124, v114
	v_sub_f32_e32 v127, v127, v114
	v_sub_f32_e32 v126, v126, v114
	v_pk_mul_f32 v[164:165], v[160:161], v[124:125]
	v_mov_b32_e32 v124, v115
	v_mov_b32_e32 v125, v115
	v_pk_mul_f32 v[126:127], v[124:125], v[126:127]
	v_mov_b32_e32 v143, v142
	v_mov_b32_e32 v158, v101
	v_mov_b32_e32 v159, v101
	v_sub_f32_e32 v123, v123, v100
	v_sub_f32_e32 v122, v122, v100
	v_pk_mul_f32 v[122:123], v[158:159], v[122:123]
	v_mov_b32_e32 v129, v128
	v_lshl_add_u64 v[162:163], v[138:139], 0, 16
	v_mov_b32_e32 v156, v137
	v_mov_b32_e32 v157, v137
	v_sub_f32_e32 v97, v97, v136
	v_sub_f32_e32 v96, v96, v136
	v_sub_f32_e32 v99, v99, v136
	v_sub_f32_e32 v98, v98, v136
	v_mov_b32_e32 v149, v148
	v_mov_b32_e32 v154, v133
	v_mov_b32_e32 v155, v133
	v_sub_f32_e32 v107, v107, v132
	v_sub_f32_e32 v106, v106, v132
	v_pk_mul_f32 v[106:107], v[154:155], v[106:107]
	v_mov_b32_e32 v109, v108
	v_mov_b32_e32 v152, v119
	v_mov_b32_e32 v153, v119
	v_sub_f32_e32 v57, v57, v118
	v_sub_f32_e32 v56, v56, v118
	v_sub_f32_e32 v59, v59, v118
	v_sub_f32_e32 v58, v58, v118
	v_mov_b32_e32 v151, v150
	v_mov_b32_e32 v146, v111
	v_mov_b32_e32 v147, v111
	v_sub_f32_e32 v43, v43, v110
	v_sub_f32_e32 v42, v42, v110
	v_mov_b32_e32 v131, v130
	v_sub_f32_e32 v25, v25, v60
	v_sub_f32_e32 v24, v24, v60
	v_sub_f32_e32 v31, v31, v140
	v_sub_f32_e32 v30, v30, v140
	v_sub_f32_e32 v27, v27, v60
	v_sub_f32_e32 v26, v26, v60
	v_pk_mul_f32 v[24:25], v[60:61], v[24:25] op_sel:[1,0]
	v_sub_f32_e32 v29, v29, v140
	v_sub_f32_e32 v28, v28, v140
	v_pk_mul_f32 v[30:31], v[140:141], v[30:31] op_sel:[1,0]
	v_pk_mul_f32 v[26:27], v[60:61], v[26:27] op_sel:[1,0]
	v_pk_mul_f32 v[28:29], v[140:141], v[28:29] op_sel:[1,0]
	v_sub_f32_e32 v37, v37, v110
	v_sub_f32_e32 v36, v36, v110
	v_sub_f32_e32 v39, v39, v110
	v_sub_f32_e32 v38, v38, v110
	v_pk_mul_f32 v[36:37], v[146:147], v[36:37]
	v_sub_f32_e32 v21, v21, v60
	v_sub_f32_e32 v20, v20, v60
	v_sub_f32_e32 v15, v15, v140
	v_sub_f32_e32 v14, v14, v140
	v_sub_f32_e32 v23, v23, v60
	v_sub_f32_e32 v22, v22, v60
	v_pk_mul_f32 v[20:21], v[60:61], v[20:21] op_sel:[1,0]
	v_sub_f32_e32 v13, v13, v140
	v_sub_f32_e32 v12, v12, v140
	v_pk_mul_f32 v[14:15], v[140:141], v[14:15] op_sel:[1,0]
	v_pk_mul_f32 v[22:23], v[60:61], v[22:23] op_sel:[1,0]
	v_pk_mul_f32 v[12:13], v[140:141], v[12:13] op_sel:[1,0]
	s_mov_b64 s[4:5], 0x90
	v_sub_f32_e32 v11, v11, v140
	v_sub_f32_e32 v10, v10, v140
	v_sub_f32_e32 v17, v17, v60
	v_sub_f32_e32 v16, v16, v60
	v_sub_f32_e32 v9, v9, v140
	v_sub_f32_e32 v8, v8, v140
	v_pk_fma_f32 v[164:165], v[164:165], v[0:1], v[4:5]
	v_pk_fma_f32 v[126:127], v[126:127], v[2:3], v[6:7]
	v_cndmask_b32_e64 v167, v165, v232, s[6:7]
	v_cndmask_b32_e64 v166, v164, v232, s[6:7]
	v_cndmask_b32_e64 v165, v127, v232, s[6:7]
	v_cndmask_b32_e64 v164, v126, v232, s[6:7]
	v_mov_b32_e32 v126, v142
	v_mov_b32_e32 v127, v142
	v_pk_mul_f32 v[170:171], v[142:143], v[166:167]
	v_pk_mul_f32 v[168:169], v[126:127], v[164:165]
	v_add_f32_e32 v115, s100, v171
	v_add_f32_e32 v45, s100, v170
	v_add_f32_e32 v145, s100, v168
	v_add_f32_e32 v168, s100, v169
	v_sub_f32_e32 v171, v121, v100
	v_sub_f32_e32 v170, v120, v100
	v_mov_b32_e32 v120, v101
	v_mov_b32_e32 v121, v101
	v_pk_mul_f32 v[170:171], v[120:121], v[170:171]
	v_pk_fma_f32 v[122:123], v[122:123], v[0:1], v[4:5]
	v_pk_fma_f32 v[170:171], v[170:171], v[2:3], v[6:7]
	v_cndmask_b32_e64 v173, v123, v232, s[6:7]
	v_cndmask_b32_e64 v172, v122, v232, s[6:7]
	v_perm_b32 v45, v168, v45, s56
	v_cndmask_b32_e64 v171, v171, v232, s[6:7]
	v_cndmask_b32_e64 v170, v170, v232, s[6:7]
	v_pk_mul_f32 v[174:175], v[128:129], v[172:173]
	v_mov_b32_e32 v122, v128
	v_mov_b32_e32 v123, v128
	v_perm_b32 v168, v145, v115, s101
	v_or_b32_e32 v168, v45, v168
	v_pk_mul_f32 v[176:177], v[122:123], v[170:171]
	v_add_f32_e32 v115, s100, v175
	v_add_f32_e32 v45, s100, v177
	v_add_f32_e32 v101, s100, v176
	v_add_f32_e32 v145, s100, v174
	v_perm_b32 v45, v45, v145, s56
	v_lshl_add_u64 v[174:175], v[134:135], 0, v[162:163]
	v_cvt_pk_f16_f32 v165, v164, v165
	v_cvt_pk_f16_f32 v164, v166, v167
	v_cvt_pk_f16_f32 v167, v170, v171
	v_cvt_pk_f16_f32 v166, v172, v173
	v_perm_b32 v169, v101, v115, s101
	v_or_b32_e32 v169, v45, v169
	s_nop 0
	v_permlane16_swap_b32_e32 v164, v166
	v_permlane16_swap_b32_e32 v165, v167
	v_lshl_add_u64 v[170:171], v[174:175], 1, s[60:61]
	global_store_dwordx4 v[170:171], v[164:167], off
	v_permlane16_swap_b32_e32 v168, v169
	s_nop 0
	v_lshl_add_u64 v[164:165], s[72:73], 0, v[174:175]
	global_store_dwordx2 v[164:165], v[168:169], off
	v_pk_mul_f32 v[164:165], v[156:157], v[96:97]
	v_mov_b32_e32 v96, v137
	v_mov_b32_e32 v97, v137
	v_pk_mul_f32 v[98:99], v[96:97], v[98:99]
	v_pk_fma_f32 v[164:165], v[164:165], v[0:1], v[4:5]
	v_pk_fma_f32 v[98:99], v[98:99], v[2:3], v[6:7]
	v_cndmask_b32_e64 v167, v165, v232, s[6:7]
	v_cndmask_b32_e64 v166, v164, v232, s[6:7]
	v_cndmask_b32_e64 v165, v99, v232, s[6:7]
	v_cndmask_b32_e64 v164, v98, v232, s[6:7]
	v_mov_b32_e32 v98, v148
	v_mov_b32_e32 v99, v148
	v_pk_mul_f32 v[170:171], v[148:149], v[166:167]
	v_pk_mul_f32 v[168:169], v[98:99], v[164:165]
	v_add_f32_e32 v101, s100, v171
	v_add_f32_e32 v45, s100, v170
	v_add_f32_e32 v115, s100, v168
	v_add_f32_e32 v137, s100, v169
	v_sub_f32_e32 v171, v105, v132
	v_sub_f32_e32 v170, v104, v132
	v_mov_b32_e32 v104, v133
	v_mov_b32_e32 v105, v133
	v_pk_mul_f32 v[170:171], v[104:105], v[170:171]
	v_pk_fma_f32 v[106:107], v[106:107], v[0:1], v[4:5]
	v_pk_fma_f32 v[170:171], v[170:171], v[2:3], v[6:7]
	v_cndmask_b32_e64 v173, v107, v232, s[6:7]
	v_cndmask_b32_e64 v172, v106, v232, s[6:7]
	v_perm_b32 v45, v137, v45, s56
	v_cndmask_b32_e64 v171, v171, v232, s[6:7]
	v_cndmask_b32_e64 v170, v170, v232, s[6:7]
	v_pk_mul_f32 v[174:175], v[108:109], v[172:173]
	v_mov_b32_e32 v106, v108
	v_mov_b32_e32 v107, v108
	v_perm_b32 v168, v115, v101, s101
	v_or_b32_e32 v168, v45, v168
	v_pk_mul_f32 v[176:177], v[106:107], v[170:171]
	v_add_f32_e32 v115, s100, v175
	v_add_f32_e32 v45, s100, v177
	v_add_f32_e32 v101, s100, v176
	v_add_f32_e32 v133, s100, v174
	v_perm_b32 v45, v45, v133, s56
	v_lshl_add_u64 v[174:175], v[116:117], 0, v[162:163]
	v_cvt_pk_f16_f32 v165, v164, v165
	v_cvt_pk_f16_f32 v164, v166, v167
	v_cvt_pk_f16_f32 v167, v170, v171
	v_cvt_pk_f16_f32 v166, v172, v173
	v_perm_b32 v169, v101, v115, s101
	v_or_b32_e32 v169, v45, v169
	s_nop 0
	v_permlane16_swap_b32_e32 v164, v166
	v_permlane16_swap_b32_e32 v165, v167
	v_lshl_add_u64 v[170:171], v[174:175], 1, s[60:61]
	global_store_dwordx4 v[170:171], v[164:167], off
	v_permlane16_swap_b32_e32 v168, v169
	s_nop 0
	v_lshl_add_u64 v[164:165], s[72:73], 0, v[174:175]
	global_store_dwordx2 v[164:165], v[168:169], off
	v_pk_mul_f32 v[164:165], v[152:153], v[56:57]
	v_mov_b32_e32 v56, v119
	v_mov_b32_e32 v57, v119
	v_pk_mul_f32 v[58:59], v[56:57], v[58:59]
	v_pk_fma_f32 v[164:165], v[164:165], v[0:1], v[4:5]
	v_pk_fma_f32 v[58:59], v[58:59], v[2:3], v[6:7]
	v_cndmask_b32_e64 v167, v165, v232, s[6:7]
	v_cndmask_b32_e64 v166, v164, v232, s[6:7]
	v_cndmask_b32_e64 v165, v59, v232, s[6:7]
	v_cndmask_b32_e64 v164, v58, v232, s[6:7]
	v_mov_b32_e32 v58, v150
	v_mov_b32_e32 v59, v150
	v_pk_mul_f32 v[170:171], v[150:151], v[166:167]
	v_pk_mul_f32 v[168:169], v[58:59], v[164:165]
	v_add_f32_e32 v101, s100, v171
	v_add_f32_e32 v45, s100, v170
	v_add_f32_e32 v115, s100, v168
	v_add_f32_e32 v119, s100, v169
	v_sub_f32_e32 v171, v41, v110
	v_sub_f32_e32 v170, v40, v110
	v_mov_b32_e32 v40, v111
	v_mov_b32_e32 v41, v111
	v_pk_mul_f32 v[170:171], v[146:147], v[170:171]
	v_pk_mul_f32 v[42:43], v[40:41], v[42:43]
	v_pk_fma_f32 v[170:171], v[170:171], v[0:1], v[4:5]
	v_pk_fma_f32 v[42:43], v[42:43], v[2:3], v[6:7]
	v_cndmask_b32_e64 v171, v171, v232, s[6:7]
	v_cndmask_b32_e64 v170, v170, v232, s[6:7]
	v_cndmask_b32_e64 v173, v43, v232, s[6:7]
	v_cndmask_b32_e64 v172, v42, v232, s[6:7]
	v_pk_mul_f32 v[174:175], v[130:131], v[170:171]
	v_mov_b32_e32 v42, v130
	v_mov_b32_e32 v43, v130
	v_perm_b32 v45, v119, v45, s56
	v_pk_mul_f32 v[176:177], v[42:43], v[172:173]
	v_add_f32_e32 v111, s100, v175
	v_perm_b32 v168, v115, v101, s101
	v_or_b32_e32 v168, v45, v168
	v_add_f32_e32 v45, s100, v177
	v_add_f32_e32 v101, s100, v176
	v_add_f32_e32 v115, s100, v174
	v_pk_fma_f32 v[24:25], v[24:25], v[0:1], v[4:5]
	v_pk_fma_f32 v[0:1], v[30:31], v[0:1], v[4:5]
	v_perm_b32 v45, v45, v115, s56
	v_lshl_add_u64 v[174:175], v[62:63], 0, v[162:163]
	v_cvt_pk_f16_f32 v165, v164, v165
	v_cvt_pk_f16_f32 v164, v166, v167
	v_cvt_pk_f16_f32 v167, v172, v173
	v_cvt_pk_f16_f32 v166, v170, v171
	v_pk_fma_f32 v[26:27], v[26:27], v[2:3], v[6:7]
	v_pk_fma_f32 v[2:3], v[28:29], v[2:3], v[6:7]
	v_cndmask_b32_e64 v5, v1, v232, s[6:7]
	v_cndmask_b32_e64 v4, v0, v232, s[6:7]
	v_perm_b32 v169, v101, v111, s101
	v_or_b32_e32 v169, v45, v169
	v_permlane16_swap_b32_e32 v164, v166
	v_permlane16_swap_b32_e32 v165, v167
	v_lshl_add_u64 v[170:171], v[174:175], 1, s[60:61]
	v_cndmask_b32_e64 v25, v25, v232, s[6:7]
	v_cndmask_b32_e64 v24, v24, v232, s[6:7]
	v_cndmask_b32_e64 v3, v3, v232, s[6:7]
	v_cndmask_b32_e64 v2, v2, v232, s[6:7]
	v_pk_mul_f32 v[0:1], v[144:145], v[4:5] op_sel_hi:[0,1]
	global_store_dwordx4 v[170:171], v[164:167], off
	v_permlane16_swap_b32_e32 v168, v169
	s_nop 0
	v_lshl_add_u64 v[164:165], s[72:73], 0, v[174:175]
	v_cndmask_b32_e64 v27, v27, v232, s[6:7]
	v_cndmask_b32_e64 v26, v26, v232, s[6:7]
	v_pk_mul_f32 v[166:167], v[44:45], v[24:25] op_sel_hi:[0,1]
	v_pk_mul_f32 v[6:7], v[144:145], v[2:3] op_sel_hi:[0,1]
	v_add_f32_e32 v1, s100, v1
	global_store_dwordx2 v[164:165], v[168:169], off
	v_pk_mul_f32 v[164:165], v[44:45], v[26:27] op_sel_hi:[0,1]
	v_add_f32_e32 v101, s100, v167
	v_add_f32_e32 v7, s100, v7
	v_add_f32_e32 v6, s100, v6
	v_add_f32_e32 v0, s100, v0
	v_add_f32_e32 v45, s100, v166
	v_add_f32_e32 v111, s100, v164
	v_add_f32_e32 v115, s100, v165
	v_perm_b32 v0, v7, v0, s56
	v_perm_b32 v45, v115, v45, s56
	v_perm_b32 v165, v6, v1, s101
	v_or_b32_e32 v165, v0, v165
	v_lshl_add_u64 v[6:7], v[46:47], 0, v[162:163]
	v_cvt_pk_f16_f32 v1, v26, v27
	v_cvt_pk_f16_f32 v0, v24, v25
	v_cvt_pk_f16_f32 v3, v2, v3
	v_cvt_pk_f16_f32 v2, v4, v5
	v_perm_b32 v164, v111, v101, s101
	v_or_b32_e32 v164, v45, v164
	s_nop 0
	v_permlane16_swap_b32_e32 v0, v2
	v_permlane16_swap_b32_e32 v1, v3
	v_lshl_add_u64 v[4:5], v[6:7], 1, s[60:61]
	global_store_dwordx4 v[4:5], v[0:3], off
	v_permlane16_swap_b32_e32 v164, v165
	s_nop 0
	v_lshl_add_u64 v[0:1], s[72:73], 0, v[6:7]
	global_store_dwordx2 v[0:1], v[164:165], off
	v_mov_b32_e32 v0, v188
	v_mov_b32_e32 v1, v189
	v_mov_b32_e32 v2, v190
	v_mov_b32_e32 v3, v191
	v_mov_b32_e32 v4, v192
	v_mov_b32_e32 v5, v193
	v_mov_b32_e32 v6, v194
	v_mov_b32_e32 v7, v195
	v_sub_f32_e32 v29, v81, v114
	v_sub_f32_e32 v28, v80, v114
	v_sub_f32_e32 v27, v83, v114
	v_sub_f32_e32 v26, v82, v114
	v_pk_mul_f32 v[28:29], v[160:161], v[28:29]
	v_pk_mul_f32 v[26:27], v[124:125], v[26:27]
	v_sub_f32_e32 v83, v87, v100
	v_sub_f32_e32 v82, v86, v100
	v_pk_mul_f32 v[82:83], v[120:121], v[82:83]
	v_lshl_add_u64 v[24:25], v[138:139], 0, s[96:97]
	v_pk_mul_f32 v[38:39], v[40:41], v[38:39]
	v_pk_mul_f32 v[10:11], v[140:141], v[10:11] op_sel:[1,0]
	v_sub_f32_e32 v19, v19, v60
	v_sub_f32_e32 v18, v18, v60
	v_pk_mul_f32 v[16:17], v[60:61], v[16:17] op_sel:[1,0]
	v_pk_mul_f32 v[8:9], v[140:141], v[8:9] op_sel:[1,0]
	v_pk_mul_f32 v[18:19], v[60:61], v[18:19] op_sel:[1,0]
	v_pk_fma_f32 v[28:29], v[28:29], v[0:1], v[4:5]
	v_pk_fma_f32 v[26:27], v[26:27], v[2:3], v[6:7]
	v_cndmask_b32_e64 v29, v29, v232, s[6:7]
	v_cndmask_b32_e64 v28, v28, v232, s[6:7]
	v_cndmask_b32_e64 v27, v27, v232, s[6:7]
	v_cndmask_b32_e64 v26, v26, v232, s[6:7]
	v_pk_mul_f32 v[80:81], v[142:143], v[28:29]
	v_pk_mul_f32 v[30:31], v[126:127], v[26:27]
	v_add_f32_e32 v45, s100, v80
	v_add_f32_e32 v80, s100, v81
	v_add_f32_e32 v30, s100, v30
	v_add_f32_e32 v31, s100, v31
	v_perm_b32 v31, v31, v45, s56
	v_perm_b32 v30, v30, v80, s101
	v_or_b32_e32 v30, v31, v30
	v_sub_f32_e32 v81, v85, v100
	v_sub_f32_e32 v80, v84, v100
	v_pk_mul_f32 v[80:81], v[158:159], v[80:81]
	v_pk_fma_f32 v[82:83], v[82:83], v[2:3], v[6:7]
	v_pk_fma_f32 v[80:81], v[80:81], v[0:1], v[4:5]
	v_cndmask_b32_e64 v83, v83, v232, s[6:7]
	v_cndmask_b32_e64 v81, v81, v232, s[6:7]
	v_cndmask_b32_e64 v80, v80, v232, s[6:7]
	v_cndmask_b32_e64 v82, v82, v232, s[6:7]
	v_pk_mul_f32 v[84:85], v[128:129], v[80:81]
	v_pk_mul_f32 v[86:87], v[122:123], v[82:83]
	v_add_f32_e32 v85, s100, v85
	v_add_f32_e32 v31, s100, v87
	v_add_f32_e32 v45, s100, v86
	v_add_f32_e32 v84, s100, v84
	v_perm_b32 v31, v31, v84, s56
	v_perm_b32 v85, v45, v85, s101
	v_or_b32_e32 v31, v31, v85
	v_lshl_add_u64 v[84:85], v[134:135], 0, v[24:25]
	v_cvt_pk_f16_f32 v27, v26, v27
	v_cvt_pk_f16_f32 v26, v28, v29
	v_cvt_pk_f16_f32 v29, v82, v83
	v_cvt_pk_f16_f32 v28, v80, v81
	s_nop 1
	v_permlane16_swap_b32_e32 v26, v28
	v_permlane16_swap_b32_e32 v27, v29
	v_lshl_add_u64 v[80:81], v[84:85], 1, s[60:61]
	global_store_dwordx4 v[80:81], v[26:29], off
	v_permlane16_swap_b32_e32 v30, v31
	s_nop 0
	v_lshl_add_u64 v[26:27], s[72:73], 0, v[84:85]
	v_sub_f32_e32 v29, v89, v136
	v_sub_f32_e32 v28, v88, v136
	global_store_dwordx2 v[26:27], v[30:31], off
	v_sub_f32_e32 v27, v91, v136
	v_sub_f32_e32 v26, v90, v136
	v_pk_mul_f32 v[28:29], v[156:157], v[28:29]
	v_pk_mul_f32 v[26:27], v[96:97], v[26:27]
	v_pk_fma_f32 v[28:29], v[28:29], v[0:1], v[4:5]
	v_pk_fma_f32 v[26:27], v[26:27], v[2:3], v[6:7]
	v_cndmask_b32_e64 v29, v29, v232, s[6:7]
	v_cndmask_b32_e64 v28, v28, v232, s[6:7]
	v_cndmask_b32_e64 v27, v27, v232, s[6:7]
	v_cndmask_b32_e64 v26, v26, v232, s[6:7]
	v_pk_mul_f32 v[80:81], v[148:149], v[28:29]
	v_pk_mul_f32 v[30:31], v[98:99], v[26:27]
	v_add_f32_e32 v45, s100, v80
	v_add_f32_e32 v80, s100, v81
	v_add_f32_e32 v30, s100, v30
	v_add_f32_e32 v31, s100, v31
	v_perm_b32 v31, v31, v45, s56
	v_perm_b32 v30, v30, v80, s101
	v_or_b32_e32 v30, v31, v30
	v_sub_f32_e32 v81, v95, v132
	v_sub_f32_e32 v80, v94, v132
	v_sub_f32_e32 v83, v93, v132
	v_sub_f32_e32 v82, v92, v132
	v_pk_mul_f32 v[80:81], v[154:155], v[80:81]
	v_pk_mul_f32 v[82:83], v[104:105], v[82:83]
	v_pk_fma_f32 v[80:81], v[80:81], v[0:1], v[4:5]
	v_pk_fma_f32 v[82:83], v[82:83], v[2:3], v[6:7]
	v_cndmask_b32_e64 v81, v81, v232, s[6:7]
	v_cndmask_b32_e64 v80, v80, v232, s[6:7]
	v_cndmask_b32_e64 v83, v83, v232, s[6:7]
	v_cndmask_b32_e64 v82, v82, v232, s[6:7]
	v_pk_mul_f32 v[84:85], v[108:109], v[80:81]
	v_pk_mul_f32 v[86:87], v[106:107], v[82:83]
	v_add_f32_e32 v85, s100, v85
	v_add_f32_e32 v31, s100, v87
	v_add_f32_e32 v45, s100, v86
	v_add_f32_e32 v84, s100, v84
	v_perm_b32 v31, v31, v84, s56
	v_perm_b32 v85, v45, v85, s101
	v_or_b32_e32 v31, v31, v85
	v_lshl_add_u64 v[84:85], v[116:117], 0, v[24:25]
	v_cvt_pk_f16_f32 v27, v26, v27
	v_cvt_pk_f16_f32 v26, v28, v29
	v_cvt_pk_f16_f32 v29, v82, v83
	v_cvt_pk_f16_f32 v28, v80, v81
	s_nop 1
	v_permlane16_swap_b32_e32 v26, v28
	v_permlane16_swap_b32_e32 v27, v29
	v_lshl_add_u64 v[80:81], v[84:85], 1, s[60:61]
	global_store_dwordx4 v[80:81], v[26:29], off
	v_permlane16_swap_b32_e32 v30, v31
	s_nop 0
	v_lshl_add_u64 v[26:27], s[72:73], 0, v[84:85]
	v_sub_f32_e32 v29, v53, v118
	v_sub_f32_e32 v28, v52, v118
	global_store_dwordx2 v[26:27], v[30:31], off
	v_sub_f32_e32 v27, v55, v118
	v_sub_f32_e32 v26, v54, v118
	v_pk_mul_f32 v[28:29], v[152:153], v[28:29]
	v_pk_mul_f32 v[26:27], v[56:57], v[26:27]
	v_pk_fma_f32 v[28:29], v[28:29], v[0:1], v[4:5]
	v_pk_fma_f32 v[26:27], v[26:27], v[2:3], v[6:7]
	v_cndmask_b32_e64 v29, v29, v232, s[6:7]
	v_cndmask_b32_e64 v28, v28, v232, s[6:7]
	v_cndmask_b32_e64 v27, v27, v232, s[6:7]
	v_cndmask_b32_e64 v26, v26, v232, s[6:7]
	v_pk_mul_f32 v[52:53], v[150:151], v[28:29]
	v_pk_mul_f32 v[30:31], v[58:59], v[26:27]
	v_add_f32_e32 v45, s100, v52
	v_add_f32_e32 v52, s100, v53
	v_add_f32_e32 v30, s100, v30
	v_add_f32_e32 v31, s100, v31
	v_pk_fma_f32 v[36:37], v[36:37], v[0:1], v[4:5]
	v_perm_b32 v31, v31, v45, s56
	v_pk_fma_f32 v[38:39], v[38:39], v[2:3], v[6:7]
	v_cndmask_b32_e64 v37, v37, v232, s[6:7]
	v_cndmask_b32_e64 v36, v36, v232, s[6:7]
	v_perm_b32 v30, v30, v52, s101
	v_or_b32_e32 v30, v31, v30
	v_cndmask_b32_e64 v39, v39, v232, s[6:7]
	v_cndmask_b32_e64 v38, v38, v232, s[6:7]
	v_pk_mul_f32 v[52:53], v[130:131], v[36:37]
	v_pk_mul_f32 v[54:55], v[42:43], v[38:39]
	v_add_f32_e32 v53, s100, v53
	v_add_f32_e32 v31, s100, v55
	v_add_f32_e32 v45, s100, v54
	v_add_f32_e32 v52, s100, v52
	v_perm_b32 v31, v31, v52, s56
	v_perm_b32 v53, v45, v53, s101
	v_or_b32_e32 v31, v31, v53
	v_lshl_add_u64 v[52:53], v[62:63], 0, v[24:25]
	v_cvt_pk_f16_f32 v27, v26, v27
	v_cvt_pk_f16_f32 v26, v28, v29
	v_cvt_pk_f16_f32 v29, v38, v39
	v_cvt_pk_f16_f32 v28, v36, v37
	v_pk_fma_f32 v[20:21], v[20:21], v[0:1], v[4:5]
	v_pk_fma_f32 v[0:1], v[14:15], v[0:1], v[4:5]
	v_permlane16_swap_b32_e32 v26, v28
	v_permlane16_swap_b32_e32 v27, v29
	v_lshl_add_u64 v[36:37], v[52:53], 1, s[60:61]
	v_pk_fma_f32 v[22:23], v[22:23], v[2:3], v[6:7]
	v_cndmask_b32_e64 v21, v21, v232, s[6:7]
	v_cndmask_b32_e64 v20, v20, v232, s[6:7]
	v_pk_fma_f32 v[2:3], v[12:13], v[2:3], v[6:7]
	v_cndmask_b32_e64 v5, v1, v232, s[6:7]
	v_cndmask_b32_e64 v4, v0, v232, s[6:7]
	global_store_dwordx4 v[36:37], v[26:29], off
	v_permlane16_swap_b32_e32 v30, v31
	s_nop 0
	v_lshl_add_u64 v[26:27], s[72:73], 0, v[52:53]
	v_cndmask_b32_e64 v23, v23, v232, s[6:7]
	v_cndmask_b32_e64 v22, v22, v232, s[6:7]
	v_pk_mul_f32 v[28:29], v[44:45], v[20:21] op_sel_hi:[0,1]
	v_cndmask_b32_e64 v3, v3, v232, s[6:7]
	v_cndmask_b32_e64 v2, v2, v232, s[6:7]
	v_pk_mul_f32 v[0:1], v[144:145], v[4:5] op_sel_hi:[0,1]
	global_store_dwordx2 v[26:27], v[30:31], off
	v_pk_mul_f32 v[26:27], v[44:45], v[22:23] op_sel_hi:[0,1]
	v_add_f32_e32 v29, s100, v29
	v_pk_mul_f32 v[6:7], v[144:145], v[2:3] op_sel_hi:[0,1]
	v_add_f32_e32 v1, s100, v1
	v_add_f32_e32 v28, s100, v28
	v_add_f32_e32 v26, s100, v26
	v_add_f32_e32 v27, s100, v27
	v_add_f32_e32 v7, s100, v7
	v_add_f32_e32 v6, s100, v6
	v_add_f32_e32 v0, s100, v0
	v_perm_b32 v27, v27, v28, s56
	v_perm_b32 v0, v7, v0, s56
	v_perm_b32 v26, v26, v29, s101
	v_or_b32_e32 v26, v27, v26
	v_perm_b32 v27, v6, v1, s101
	v_or_b32_e32 v27, v0, v27
	v_lshl_add_u64 v[6:7], v[46:47], 0, v[24:25]
	v_cvt_pk_f16_f32 v1, v22, v23
	v_cvt_pk_f16_f32 v0, v20, v21
	v_cvt_pk_f16_f32 v3, v2, v3
	v_cvt_pk_f16_f32 v2, v4, v5
	s_nop 1
	v_permlane16_swap_b32_e32 v0, v2
	v_permlane16_swap_b32_e32 v1, v3
	v_lshl_add_u64 v[4:5], v[6:7], 1, s[60:61]
	global_store_dwordx4 v[4:5], v[0:3], off
	v_permlane16_swap_b32_e32 v26, v27
	s_nop 0
	v_lshl_add_u64 v[0:1], s[72:73], 0, v[6:7]
	global_store_dwordx2 v[0:1], v[26:27], off
	v_mov_b32_e32 v0, v196
	v_mov_b32_e32 v1, v197
	v_mov_b32_e32 v2, v198
	v_mov_b32_e32 v3, v199
	v_mov_b32_e32 v4, v200
	v_mov_b32_e32 v5, v201
	v_mov_b32_e32 v6, v202
	v_mov_b32_e32 v7, v203
	v_sub_f32_e32 v21, v69, v114
	v_sub_f32_e32 v20, v68, v114
	v_sub_f32_e32 v15, v71, v114
	v_sub_f32_e32 v14, v70, v114
	v_pk_mul_f32 v[20:21], v[160:161], v[20:21]
	v_pk_mul_f32 v[14:15], v[124:125], v[14:15]
	v_sub_f32_e32 v27, v73, v100
	v_sub_f32_e32 v26, v72, v100
	v_pk_mul_f32 v[26:27], v[120:121], v[26:27]
	v_lshl_add_u64 v[12:13], v[138:139], 0, s[4:5]
	v_pk_fma_f32 v[20:21], v[20:21], v[0:1], v[4:5]
	v_pk_fma_f32 v[14:15], v[14:15], v[2:3], v[6:7]
	v_cndmask_b32_e64 v23, v21, v232, s[6:7]
	v_cndmask_b32_e64 v22, v20, v232, s[6:7]
	v_cndmask_b32_e64 v15, v15, v232, s[6:7]
	v_cndmask_b32_e64 v14, v14, v232, s[6:7]
	v_pk_mul_f32 v[24:25], v[142:143], v[22:23]
	v_pk_mul_f32 v[20:21], v[126:127], v[14:15]
	v_add_f32_e32 v25, s100, v25
	v_add_f32_e32 v24, s100, v24
	v_add_f32_e32 v20, s100, v20
	v_add_f32_e32 v21, s100, v21
	v_perm_b32 v21, v21, v24, s56
	v_perm_b32 v24, v20, v25, s101
	v_or_b32_e32 v24, v21, v24
	v_sub_f32_e32 v21, v75, v100
	v_sub_f32_e32 v20, v74, v100
	v_pk_mul_f32 v[20:21], v[158:159], v[20:21]
	v_pk_fma_f32 v[26:27], v[26:27], v[2:3], v[6:7]
	v_pk_fma_f32 v[20:21], v[20:21], v[0:1], v[4:5]
	v_cndmask_b32_e64 v27, v27, v232, s[6:7]
	v_cndmask_b32_e64 v29, v21, v232, s[6:7]
	v_cndmask_b32_e64 v28, v20, v232, s[6:7]
	v_cndmask_b32_e64 v26, v26, v232, s[6:7]
	v_pk_mul_f32 v[20:21], v[128:129], v[28:29]
	v_pk_mul_f32 v[30:31], v[122:123], v[26:27]
	v_add_f32_e32 v21, s100, v21
	v_add_f32_e32 v25, s100, v31
	v_add_f32_e32 v30, s100, v30
	v_add_f32_e32 v20, s100, v20
	v_perm_b32 v20, v25, v20, s56
	v_perm_b32 v25, v30, v21, s101
	v_or_b32_e32 v25, v20, v25
	v_lshl_add_u64 v[30:31], v[134:135], 0, v[12:13]
	v_cvt_pk_f16_f32 v21, v14, v15
	v_cvt_pk_f16_f32 v20, v22, v23
	v_cvt_pk_f16_f32 v23, v26, v27
	v_cvt_pk_f16_f32 v22, v28, v29
	s_nop 1
	v_permlane16_swap_b32_e32 v20, v22
	v_permlane16_swap_b32_e32 v21, v23
	v_lshl_add_u64 v[14:15], v[30:31], 1, s[60:61]
	global_store_dwordx4 v[14:15], v[20:23], off
	v_permlane16_swap_b32_e32 v24, v25
	v_lshl_add_u64 v[14:15], s[72:73], 0, v[30:31]
	v_sub_f32_e32 v21, v77, v136
	v_sub_f32_e32 v20, v76, v136
	global_store_dwordx2 v[14:15], v[24:25], off
	v_sub_f32_e32 v15, v79, v136
	v_sub_f32_e32 v14, v78, v136
	v_pk_mul_f32 v[20:21], v[156:157], v[20:21]
	v_pk_mul_f32 v[14:15], v[96:97], v[14:15]
	v_pk_fma_f32 v[20:21], v[20:21], v[0:1], v[4:5]
	v_pk_fma_f32 v[14:15], v[14:15], v[2:3], v[6:7]
	v_cndmask_b32_e64 v23, v21, v232, s[6:7]
	v_cndmask_b32_e64 v22, v20, v232, s[6:7]
	v_cndmask_b32_e64 v15, v15, v232, s[6:7]
	v_cndmask_b32_e64 v14, v14, v232, s[6:7]
	v_pk_mul_f32 v[24:25], v[148:149], v[22:23]
	v_pk_mul_f32 v[20:21], v[98:99], v[14:15]
	v_add_f32_e32 v25, s100, v25
	v_add_f32_e32 v24, s100, v24
	v_add_f32_e32 v20, s100, v20
	v_add_f32_e32 v21, s100, v21
	v_perm_b32 v21, v21, v24, s56
	v_perm_b32 v24, v20, v25, s101
	v_or_b32_e32 v24, v21, v24
	v_sub_f32_e32 v21, v65, v132
	v_sub_f32_e32 v20, v64, v132
	v_sub_f32_e32 v27, v67, v132
	v_sub_f32_e32 v26, v66, v132
	v_pk_mul_f32 v[20:21], v[154:155], v[20:21]
	v_pk_mul_f32 v[26:27], v[104:105], v[26:27]
	v_pk_fma_f32 v[20:21], v[20:21], v[0:1], v[4:5]
	v_pk_fma_f32 v[26:27], v[26:27], v[2:3], v[6:7]
	v_cndmask_b32_e64 v29, v21, v232, s[6:7]
	v_cndmask_b32_e64 v28, v20, v232, s[6:7]
	v_cndmask_b32_e64 v27, v27, v232, s[6:7]
	v_cndmask_b32_e64 v26, v26, v232, s[6:7]
	v_pk_mul_f32 v[20:21], v[108:109], v[28:29]
	v_pk_mul_f32 v[30:31], v[106:107], v[26:27]
	v_add_f32_e32 v21, s100, v21
	v_add_f32_e32 v25, s100, v31
	v_add_f32_e32 v30, s100, v30
	v_add_f32_e32 v20, s100, v20
	v_perm_b32 v20, v25, v20, s56
	v_perm_b32 v25, v30, v21, s101
	v_or_b32_e32 v25, v20, v25
	v_lshl_add_u64 v[30:31], v[116:117], 0, v[12:13]
	v_cvt_pk_f16_f32 v21, v14, v15
	v_cvt_pk_f16_f32 v20, v22, v23
	v_cvt_pk_f16_f32 v23, v26, v27
	v_cvt_pk_f16_f32 v22, v28, v29
	s_nop 1
	v_permlane16_swap_b32_e32 v20, v22
	v_permlane16_swap_b32_e32 v21, v23
	v_lshl_add_u64 v[14:15], v[30:31], 1, s[60:61]
	global_store_dwordx4 v[14:15], v[20:23], off
	v_permlane16_swap_b32_e32 v24, v25
	v_lshl_add_u64 v[14:15], s[72:73], 0, v[30:31]
	v_sub_f32_e32 v21, v49, v118
	v_sub_f32_e32 v20, v48, v118
	global_store_dwordx2 v[14:15], v[24:25], off
	v_sub_f32_e32 v15, v51, v118
	v_sub_f32_e32 v14, v50, v118
	v_pk_mul_f32 v[20:21], v[152:153], v[20:21]
	v_pk_mul_f32 v[14:15], v[56:57], v[14:15]
	v_pk_fma_f32 v[20:21], v[20:21], v[0:1], v[4:5]
	v_pk_fma_f32 v[14:15], v[14:15], v[2:3], v[6:7]
	v_cndmask_b32_e64 v23, v21, v232, s[6:7]
	v_cndmask_b32_e64 v22, v20, v232, s[6:7]
	v_cndmask_b32_e64 v15, v15, v232, s[6:7]
	v_cndmask_b32_e64 v14, v14, v232, s[6:7]
	v_pk_mul_f32 v[24:25], v[150:151], v[22:23]
	v_pk_mul_f32 v[20:21], v[58:59], v[14:15]
	v_add_f32_e32 v25, s100, v25
	v_add_f32_e32 v24, s100, v24
	v_add_f32_e32 v20, s100, v20
	v_add_f32_e32 v21, s100, v21
	v_perm_b32 v21, v21, v24, s56
	v_perm_b32 v24, v20, v25, s101
	v_or_b32_e32 v24, v21, v24
	v_sub_f32_e32 v21, v33, v110
	v_sub_f32_e32 v20, v32, v110
	v_sub_f32_e32 v27, v35, v110
	v_sub_f32_e32 v26, v34, v110
	v_pk_mul_f32 v[20:21], v[146:147], v[20:21]
	v_pk_mul_f32 v[26:27], v[40:41], v[26:27]
	v_pk_fma_f32 v[20:21], v[20:21], v[0:1], v[4:5]
	v_pk_fma_f32 v[26:27], v[26:27], v[2:3], v[6:7]
	v_cndmask_b32_e64 v29, v21, v232, s[6:7]
	v_cndmask_b32_e64 v28, v20, v232, s[6:7]
	v_cndmask_b32_e64 v27, v27, v232, s[6:7]
	v_cndmask_b32_e64 v26, v26, v232, s[6:7]
	v_pk_mul_f32 v[20:21], v[130:131], v[28:29]
	v_pk_mul_f32 v[30:31], v[42:43], v[26:27]
	v_add_f32_e32 v21, s100, v21
	v_add_f32_e32 v25, s100, v31
	v_add_f32_e32 v30, s100, v30
	v_add_f32_e32 v20, s100, v20
	v_perm_b32 v20, v25, v20, s56
	v_perm_b32 v25, v30, v21, s101
	v_or_b32_e32 v25, v20, v25
	v_lshl_add_u64 v[30:31], v[62:63], 0, v[12:13]
	v_cvt_pk_f16_f32 v21, v14, v15
	v_cvt_pk_f16_f32 v20, v22, v23
	v_cvt_pk_f16_f32 v23, v26, v27
	v_cvt_pk_f16_f32 v22, v28, v29
	s_nop 1
	v_permlane16_swap_b32_e32 v20, v22
	v_permlane16_swap_b32_e32 v21, v23
	v_lshl_add_u64 v[14:15], v[30:31], 1, s[60:61]
	v_pk_fma_f32 v[10:11], v[10:11], v[0:1], v[4:5]
	v_pk_fma_f32 v[0:1], v[16:17], v[0:1], v[4:5]
	global_store_dwordx4 v[14:15], v[20:23], off
	v_permlane16_swap_b32_e32 v24, v25
	v_lshl_add_u64 v[14:15], s[72:73], 0, v[30:31]
	v_pk_fma_f32 v[8:9], v[8:9], v[2:3], v[6:7]
	v_cndmask_b32_e64 v11, v11, v232, s[6:7]
	v_cndmask_b32_e64 v10, v10, v232, s[6:7]
	v_pk_fma_f32 v[2:3], v[18:19], v[2:3], v[6:7]
	v_cndmask_b32_e64 v5, v1, v232, s[6:7]
	v_cndmask_b32_e64 v4, v0, v232, s[6:7]
	global_store_dwordx2 v[14:15], v[24:25], off
	v_cndmask_b32_e64 v9, v9, v232, s[6:7]
	v_cndmask_b32_e64 v8, v8, v232, s[6:7]
	v_pk_mul_f32 v[14:15], v[144:145], v[10:11] op_sel_hi:[0,1]
	v_cndmask_b32_e64 v3, v3, v232, s[6:7]
	v_cndmask_b32_e64 v2, v2, v232, s[6:7]
	v_pk_mul_f32 v[0:1], v[44:45], v[4:5] op_sel_hi:[0,1]
	v_pk_mul_f32 v[20:21], v[144:145], v[8:9] op_sel_hi:[0,1]
	v_add_f32_e32 v15, s100, v15
	v_pk_mul_f32 v[6:7], v[44:45], v[2:3] op_sel_hi:[0,1]
	v_add_f32_e32 v1, s100, v1
	v_add_f32_e32 v21, s100, v21
	v_add_f32_e32 v20, s100, v20
	v_add_f32_e32 v14, s100, v14
	v_add_f32_e32 v7, s100, v7
	v_add_f32_e32 v6, s100, v6
	v_add_f32_e32 v0, s100, v0
	v_perm_b32 v14, v21, v14, s56
	v_perm_b32 v0, v7, v0, s56
	v_perm_b32 v15, v20, v15, s101
	v_or_b32_e32 v15, v14, v15
	v_perm_b32 v14, v6, v1, s101
	v_or_b32_e32 v14, v0, v14
	v_lshl_add_u64 v[6:7], v[46:47], 0, v[12:13]
	v_cvt_pk_f16_f32 v1, v2, v3
	v_cvt_pk_f16_f32 v0, v4, v5
	v_cvt_pk_f16_f32 v3, v8, v9
	v_cvt_pk_f16_f32 v2, v10, v11
	s_nop 1
	v_permlane16_swap_b32_e32 v0, v2
	v_permlane16_swap_b32_e32 v1, v3
	v_lshl_add_u64 v[4:5], v[6:7], 1, s[60:61]
	global_store_dwordx4 v[4:5], v[0:3], off
	v_permlane16_swap_b32_e32 v14, v15
	s_nop 0
	v_lshl_add_u64 v[0:1], s[72:73], 0, v[6:7]
	global_store_dwordx2 v[0:1], v[14:15], off

.LBB0_1057:
	s_mov_b32 s100, 0x4b400000
	s_mov_b32 s101, 0xc04000c
	s_waitcnt vmcnt(0) lgkmcnt(0)
	s_barrier
	ds_read_b32 v32, v231 offset:10240
	s_and_saveexec_b64 s[10:11], s[8:9]
	s_cbranch_execz .LBB0_1059
	v_readlane_b32 s8, v254, 5
	v_lshlrev_b64 v[2:3], 5, v[0:1]
	v_readlane_b32 s9, v254, 6
	s_nop 1
	v_lshl_add_u64 v[2:3], s[8:9], 0, v[2:3]
	global_load_dwordx2 v[6:7], v[2:3], off sc1
	global_load_dwordx2 v[34:35], v[2:3], off offset:8 sc1
	global_load_dwordx2 v[36:37], v[2:3], off offset:16 sc1
	global_load_dwordx2 v[38:39], v[2:3], off offset:24 sc1
	s_waitcnt vmcnt(0)
	v_add_f32_e32 v5, 0, v6
	v_add_f32_e32 v5, v5, v34
	v_add_f32_e32 v5, v5, v36
	v_add_f32_e32 v3, v5, v38
	v_fmamk_f32 v5, v3, 0xbe800000, v6
	v_mul_f32_e32 v6, 0x43800000, v5
	v_fmac_f32_e32 v7, v5, v6
	v_fmamk_f32 v6, v3, 0xbe800000, v34
	v_add_f32_e32 v5, 0, v7
	v_mul_f32_e32 v7, 0x43800000, v6
	v_fmac_f32_e32 v35, v6, v7
	v_fmamk_f32 v6, v3, 0xbe800000, v36
	v_mul_f32_e32 v2, 0x3e800000, v3
	v_mul_f32_e32 v7, 0x43800000, v6
	v_fmamk_f32 v3, v3, 0xbe800000, v38
	v_add_f32_e32 v5, v35, v5
	v_fmac_f32_e32 v37, v6, v7
	v_mul_f32_e32 v6, 0x43800000, v3
	v_add_f32_e32 v5, v37, v5
	v_fmac_f32_e32 v39, v3, v6
	v_add_f32_e32 v3, v39, v5
	v_fmamk_f32 v3, v3, 0x3a800000, v217
	v_cmp_gt_f32_e32 vcc, s79, v3
	v_mul_f32_e32 v5, 0x4f800000, v3
	s_nop 0
	v_cndmask_b32_e32 v3, v3, v5, vcc
	v_sqrt_f32_e32 v5, v3
	s_nop 0
	v_add_u32_e32 v6, -1, v5
	v_fma_f32 v7, -v6, v5, v3
	v_cmp_ge_f32_e64 s[8:9], 0, v7
	v_add_u32_e32 v7, 1, v5
	s_nop 0
	v_cndmask_b32_e64 v6, v5, v6, s[8:9]
	v_fma_f32 v5, -v7, v5, v3
	v_cmp_lt_f32_e64 s[8:9], 0, v5
	s_nop 1
	v_cndmask_b32_e64 v5, v6, v7, s[8:9]
	v_mul_f32_e32 v6, 0x37800000, v5
	v_cndmask_b32_e32 v5, v5, v6, vcc
	v_cmp_class_f32_e32 vcc, v3, v215
	s_nop 1
	v_cndmask_b32_e32 v3, v5, v3, vcc
	v_div_scale_f32 v5, s[8:9], v3, v3, 1.0
	v_rcp_f32_e32 v6, v5
	v_readlane_b32 s8, v253, 49
	v_readlane_b32 s9, v253, 50
	v_fma_f32 v7, -v5, v6, 1.0
	v_fmac_f32_e32 v6, v7, v6
	v_div_scale_f32 v7, vcc, 1.0, v3, 1.0
	v_mul_f32_e32 v33, v7, v6
	v_fma_f32 v34, -v5, v33, v7
	v_fmac_f32_e32 v33, v34, v6
	v_fma_f32 v5, -v5, v33, v7
	v_div_fmas_f32 v5, v5, v6, v33
	v_div_fixup_f32 v3, v5, v3, 1.0
	v_lshl_add_u32 v5, v4, 3, 0
	ds_write_b64 v5, v[2:3] offset:8192
	v_lshl_add_u64 v[0:1], v[0:1], 4, s[8:9]
	global_load_dword v6, v[0:1], off sc1
	global_load_dword v7, v[0:1], off offset:4 sc1
	s_waitcnt vmcnt(0)
	v_max3_f32 v6, v6, 0, v7
	global_load_dword v7, v[0:1], off offset:8 sc1
	s_nop 0
	global_load_dword v0, v[0:1], off offset:12 sc1
	v_mul_f32_e32 v1, s29, v3
	s_waitcnt vmcnt(0)
	v_max3_f32 v0, v6, v7, v0
	v_add_f32_e64 v0, |v2|, v0
	v_fma_f32 v0, v0, v1, s28
	v_lshlrev_b32_e32 v1, 2, v4
	v_sub_u32_e32 v1, v5, v1
	ds_write_b32 v1, v0 offset:12288

.LBB0_1063:
	s_or_b64 exec, exec, s[10:11]
	v_sub_f32_e32 v113, v149, v32
	v_sub_f32_e32 v112, v148, v32
	v_pk_mul_f32 v[112:113], v[32:33], v[112:113] op_sel:[1,0]
	v_div_scale_f32 v97, s[10:11], v44, v44, s81
	s_waitcnt vmcnt(0)
	v_pk_fma_f32 v[112:113], v[0:1], v[112:113], v[4:5]
	v_sub_f32_e32 v99, v151, v32
	v_cndmask_b32_e64 v159, v113, v232, s[6:7]
	v_rcp_f32_e32 v113, v97
	v_cndmask_b32_e64 v158, v112, v232, s[6:7]
	v_sub_f32_e32 v98, v150, v32
	v_pk_mul_f32 v[98:99], v[32:33], v[98:99] op_sel:[1,0]
	v_fma_f32 v112, -v97, v113, 1.0
	v_fmac_f32_e32 v113, v112, v113
	v_div_scale_f32 v112, vcc, s81, v44, s81
	v_mul_f32_e32 v114, v112, v113
	v_fma_f32 v148, -v97, v114, v112
	v_fmac_f32_e32 v114, v148, v113
	v_fma_f32 v97, -v97, v114, v112
	v_div_fmas_f32 v97, v97, v113, v114
	v_pk_fma_f32 v[98:99], v[2:3], v[98:99], v[6:7]
	v_div_fixup_f32 v44, v97, v44, s81
	v_cndmask_b32_e64 v99, v99, v232, s[6:7]
	v_cndmask_b32_e64 v98, v98, v232, s[6:7]
	v_pk_mul_f32 v[148:149], v[44:45], v[158:159] op_sel_hi:[0,1]
	v_pk_mul_f32 v[112:113], v[44:45], v[98:99] op_sel_hi:[0,1]
	v_add_f32_e32 v114, s100, v149
	v_add_f32_e32 v97, s100, v148
	v_add_f32_e32 v112, s100, v112
	v_add_f32_e32 v113, s100, v113
	v_readlane_b32 s3, v254, 17
	v_perm_b32 v97, v113, v97, s85
	s_add_i32 s3, s3, s4
	v_perm_b32 v161, v112, v114, s101
	v_or_b32_e32 v161, v97, v161
	v_or_b32_e32 v149, s3, v96
	v_and_b32_e32 v96, -8, v179
	v_div_scale_f32 v114, s[4:5], v47, v47, s81
	v_ashrrev_i32_e32 v97, 31, v96
	v_rcp_f32_e32 v148, v114
	v_lshl_add_u64 v[112:113], s[0:1], 0, v[96:97]
	v_sub_f32_e32 v97, v153, v38
	v_sub_f32_e32 v96, v152, v38
	v_pk_mul_f32 v[96:97], v[38:39], v[96:97] op_sel:[1,0]
	v_sub_f32_e32 v151, v155, v38
	v_pk_fma_f32 v[96:97], v[2:3], v[96:97], v[6:7]
	v_sub_f32_e32 v150, v154, v38
	v_cndmask_b32_e64 v152, v96, v232, s[6:7]
	v_fma_f32 v96, -v114, v148, 1.0
	v_pk_mul_f32 v[150:151], v[38:39], v[150:151] op_sel:[1,0]
	v_fmac_f32_e32 v148, v96, v148
	v_div_scale_f32 v96, vcc, s81, v47, s81
	v_pk_fma_f32 v[150:151], v[0:1], v[150:151], v[4:5]
	v_cndmask_b32_e64 v153, v97, v232, s[6:7]
	v_mul_f32_e32 v97, v96, v148
	v_cndmask_b32_e64 v154, v150, v232, s[6:7]
	v_fma_f32 v150, -v114, v97, v96
	v_fmac_f32_e32 v97, v150, v148
	v_fma_f32 v96, -v114, v97, v96
	v_div_fmas_f32 v96, v96, v148, v97
	v_cndmask_b32_e64 v155, v151, v232, s[6:7]
	v_div_fixup_f32 v114, v96, v47, s81
	v_pk_mul_f32 v[150:151], v[114:115], v[154:155] op_sel_hi:[0,1]
	v_pk_mul_f32 v[96:97], v[114:115], v[152:153] op_sel_hi:[0,1]
	v_add_f32_e32 v148, s100, v151
	v_add_f32_e32 v47, s100, v150
	v_add_f32_e32 v96, s100, v96
	v_add_f32_e32 v97, s100, v97
	v_perm_b32 v47, v97, v47, s85
	v_and_b32_e32 v151, 16, v178
	v_perm_b32 v160, v96, v148, s101
	v_or_b32_e32 v160, v47, v160
	v_or_b32_e32 v96, v149, v151
	v_ashrrev_i32_e32 v97, 31, v96
	v_lshlrev_b64 v[96:97], 10, v[96:97]
	v_lshl_add_u64 v[162:163], v[96:97], 0, v[112:113]
	v_cvt_pk_f16_f32 v153, v152, v153
	v_cvt_pk_f16_f32 v152, v154, v155
	v_cvt_pk_f16_f32 v155, v98, v99
	v_cvt_pk_f16_f32 v154, v158, v159
	s_nop 1
	v_permlane16_swap_b32_e32 v152, v154
	v_permlane16_swap_b32_e32 v153, v155
	v_lshl_add_u64 v[98:99], v[162:163], 1, s[60:61]
	global_store_dwordx4 v[98:99], v[152:155], off
	v_add_u32_e32 v47, v46, v115
	v_add_u32_e32 v46, v47, v156
	ds_read_b64 v[98:99], v47 offset:8448
	ds_read_b32 v47, v46 offset:12416
	v_permlane16_swap_b32_e32 v160, v161
	v_lshl_add_u64 v[152:153], s[72:73], 0, v[162:163]
	global_store_dwordx2 v[152:153], v[160:161], off
	s_waitcnt lgkmcnt(0)
	v_max_f32_e32 v47, v47, v47
	v_max_f32_e32 v148, 0xda24260, v47
	s_and_saveexec_b64 s[10:11], s[8:9]
	s_cbranch_execz .LBB0_1065
	v_readlane_b32 s3, v254, 17
	v_mul_f32_e32 v47, 0x3c010204, v148
	v_cndmask_b32_e64 v47, v47, v232, s[6:7]
	v_add3_u32 v152, s3, v45, 32
	v_ashrrev_i32_e32 v153, 31, v152
	v_lshl_add_u64 v[152:153], v[152:153], 2, s[24:25]
	global_store_dword v[152:153], v47, off

.LBB0_1067:
	s_or_b64 exec, exec, s[10:11]
	s_waitcnt lgkmcnt(0)
	v_sub_f32_e32 v109, v109, v46
	v_sub_f32_e32 v108, v108, v46
	v_pk_mul_f32 v[108:109], v[46:47], v[108:109] op_sel:[1,0]
	v_sub_f32_e32 v111, v111, v46
	v_pk_fma_f32 v[108:109], v[0:1], v[108:109], v[4:5]
	v_sub_f32_e32 v110, v110, v46
	v_cndmask_b32_e64 v159, v109, v232, s[6:7]
	v_div_scale_f32 v109, s[4:5], v152, v152, s81
	v_rcp_f32_e32 v153, v109
	v_cndmask_b32_e64 v158, v108, v232, s[6:7]
	v_pk_mul_f32 v[110:111], v[46:47], v[110:111] op_sel:[1,0]
	v_sub_f32_e32 v125, v125, v98
	v_fma_f32 v108, -v109, v153, 1.0
	v_fmac_f32_e32 v153, v108, v153
	v_div_scale_f32 v108, vcc, s81, v152, s81
	v_mul_f32_e32 v154, v108, v153
	v_fma_f32 v155, -v109, v154, v108
	v_fmac_f32_e32 v154, v155, v153
	v_fma_f32 v108, -v109, v154, v108
	v_div_fmas_f32 v108, v108, v153, v154
	v_pk_fma_f32 v[110:111], v[2:3], v[110:111], v[6:7]
	v_div_fixup_f32 v108, v108, v152, s81
	v_cndmask_b32_e64 v111, v111, v232, s[6:7]
	v_cndmask_b32_e64 v110, v110, v232, s[6:7]
	v_pk_mul_f32 v[154:155], v[108:109], v[158:159] op_sel_hi:[0,1]
	v_pk_mul_f32 v[152:153], v[108:109], v[110:111] op_sel_hi:[0,1]
	v_add_f32_e32 v109, s100, v154
	v_add_f32_e32 v154, s100, v155
	v_add_f32_e32 v152, s100, v152
	v_add_f32_e32 v153, s100, v153
	v_sub_f32_e32 v124, v124, v98
	v_perm_b32 v109, v153, v109, s85
	v_pk_mul_f32 v[124:125], v[98:99], v[124:125] op_sel:[1,0]
	v_perm_b32 v161, v152, v154, s101
	v_or_b32_e32 v161, v109, v161
	v_pk_fma_f32 v[124:125], v[0:1], v[124:125], v[4:5]
	v_div_scale_f32 v109, s[4:5], v148, v148, s81
	v_cndmask_b32_e64 v155, v125, v232, s[6:7]
	v_rcp_f32_e32 v125, v109
	v_cndmask_b32_e64 v154, v124, v232, s[6:7]
	v_sub_f32_e32 v127, v127, v98
	v_sub_f32_e32 v126, v126, v98
	v_fma_f32 v124, -v109, v125, 1.0
	v_fmac_f32_e32 v125, v124, v125
	v_div_scale_f32 v124, vcc, s81, v148, s81
	v_mul_f32_e32 v152, v124, v125
	v_fma_f32 v153, -v109, v152, v124
	v_fmac_f32_e32 v152, v153, v125
	v_fma_f32 v109, -v109, v152, v124
	v_pk_mul_f32 v[126:127], v[98:99], v[126:127] op_sel:[1,0]
	v_div_fmas_f32 v109, v109, v125, v152
	v_pk_fma_f32 v[126:127], v[2:3], v[126:127], v[6:7]
	v_div_fixup_f32 v148, v109, v148, s81
	v_cndmask_b32_e64 v127, v127, v232, s[6:7]
	v_cndmask_b32_e64 v126, v126, v232, s[6:7]
	v_pk_mul_f32 v[152:153], v[148:149], v[154:155] op_sel_hi:[0,1]
	v_pk_mul_f32 v[124:125], v[148:149], v[126:127] op_sel_hi:[0,1]
	v_add_f32_e32 v109, s100, v152
	v_add_f32_e32 v152, s100, v153
	v_add_f32_e32 v124, s100, v124
	v_add_f32_e32 v125, s100, v125
	v_perm_b32 v109, v125, v109, s85
	v_perm_b32 v160, v124, v152, s101
	v_or_b32_e32 v160, v109, v160
	v_or_b32_e32 v109, 32, v151
	v_or_b32_e32 v124, v149, v109
	v_ashrrev_i32_e32 v125, 31, v124
	v_lshlrev_b64 v[124:125], 10, v[124:125]
	v_lshl_add_u64 v[162:163], v[124:125], 0, v[112:113]
	v_cvt_pk_f16_f32 v153, v126, v127
	v_cvt_pk_f16_f32 v152, v154, v155
	v_cvt_pk_f16_f32 v155, v110, v111
	v_cvt_pk_f16_f32 v154, v158, v159
	s_nop 1
	v_permlane16_swap_b32_e32 v152, v154
	v_permlane16_swap_b32_e32 v153, v155
	v_lshl_add_u64 v[110:111], v[162:163], 1, s[60:61]
	global_store_dwordx4 v[110:111], v[152:155], off
	v_add_u32_e32 v111, v150, v115
	v_add_u32_e32 v110, v111, v156
	ds_read_b32 v150, v110 offset:12800
	ds_read_b64 v[126:127], v111 offset:9216
	v_permlane16_swap_b32_e32 v160, v161
	v_lshl_add_u64 v[152:153], s[72:73], 0, v[162:163]
	s_waitcnt lgkmcnt(1)
	v_max_f32_e32 v111, v150, v150
	v_max_f32_e32 v150, 0xda24260, v111
	global_store_dwordx2 v[152:153], v[160:161], off
	s_and_saveexec_b64 s[10:11], s[8:9]
	s_cbranch_execz .LBB0_1069
	v_readlane_b32 s3, v254, 14
	v_mul_f32_e32 v111, 0x3c010204, v150
	v_cndmask_b32_e64 v111, v111, v232, s[6:7]
	v_add_u32_e32 v152, s3, v45
	v_ashrrev_i32_e32 v153, 31, v152
	v_lshl_add_u64 v[152:153], v[152:153], 2, s[24:25]
	global_store_dword v[152:153], v111, off

.LBB0_1071:
	s_or_b64 exec, exec, s[10:11]
	s_waitcnt lgkmcnt(0)
	v_sub_f32_e32 v77, v77, v110
	v_sub_f32_e32 v76, v76, v110
	v_pk_mul_f32 v[76:77], v[110:111], v[76:77] op_sel:[1,0]
	v_sub_f32_e32 v79, v79, v110
	v_pk_fma_f32 v[76:77], v[0:1], v[76:77], v[4:5]
	v_sub_f32_e32 v78, v78, v110
	v_cndmask_b32_e64 v155, v77, v232, s[6:7]
	v_div_scale_f32 v77, s[4:5], v153, v153, s81
	v_rcp_f32_e32 v157, v77
	v_cndmask_b32_e64 v154, v76, v232, s[6:7]
	v_pk_mul_f32 v[78:79], v[110:111], v[78:79] op_sel:[1,0]
	v_sub_f32_e32 v93, v93, v126
	v_fma_f32 v76, -v77, v157, 1.0
	v_fmac_f32_e32 v157, v76, v157
	v_div_scale_f32 v76, vcc, s81, v153, s81
	v_mul_f32_e32 v158, v76, v157
	v_fma_f32 v159, -v77, v158, v76
	v_fmac_f32_e32 v158, v159, v157
	v_fma_f32 v76, -v77, v158, v76
	v_div_fmas_f32 v76, v76, v157, v158
	v_pk_fma_f32 v[78:79], v[2:3], v[78:79], v[6:7]
	v_div_fixup_f32 v76, v76, v153, s81
	v_cndmask_b32_e64 v79, v79, v232, s[6:7]
	v_cndmask_b32_e64 v78, v78, v232, s[6:7]
	v_pk_mul_f32 v[160:161], v[76:77], v[154:155] op_sel_hi:[0,1]
	v_pk_mul_f32 v[158:159], v[76:77], v[78:79] op_sel_hi:[0,1]
	v_add_f32_e32 v153, s100, v161
	v_add_f32_e32 v77, s100, v160
	v_add_f32_e32 v157, s100, v158
	v_add_f32_e32 v158, s100, v159
	v_sub_f32_e32 v92, v92, v126
	v_pk_mul_f32 v[92:93], v[126:127], v[92:93] op_sel:[1,0]
	v_pk_fma_f32 v[92:93], v[0:1], v[92:93], v[4:5]
	v_perm_b32 v77, v158, v77, s85
	v_cndmask_b32_e64 v161, v93, v232, s[6:7]
	v_div_scale_f32 v93, s[4:5], v150, v150, s81
	v_perm_b32 v163, v157, v153, s101
	v_or_b32_e32 v163, v77, v163
	v_add_u32_e32 v77, 0x80, v149
	v_rcp_f32_e32 v149, v93
	v_cndmask_b32_e64 v160, v92, v232, s[6:7]
	v_sub_f32_e32 v95, v95, v126
	v_sub_f32_e32 v94, v94, v126
	v_fma_f32 v92, -v93, v149, 1.0
	v_fmac_f32_e32 v149, v92, v149
	v_div_scale_f32 v92, vcc, s81, v150, s81
	v_mul_f32_e32 v153, v92, v149
	v_fma_f32 v157, -v93, v153, v92
	v_fmac_f32_e32 v153, v157, v149
	v_fma_f32 v92, -v93, v153, v92
	v_pk_mul_f32 v[94:95], v[126:127], v[94:95] op_sel:[1,0]
	v_div_fmas_f32 v92, v92, v149, v153
	v_pk_fma_f32 v[94:95], v[2:3], v[94:95], v[6:7]
	v_div_fixup_f32 v150, v92, v150, s81
	v_cndmask_b32_e64 v95, v95, v232, s[6:7]
	v_cndmask_b32_e64 v94, v94, v232, s[6:7]
	v_pk_mul_f32 v[158:159], v[150:151], v[160:161] op_sel_hi:[0,1]
	v_pk_mul_f32 v[92:93], v[150:151], v[94:95] op_sel_hi:[0,1]
	v_add_f32_e32 v153, s100, v159
	v_add_f32_e32 v149, s100, v158
	v_add_f32_e32 v92, s100, v92
	v_add_f32_e32 v93, s100, v93
	v_perm_b32 v93, v93, v149, s85
	v_perm_b32 v162, v92, v153, s101
	v_or_b32_e32 v162, v93, v162
	v_or_b32_e32 v92, v77, v151
	v_ashrrev_i32_e32 v93, 31, v92
	v_lshlrev_b64 v[92:93], 10, v[92:93]
	v_lshl_add_u64 v[164:165], v[92:93], 0, v[112:113]
	v_cvt_pk_f16_f32 v159, v94, v95
	v_cvt_pk_f16_f32 v158, v160, v161
	v_cvt_pk_f16_f32 v161, v78, v79
	v_cvt_pk_f16_f32 v160, v154, v155
	s_nop 1
	v_permlane16_swap_b32_e32 v158, v160
	v_permlane16_swap_b32_e32 v159, v161
	v_lshl_add_u64 v[78:79], v[164:165], 1, s[60:61]
	global_store_dwordx4 v[78:79], v[158:161], off
	v_add_u32_e32 v78, v152, v115
	v_add_u32_e32 v94, v78, v156
	ds_read_b32 v95, v94 offset:12928
	ds_read_b64 v[78:79], v78 offset:9472
	v_permlane16_swap_b32_e32 v162, v163
	v_lshl_add_u64 v[152:153], s[72:73], 0, v[164:165]
	s_waitcnt lgkmcnt(1)
	v_max_f32_e32 v95, v95, v95
	v_max_f32_e32 v149, 0xda24260, v95
	global_store_dwordx2 v[152:153], v[162:163], off
	s_and_saveexec_b64 s[10:11], s[8:9]
	s_cbranch_execz .LBB0_1073
	v_readlane_b32 s3, v254, 16
	v_mul_f32_e32 v95, 0x3c010204, v149
	v_cndmask_b32_e64 v95, v95, v232, s[6:7]
	v_add_u32_e32 v152, s3, v45
	v_ashrrev_i32_e32 v153, 31, v152
	v_lshl_add_u64 v[152:153], v[152:153], 2, s[24:25]
	global_store_dword v[152:153], v95, off

.LBB0_1075:
	s_or_b64 exec, exec, s[10:11]
	s_waitcnt lgkmcnt(0)
	v_sub_f32_e32 v129, v129, v94
	v_sub_f32_e32 v128, v128, v94
	v_pk_mul_f32 v[128:129], v[94:95], v[128:129] op_sel:[1,0]
	v_div_scale_f32 v45, s[4:5], v115, v115, s81
	v_pk_fma_f32 v[128:129], v[2:3], v[128:129], v[6:7]
	v_sub_f32_e32 v131, v131, v94
	v_cndmask_b32_e64 v153, v129, v232, s[6:7]
	v_rcp_f32_e32 v129, v45
	v_cndmask_b32_e64 v152, v128, v232, s[6:7]
	v_sub_f32_e32 v130, v130, v94
	v_pk_mul_f32 v[130:131], v[94:95], v[130:131] op_sel:[1,0]
	v_fma_f32 v128, -v45, v129, 1.0
	v_fmac_f32_e32 v129, v128, v129
	v_div_scale_f32 v128, vcc, s81, v115, s81
	v_mul_f32_e32 v151, v128, v129
	v_fma_f32 v154, -v45, v151, v128
	v_fmac_f32_e32 v151, v154, v129
	v_fma_f32 v45, -v45, v151, v128
	v_pk_fma_f32 v[130:131], v[0:1], v[130:131], v[4:5]
	v_div_fmas_f32 v45, v45, v129, v151
	v_sub_f32_e32 v63, v63, v78
	v_sub_f32_e32 v62, v62, v78
	v_cndmask_b32_e64 v131, v131, v232, s[6:7]
	v_cndmask_b32_e64 v130, v130, v232, s[6:7]
	v_div_fixup_f32 v128, v45, v115, s81
	v_pk_mul_f32 v[62:63], v[78:79], v[62:63] op_sel:[1,0]
	v_pk_mul_f32 v[154:155], v[128:129], v[130:131] op_sel_hi:[0,1]
	v_pk_fma_f32 v[2:3], v[2:3], v[62:63], v[6:7]
	v_div_scale_f32 v6, s[4:5], v149, v149, s81
	v_pk_mul_f32 v[156:157], v[128:129], v[152:153] op_sel_hi:[0,1]
	v_add_f32_e32 v129, s100, v155
	v_rcp_f32_e32 v7, v6
	v_add_f32_e32 v45, s100, v157
	v_add_f32_e32 v115, s100, v156
	v_add_f32_e32 v151, s100, v154
	v_sub_f32_e32 v61, v61, v78
	v_sub_f32_e32 v60, v60, v78
	v_pk_mul_f32 v[60:61], v[78:79], v[60:61] op_sel:[1,0]
	v_pk_fma_f32 v[0:1], v[0:1], v[60:61], v[4:5]
	v_cndmask_b32_e64 v4, v0, v232, s[6:7]
	v_fma_f32 v0, -v6, v7, 1.0
	v_fmac_f32_e32 v7, v0, v7
	v_div_scale_f32 v0, vcc, s81, v149, s81
	v_perm_b32 v45, v45, v151, s85
	v_cndmask_b32_e64 v5, v1, v232, s[6:7]
	v_mul_f32_e32 v1, v0, v7
	v_perm_b32 v155, v115, v129, s101
	v_or_b32_e32 v155, v45, v155
	v_fma_f32 v45, -v6, v1, v0
	v_fmac_f32_e32 v1, v45, v7
	v_fma_f32 v0, -v6, v1, v0
	v_div_fmas_f32 v0, v0, v7, v1
	v_div_fixup_f32 v60, v0, v149, s81
	v_cndmask_b32_e64 v3, v3, v232, s[6:7]
	v_cndmask_b32_e64 v2, v2, v232, s[6:7]
	v_pk_mul_f32 v[0:1], v[60:61], v[4:5] op_sel_hi:[0,1]
	v_pk_mul_f32 v[6:7], v[60:61], v[2:3] op_sel_hi:[0,1]
	v_add_f32_e32 v1, s100, v1
	v_add_f32_e32 v7, s100, v7
	v_add_f32_e32 v6, s100, v6
	v_add_f32_e32 v0, s100, v0
	v_perm_b32 v0, v7, v0, s85
	v_perm_b32 v154, v6, v1, s101
	v_or_b32_e32 v154, v0, v154
	v_or_b32_e32 v0, v77, v109
	v_ashrrev_i32_e32 v1, 31, v0
	v_lshlrev_b64 v[62:63], 10, v[0:1]
	v_lshl_add_u64 v[6:7], v[62:63], 0, v[112:113]
	v_cvt_pk_f16_f32 v1, v2, v3
	v_cvt_pk_f16_f32 v0, v4, v5
	v_cvt_pk_f16_f32 v3, v152, v153
	v_cvt_pk_f16_f32 v2, v130, v131
	s_nop 1
	v_permlane16_swap_b32_e32 v0, v2
	v_permlane16_swap_b32_e32 v1, v3
	v_lshl_add_u64 v[4:5], v[6:7], 1, s[60:61]
	global_store_dwordx4 v[4:5], v[0:3], off
	v_permlane16_swap_b32_e32 v154, v155
	s_nop 0
	v_lshl_add_u64 v[0:1], s[72:73], 0, v[6:7]
	global_store_dwordx2 v[0:1], v[154:155], off
	v_mov_b32_e32 v0, v180
	v_mov_b32_e32 v1, v181
	v_mov_b32_e32 v2, v182
	v_mov_b32_e32 v3, v183
	v_mov_b32_e32 v4, v184
	v_mov_b32_e32 v5, v185
	v_mov_b32_e32 v6, v186
	v_mov_b32_e32 v7, v187
	v_mov_b32_e32 v160, v39
	v_mov_b32_e32 v161, v39
	v_sub_f32_e32 v165, v141, v38
	v_sub_f32_e32 v164, v140, v38
	v_sub_f32_e32 v141, v143, v38
	v_sub_f32_e32 v140, v142, v38
	v_pk_mul_f32 v[142:143], v[160:161], v[140:141]
	v_mov_b32_e32 v140, v39
	v_mov_b32_e32 v141, v39
	v_pk_mul_f32 v[164:165], v[140:141], v[164:165]
	v_mov_b32_e32 v115, v114
	v_mov_b32_e32 v158, v33
	v_mov_b32_e32 v159, v33
	v_sub_f32_e32 v147, v147, v32
	v_sub_f32_e32 v146, v146, v32
	v_pk_mul_f32 v[146:147], v[158:159], v[146:147]
	v_mov_b32_e32 v45, v44
	v_lshl_add_u64 v[162:163], v[112:113], 0, 16
	v_mov_b32_e32 v156, v99
	v_mov_b32_e32 v157, v99
	v_sub_f32_e32 v121, v121, v98
	v_sub_f32_e32 v120, v120, v98
	v_sub_f32_e32 v123, v123, v98
	v_sub_f32_e32 v122, v122, v98
	v_mov_b32_e32 v149, v148
	v_mov_b32_e32 v154, v47
	v_mov_b32_e32 v155, v47
	v_sub_f32_e32 v107, v107, v46
	v_sub_f32_e32 v106, v106, v46
	v_mov_b32_e32 v109, v108
	v_mov_b32_e32 v152, v127
	v_mov_b32_e32 v153, v127
	v_sub_f32_e32 v89, v89, v126
	v_sub_f32_e32 v88, v88, v126
	v_sub_f32_e32 v91, v91, v126
	v_sub_f32_e32 v90, v90, v126
	v_mov_b32_e32 v151, v150
	v_mov_b32_e32 v130, v111
	v_mov_b32_e32 v131, v111
	v_sub_f32_e32 v75, v75, v110
	v_sub_f32_e32 v74, v74, v110
	v_mov_b32_e32 v77, v76
	v_sub_f32_e32 v57, v57, v78
	v_sub_f32_e32 v56, v56, v78
	v_sub_f32_e32 v41, v41, v94
	v_sub_f32_e32 v40, v40, v94
	v_sub_f32_e32 v59, v59, v78
	v_sub_f32_e32 v58, v58, v78
	v_pk_mul_f32 v[56:57], v[78:79], v[56:57] op_sel:[1,0]
	v_sub_f32_e32 v43, v43, v94
	v_sub_f32_e32 v42, v42, v94
	v_pk_mul_f32 v[40:41], v[94:95], v[40:41] op_sel:[1,0]
	v_pk_mul_f32 v[58:59], v[78:79], v[58:59] op_sel:[1,0]
	v_pk_mul_f32 v[42:43], v[94:95], v[42:43] op_sel:[1,0]
	v_sub_f32_e32 v53, v53, v78
	v_sub_f32_e32 v52, v52, v78
	v_sub_f32_e32 v13, v13, v94
	v_sub_f32_e32 v12, v12, v94
	v_pk_mul_f32 v[52:53], v[78:79], v[52:53] op_sel:[1,0]
	v_sub_f32_e32 v15, v15, v94
	v_sub_f32_e32 v14, v14, v94
	v_pk_mul_f32 v[12:13], v[94:95], v[12:13] op_sel:[1,0]
	v_pk_mul_f32 v[14:15], v[94:95], v[14:15] op_sel:[1,0]
	v_sub_f32_e32 v23, v23, v32
	v_sub_f32_e32 v22, v22, v32
	v_sub_f32_e32 v21, v21, v32
	v_sub_f32_e32 v20, v20, v32
	v_pk_mul_f32 v[22:23], v[158:159], v[22:23]
	s_mov_b64 s[4:5], 0x90
	v_sub_f32_e32 v9, v9, v94
	v_sub_f32_e32 v8, v8, v94
	v_sub_f32_e32 v11, v11, v94
	v_sub_f32_e32 v10, v10, v94
	v_pk_mul_f32 v[8:9], v[94:95], v[8:9] op_sel:[1,0]
	v_pk_mul_f32 v[10:11], v[94:95], v[10:11] op_sel:[1,0]
	v_pk_fma_f32 v[142:143], v[142:143], v[0:1], v[4:5]
	v_pk_fma_f32 v[164:165], v[164:165], v[2:3], v[6:7]
	v_cndmask_b32_e64 v167, v143, v232, s[6:7]
	v_cndmask_b32_e64 v166, v142, v232, s[6:7]
	v_cndmask_b32_e64 v165, v165, v232, s[6:7]
	v_cndmask_b32_e64 v164, v164, v232, s[6:7]
	v_mov_b32_e32 v142, v114
	v_mov_b32_e32 v143, v114
	v_pk_mul_f32 v[170:171], v[114:115], v[166:167]
	v_pk_mul_f32 v[168:169], v[142:143], v[164:165]
	v_add_f32_e32 v61, s100, v171
	v_add_f32_e32 v39, s100, v170
	v_add_f32_e32 v129, s100, v168
	v_add_f32_e32 v168, s100, v169
	v_sub_f32_e32 v171, v145, v32
	v_sub_f32_e32 v170, v144, v32
	v_mov_b32_e32 v144, v33
	v_mov_b32_e32 v145, v33
	v_pk_mul_f32 v[170:171], v[144:145], v[170:171]
	v_pk_fma_f32 v[146:147], v[146:147], v[0:1], v[4:5]
	v_pk_fma_f32 v[170:171], v[170:171], v[2:3], v[6:7]
	v_cndmask_b32_e64 v173, v147, v232, s[6:7]
	v_cndmask_b32_e64 v172, v146, v232, s[6:7]
	v_perm_b32 v39, v168, v39, s85
	v_cndmask_b32_e64 v171, v171, v232, s[6:7]
	v_cndmask_b32_e64 v170, v170, v232, s[6:7]
	v_pk_mul_f32 v[174:175], v[44:45], v[172:173]
	v_mov_b32_e32 v146, v44
	v_mov_b32_e32 v147, v44
	v_perm_b32 v168, v129, v61, s101
	v_or_b32_e32 v168, v39, v168
	v_pk_mul_f32 v[176:177], v[146:147], v[170:171]
	v_add_f32_e32 v61, s100, v175
	v_add_f32_e32 v33, s100, v177
	v_add_f32_e32 v39, s100, v176
	v_add_f32_e32 v129, s100, v174
	v_perm_b32 v33, v33, v129, s85
	v_lshl_add_u64 v[174:175], v[96:97], 0, v[162:163]
	v_cvt_pk_f16_f32 v165, v164, v165
	v_cvt_pk_f16_f32 v164, v166, v167
	v_cvt_pk_f16_f32 v167, v170, v171
	v_cvt_pk_f16_f32 v166, v172, v173
	v_perm_b32 v169, v39, v61, s101
	v_or_b32_e32 v169, v33, v169
	s_nop 0
	v_permlane16_swap_b32_e32 v164, v166
	v_permlane16_swap_b32_e32 v165, v167
	v_lshl_add_u64 v[170:171], v[174:175], 1, s[60:61]
	global_store_dwordx4 v[170:171], v[164:167], off
	v_permlane16_swap_b32_e32 v168, v169
	s_nop 0
	v_lshl_add_u64 v[164:165], s[72:73], 0, v[174:175]
	global_store_dwordx2 v[164:165], v[168:169], off
	v_pk_mul_f32 v[164:165], v[156:157], v[120:121]
	v_mov_b32_e32 v120, v99
	v_mov_b32_e32 v121, v99
	v_pk_mul_f32 v[122:123], v[120:121], v[122:123]
	v_pk_fma_f32 v[164:165], v[164:165], v[0:1], v[4:5]
	v_pk_fma_f32 v[122:123], v[122:123], v[2:3], v[6:7]
	v_cndmask_b32_e64 v167, v165, v232, s[6:7]
	v_cndmask_b32_e64 v166, v164, v232, s[6:7]
	v_cndmask_b32_e64 v165, v123, v232, s[6:7]
	v_cndmask_b32_e64 v164, v122, v232, s[6:7]
	v_mov_b32_e32 v122, v148
	v_mov_b32_e32 v123, v148
	v_pk_mul_f32 v[170:171], v[148:149], v[166:167]
	v_pk_mul_f32 v[168:169], v[122:123], v[164:165]
	v_add_f32_e32 v39, s100, v171
	v_add_f32_e32 v33, s100, v170
	v_add_f32_e32 v61, s100, v168
	v_add_f32_e32 v99, s100, v169
	v_sub_f32_e32 v171, v105, v46
	v_sub_f32_e32 v170, v104, v46
	v_mov_b32_e32 v104, v47
	v_mov_b32_e32 v105, v47
	v_pk_mul_f32 v[170:171], v[154:155], v[170:171]
	v_pk_mul_f32 v[106:107], v[104:105], v[106:107]
	v_pk_fma_f32 v[170:171], v[170:171], v[0:1], v[4:5]
	v_pk_fma_f32 v[106:107], v[106:107], v[2:3], v[6:7]
	v_cndmask_b32_e64 v171, v171, v232, s[6:7]
	v_cndmask_b32_e64 v170, v170, v232, s[6:7]
	v_cndmask_b32_e64 v173, v107, v232, s[6:7]
	v_cndmask_b32_e64 v172, v106, v232, s[6:7]
	v_pk_mul_f32 v[174:175], v[108:109], v[170:171]
	v_mov_b32_e32 v106, v108
	v_mov_b32_e32 v107, v108
	v_perm_b32 v33, v99, v33, s85
	v_pk_mul_f32 v[176:177], v[106:107], v[172:173]
	v_add_f32_e32 v47, s100, v175
	v_perm_b32 v168, v61, v39, s101
	v_or_b32_e32 v168, v33, v168
	v_add_f32_e32 v33, s100, v177
	v_add_f32_e32 v39, s100, v176
	v_add_f32_e32 v61, s100, v174
	v_perm_b32 v33, v33, v61, s85
	v_lshl_add_u64 v[174:175], v[124:125], 0, v[162:163]
	v_cvt_pk_f16_f32 v165, v164, v165
	v_cvt_pk_f16_f32 v164, v166, v167
	v_cvt_pk_f16_f32 v167, v172, v173
	v_cvt_pk_f16_f32 v166, v170, v171
	v_perm_b32 v169, v39, v47, s101
	v_or_b32_e32 v169, v33, v169
	s_nop 0
	v_permlane16_swap_b32_e32 v164, v166
	v_permlane16_swap_b32_e32 v165, v167
	v_lshl_add_u64 v[170:171], v[174:175], 1, s[60:61]
	global_store_dwordx4 v[170:171], v[164:167], off
	v_permlane16_swap_b32_e32 v168, v169
	s_nop 0
	v_lshl_add_u64 v[164:165], s[72:73], 0, v[174:175]
	global_store_dwordx2 v[164:165], v[168:169], off
	v_pk_mul_f32 v[164:165], v[152:153], v[88:89]
	v_mov_b32_e32 v88, v127
	v_mov_b32_e32 v89, v127
	v_pk_mul_f32 v[90:91], v[88:89], v[90:91]
	v_pk_fma_f32 v[164:165], v[164:165], v[0:1], v[4:5]
	v_pk_fma_f32 v[90:91], v[90:91], v[2:3], v[6:7]
	v_cndmask_b32_e64 v167, v165, v232, s[6:7]
	v_cndmask_b32_e64 v166, v164, v232, s[6:7]
	v_cndmask_b32_e64 v165, v91, v232, s[6:7]
	v_cndmask_b32_e64 v164, v90, v232, s[6:7]
	v_mov_b32_e32 v90, v150
	v_mov_b32_e32 v91, v150
	v_pk_mul_f32 v[170:171], v[150:151], v[166:167]
	v_pk_mul_f32 v[168:169], v[90:91], v[164:165]
	v_add_f32_e32 v39, s100, v171
	v_add_f32_e32 v33, s100, v170
	v_add_f32_e32 v47, s100, v168
	v_add_f32_e32 v61, s100, v169
	v_sub_f32_e32 v171, v73, v110
	v_sub_f32_e32 v170, v72, v110
	v_mov_b32_e32 v72, v111
	v_mov_b32_e32 v73, v111
	v_pk_mul_f32 v[170:171], v[130:131], v[170:171]
	v_pk_mul_f32 v[74:75], v[72:73], v[74:75]
	v_pk_fma_f32 v[170:171], v[170:171], v[0:1], v[4:5]
	v_pk_fma_f32 v[74:75], v[74:75], v[2:3], v[6:7]
	v_cndmask_b32_e64 v171, v171, v232, s[6:7]
	v_cndmask_b32_e64 v170, v170, v232, s[6:7]
	v_perm_b32 v33, v61, v33, s85
	v_cndmask_b32_e64 v173, v75, v232, s[6:7]
	v_cndmask_b32_e64 v172, v74, v232, s[6:7]
	v_pk_mul_f32 v[174:175], v[76:77], v[170:171]
	v_mov_b32_e32 v74, v76
	v_mov_b32_e32 v75, v76
	v_perm_b32 v168, v47, v39, s101
	v_or_b32_e32 v168, v33, v168
	v_pk_mul_f32 v[176:177], v[74:75], v[172:173]
	v_add_f32_e32 v47, s100, v175
	v_add_f32_e32 v33, s100, v177
	v_add_f32_e32 v39, s100, v176
	v_add_f32_e32 v61, s100, v174
	v_pk_fma_f32 v[56:57], v[56:57], v[0:1], v[4:5]
	v_pk_fma_f32 v[0:1], v[40:41], v[0:1], v[4:5]
	v_perm_b32 v33, v33, v61, s85
	v_lshl_add_u64 v[174:175], v[92:93], 0, v[162:163]
	v_cvt_pk_f16_f32 v165, v164, v165
	v_cvt_pk_f16_f32 v164, v166, v167
	v_cvt_pk_f16_f32 v167, v172, v173
	v_cvt_pk_f16_f32 v166, v170, v171
	v_pk_fma_f32 v[58:59], v[58:59], v[2:3], v[6:7]
	v_pk_fma_f32 v[2:3], v[42:43], v[2:3], v[6:7]
	v_cndmask_b32_e64 v5, v1, v232, s[6:7]
	v_cndmask_b32_e64 v4, v0, v232, s[6:7]
	v_perm_b32 v169, v39, v47, s101
	v_or_b32_e32 v169, v33, v169
	v_permlane16_swap_b32_e32 v164, v166
	v_permlane16_swap_b32_e32 v165, v167
	v_lshl_add_u64 v[170:171], v[174:175], 1, s[60:61]
	v_cndmask_b32_e64 v57, v57, v232, s[6:7]
	v_cndmask_b32_e64 v56, v56, v232, s[6:7]
	v_cndmask_b32_e64 v3, v3, v232, s[6:7]
	v_cndmask_b32_e64 v2, v2, v232, s[6:7]
	v_pk_mul_f32 v[0:1], v[128:129], v[4:5] op_sel_hi:[0,1]
	global_store_dwordx4 v[170:171], v[164:167], off
	v_permlane16_swap_b32_e32 v168, v169
	s_nop 0
	v_lshl_add_u64 v[164:165], s[72:73], 0, v[174:175]
	v_cndmask_b32_e64 v59, v59, v232, s[6:7]
	v_cndmask_b32_e64 v58, v58, v232, s[6:7]
	v_pk_mul_f32 v[166:167], v[60:61], v[56:57] op_sel_hi:[0,1]
	v_pk_mul_f32 v[6:7], v[128:129], v[2:3] op_sel_hi:[0,1]
	v_add_f32_e32 v1, s100, v1
	global_store_dwordx2 v[164:165], v[168:169], off
	v_pk_mul_f32 v[164:165], v[60:61], v[58:59] op_sel_hi:[0,1]
	v_add_f32_e32 v39, s100, v167
	v_add_f32_e32 v7, s100, v7
	v_add_f32_e32 v6, s100, v6
	v_add_f32_e32 v0, s100, v0
	v_add_f32_e32 v33, s100, v166
	v_add_f32_e32 v47, s100, v164
	v_add_f32_e32 v61, s100, v165
	v_perm_b32 v0, v7, v0, s85
	v_perm_b32 v33, v61, v33, s85
	v_perm_b32 v165, v6, v1, s101
	v_or_b32_e32 v165, v0, v165
	v_lshl_add_u64 v[6:7], v[62:63], 0, v[162:163]
	v_cvt_pk_f16_f32 v1, v58, v59
	v_cvt_pk_f16_f32 v0, v56, v57
	v_cvt_pk_f16_f32 v3, v2, v3
	v_cvt_pk_f16_f32 v2, v4, v5
	v_perm_b32 v164, v47, v39, s101
	v_or_b32_e32 v164, v33, v164
	s_nop 0
	v_permlane16_swap_b32_e32 v0, v2
	v_permlane16_swap_b32_e32 v1, v3
	v_lshl_add_u64 v[4:5], v[6:7], 1, s[60:61]
	global_store_dwordx4 v[4:5], v[0:3], off
	v_permlane16_swap_b32_e32 v164, v165
	s_nop 0
	v_lshl_add_u64 v[0:1], s[72:73], 0, v[6:7]
	global_store_dwordx2 v[0:1], v[164:165], off
	v_mov_b32_e32 v0, v188
	v_mov_b32_e32 v1, v189
	v_mov_b32_e32 v2, v190
	v_mov_b32_e32 v3, v191
	v_mov_b32_e32 v4, v192
	v_mov_b32_e32 v5, v193
	v_mov_b32_e32 v6, v194
	v_mov_b32_e32 v7, v195
	v_sub_f32_e32 v43, v137, v38
	v_sub_f32_e32 v42, v136, v38
	v_sub_f32_e32 v57, v139, v38
	v_sub_f32_e32 v56, v138, v38
	v_pk_mul_f32 v[56:57], v[160:161], v[56:57]
	v_pk_mul_f32 v[42:43], v[140:141], v[42:43]
	v_lshl_add_u64 v[40:41], v[112:113], 0, s[96:97]
	v_pk_mul_f32 v[20:21], v[144:145], v[20:21]
	v_pk_fma_f32 v[42:43], v[42:43], v[2:3], v[6:7]
	v_pk_fma_f32 v[56:57], v[56:57], v[0:1], v[4:5]
	v_cndmask_b32_e64 v43, v43, v232, s[6:7]
	v_cndmask_b32_e64 v59, v57, v232, s[6:7]
	v_cndmask_b32_e64 v58, v56, v232, s[6:7]
	v_cndmask_b32_e64 v42, v42, v232, s[6:7]
	v_pk_mul_f32 v[56:57], v[142:143], v[42:43]
	v_pk_mul_f32 v[136:137], v[114:115], v[58:59]
	v_add_f32_e32 v47, s100, v56
	v_add_f32_e32 v33, s100, v136
	v_add_f32_e32 v56, s100, v57
	v_add_f32_e32 v39, s100, v137
	v_perm_b32 v33, v56, v33, s85
	v_sub_f32_e32 v57, v133, v32
	v_sub_f32_e32 v56, v132, v32
	v_sub_f32_e32 v133, v135, v32
	v_sub_f32_e32 v132, v134, v32
	v_pk_mul_f32 v[56:57], v[158:159], v[56:57]
	v_pk_mul_f32 v[132:133], v[144:145], v[132:133]
	v_pk_fma_f32 v[56:57], v[56:57], v[0:1], v[4:5]
	v_pk_fma_f32 v[132:133], v[132:133], v[2:3], v[6:7]
	v_cndmask_b32_e64 v135, v57, v232, s[6:7]
	v_cndmask_b32_e64 v134, v56, v232, s[6:7]
	v_cndmask_b32_e64 v133, v133, v232, s[6:7]
	v_cndmask_b32_e64 v132, v132, v232, s[6:7]
	v_pk_mul_f32 v[56:57], v[44:45], v[134:135]
	v_perm_b32 v136, v47, v39, s101
	v_or_b32_e32 v136, v33, v136
	v_pk_mul_f32 v[138:139], v[146:147], v[132:133]
	v_add_f32_e32 v47, s100, v57
	v_add_f32_e32 v33, s100, v139
	v_add_f32_e32 v39, s100, v138
	v_add_f32_e32 v56, s100, v56
	v_perm_b32 v33, v33, v56, s85
	v_lshl_add_u64 v[138:139], v[96:97], 0, v[40:41]
	v_cvt_pk_f16_f32 v57, v42, v43
	v_cvt_pk_f16_f32 v56, v58, v59
	v_cvt_pk_f16_f32 v59, v132, v133
	v_cvt_pk_f16_f32 v58, v134, v135
	v_perm_b32 v137, v39, v47, s101
	v_or_b32_e32 v137, v33, v137
	s_nop 0
	v_permlane16_swap_b32_e32 v56, v58
	v_permlane16_swap_b32_e32 v57, v59
	v_lshl_add_u64 v[42:43], v[138:139], 1, s[60:61]
	global_store_dwordx4 v[42:43], v[56:59], off
	v_permlane16_swap_b32_e32 v136, v137
	v_lshl_add_u64 v[42:43], s[72:73], 0, v[138:139]
	global_store_dwordx2 v[42:43], v[136:137], off
	v_sub_f32_e32 v43, v119, v98
	v_sub_f32_e32 v42, v118, v98
	v_sub_f32_e32 v57, v117, v98
	v_sub_f32_e32 v56, v116, v98
	v_pk_mul_f32 v[56:57], v[156:157], v[56:57]
	v_pk_mul_f32 v[42:43], v[120:121], v[42:43]
	v_pk_fma_f32 v[56:57], v[56:57], v[0:1], v[4:5]
	v_pk_fma_f32 v[42:43], v[42:43], v[2:3], v[6:7]
	v_cndmask_b32_e64 v59, v57, v232, s[6:7]
	v_cndmask_b32_e64 v58, v56, v232, s[6:7]
	v_cndmask_b32_e64 v43, v43, v232, s[6:7]
	v_cndmask_b32_e64 v42, v42, v232, s[6:7]
	v_pk_mul_f32 v[56:57], v[122:123], v[42:43]
	v_pk_mul_f32 v[116:117], v[148:149], v[58:59]
	v_add_f32_e32 v47, s100, v56
	v_add_f32_e32 v33, s100, v116
	v_add_f32_e32 v56, s100, v57
	v_add_f32_e32 v39, s100, v117
	v_perm_b32 v33, v56, v33, s85
	v_sub_f32_e32 v57, v101, v46
	v_sub_f32_e32 v56, v100, v46
	v_sub_f32_e32 v101, v103, v46
	v_sub_f32_e32 v100, v102, v46
	v_pk_mul_f32 v[56:57], v[154:155], v[56:57]
	v_pk_mul_f32 v[100:101], v[104:105], v[100:101]
	v_pk_fma_f32 v[56:57], v[56:57], v[0:1], v[4:5]
	v_pk_fma_f32 v[100:101], v[100:101], v[2:3], v[6:7]
	v_cndmask_b32_e64 v103, v57, v232, s[6:7]
	v_cndmask_b32_e64 v102, v56, v232, s[6:7]
	v_cndmask_b32_e64 v101, v101, v232, s[6:7]
	v_cndmask_b32_e64 v100, v100, v232, s[6:7]
	v_pk_mul_f32 v[56:57], v[108:109], v[102:103]
	v_perm_b32 v116, v47, v39, s101
	v_or_b32_e32 v116, v33, v116
	v_pk_mul_f32 v[118:119], v[106:107], v[100:101]
	v_add_f32_e32 v47, s100, v57
	v_add_f32_e32 v33, s100, v119
	v_add_f32_e32 v39, s100, v118
	v_add_f32_e32 v56, s100, v56
	v_perm_b32 v33, v33, v56, s85
	v_lshl_add_u64 v[118:119], v[124:125], 0, v[40:41]
	v_cvt_pk_f16_f32 v57, v42, v43
	v_cvt_pk_f16_f32 v56, v58, v59
	v_cvt_pk_f16_f32 v59, v100, v101
	v_cvt_pk_f16_f32 v58, v102, v103
	v_perm_b32 v117, v39, v47, s101
	v_or_b32_e32 v117, v33, v117
	s_nop 0
	v_permlane16_swap_b32_e32 v56, v58
	v_permlane16_swap_b32_e32 v57, v59
	v_lshl_add_u64 v[42:43], v[118:119], 1, s[60:61]
	global_store_dwordx4 v[42:43], v[56:59], off
	v_permlane16_swap_b32_e32 v116, v117
	v_lshl_add_u64 v[42:43], s[72:73], 0, v[118:119]
	global_store_dwordx2 v[42:43], v[116:117], off
	v_sub_f32_e32 v43, v87, v126
	v_sub_f32_e32 v42, v86, v126
	v_sub_f32_e32 v57, v85, v126
	v_sub_f32_e32 v56, v84, v126
	v_pk_mul_f32 v[56:57], v[152:153], v[56:57]
	v_pk_mul_f32 v[42:43], v[88:89], v[42:43]
	v_pk_fma_f32 v[56:57], v[56:57], v[0:1], v[4:5]
	v_pk_fma_f32 v[42:43], v[42:43], v[2:3], v[6:7]
	v_cndmask_b32_e64 v59, v57, v232, s[6:7]
	v_cndmask_b32_e64 v58, v56, v232, s[6:7]
	v_cndmask_b32_e64 v43, v43, v232, s[6:7]
	v_cndmask_b32_e64 v42, v42, v232, s[6:7]
	v_pk_mul_f32 v[56:57], v[90:91], v[42:43]
	v_pk_mul_f32 v[84:85], v[150:151], v[58:59]
	v_add_f32_e32 v47, s100, v56
	v_add_f32_e32 v33, s100, v84
	v_add_f32_e32 v56, s100, v57
	v_add_f32_e32 v39, s100, v85
	v_perm_b32 v33, v56, v33, s85
	v_sub_f32_e32 v57, v69, v110
	v_sub_f32_e32 v56, v68, v110
	v_sub_f32_e32 v69, v71, v110
	v_sub_f32_e32 v68, v70, v110
	v_pk_mul_f32 v[56:57], v[130:131], v[56:57]
	v_pk_mul_f32 v[68:69], v[72:73], v[68:69]
	v_pk_fma_f32 v[56:57], v[56:57], v[0:1], v[4:5]
	v_pk_fma_f32 v[68:69], v[68:69], v[2:3], v[6:7]
	v_cndmask_b32_e64 v71, v57, v232, s[6:7]
	v_cndmask_b32_e64 v70, v56, v232, s[6:7]
	v_cndmask_b32_e64 v69, v69, v232, s[6:7]
	v_cndmask_b32_e64 v68, v68, v232, s[6:7]
	v_pk_mul_f32 v[56:57], v[76:77], v[70:71]
	v_perm_b32 v84, v47, v39, s101
	v_or_b32_e32 v84, v33, v84
	v_pk_mul_f32 v[86:87], v[74:75], v[68:69]
	v_add_f32_e32 v47, s100, v57
	v_add_f32_e32 v33, s100, v87
	v_add_f32_e32 v39, s100, v86
	v_add_f32_e32 v56, s100, v56
	v_perm_b32 v33, v33, v56, s85
	v_lshl_add_u64 v[86:87], v[92:93], 0, v[40:41]
	v_cvt_pk_f16_f32 v57, v42, v43
	v_cvt_pk_f16_f32 v56, v58, v59
	v_cvt_pk_f16_f32 v59, v68, v69
	v_cvt_pk_f16_f32 v58, v70, v71
	v_perm_b32 v85, v39, v47, s101
	v_or_b32_e32 v85, v33, v85
	s_nop 0
	v_permlane16_swap_b32_e32 v56, v58
	v_permlane16_swap_b32_e32 v57, v59
	v_lshl_add_u64 v[42:43], v[86:87], 1, s[60:61]
	global_store_dwordx4 v[42:43], v[56:59], off
	v_permlane16_swap_b32_e32 v84, v85
	v_lshl_add_u64 v[42:43], s[72:73], 0, v[86:87]
	global_store_dwordx2 v[42:43], v[84:85], off
	v_sub_f32_e32 v43, v55, v78
	v_sub_f32_e32 v42, v54, v78
	v_pk_mul_f32 v[42:43], v[78:79], v[42:43] op_sel:[1,0]
	v_pk_fma_f32 v[52:53], v[52:53], v[0:1], v[4:5]
	v_pk_fma_f32 v[0:1], v[12:13], v[0:1], v[4:5]
	v_pk_fma_f32 v[42:43], v[42:43], v[2:3], v[6:7]
	v_pk_fma_f32 v[2:3], v[14:15], v[2:3], v[6:7]
	v_cndmask_b32_e64 v5, v1, v232, s[6:7]
	v_cndmask_b32_e64 v4, v0, v232, s[6:7]
	v_cndmask_b32_e64 v53, v53, v232, s[6:7]
	v_cndmask_b32_e64 v52, v52, v232, s[6:7]
	v_cndmask_b32_e64 v3, v3, v232, s[6:7]
	v_cndmask_b32_e64 v2, v2, v232, s[6:7]
	v_pk_mul_f32 v[0:1], v[128:129], v[4:5] op_sel_hi:[0,1]
	v_cndmask_b32_e64 v43, v43, v232, s[6:7]
	v_cndmask_b32_e64 v42, v42, v232, s[6:7]
	v_pk_mul_f32 v[56:57], v[60:61], v[52:53] op_sel_hi:[0,1]
	v_pk_mul_f32 v[6:7], v[128:129], v[2:3] op_sel_hi:[0,1]
	v_add_f32_e32 v1, s100, v1
	v_pk_mul_f32 v[54:55], v[60:61], v[42:43] op_sel_hi:[0,1]
	v_add_f32_e32 v39, s100, v57
	v_add_f32_e32 v7, s100, v7
	v_add_f32_e32 v6, s100, v6
	v_add_f32_e32 v0, s100, v0
	v_add_f32_e32 v33, s100, v56
	v_add_f32_e32 v47, s100, v54
	v_add_f32_e32 v54, s100, v55
	v_perm_b32 v0, v7, v0, s85
	v_perm_b32 v33, v54, v33, s85
	v_perm_b32 v55, v6, v1, s101
	v_or_b32_e32 v55, v0, v55
	v_lshl_add_u64 v[6:7], v[62:63], 0, v[40:41]
	v_cvt_pk_f16_f32 v1, v42, v43
	v_cvt_pk_f16_f32 v0, v52, v53
	v_cvt_pk_f16_f32 v3, v2, v3
	v_cvt_pk_f16_f32 v2, v4, v5
	v_perm_b32 v54, v47, v39, s101
	v_or_b32_e32 v54, v33, v54
	s_nop 0
	v_permlane16_swap_b32_e32 v0, v2
	v_permlane16_swap_b32_e32 v1, v3
	v_lshl_add_u64 v[4:5], v[6:7], 1, s[60:61]
	global_store_dwordx4 v[4:5], v[0:3], off
	v_permlane16_swap_b32_e32 v54, v55
	s_nop 0
	v_lshl_add_u64 v[0:1], s[72:73], 0, v[6:7]
	global_store_dwordx2 v[0:1], v[54:55], off
	v_mov_b32_e32 v0, v196
	v_mov_b32_e32 v1, v197
	v_mov_b32_e32 v2, v198
	v_mov_b32_e32 v3, v199
	v_mov_b32_e32 v4, v200
	v_mov_b32_e32 v5, v201
	v_mov_b32_e32 v6, v202
	v_mov_b32_e32 v7, v203
	v_sub_f32_e32 v15, v17, v38
	v_sub_f32_e32 v14, v16, v38
	v_sub_f32_e32 v17, v19, v38
	v_sub_f32_e32 v16, v18, v38
	v_pk_mul_f32 v[16:17], v[160:161], v[16:17]
	v_pk_mul_f32 v[14:15], v[140:141], v[14:15]
	v_lshl_add_u64 v[12:13], v[112:113], 0, s[4:5]
	v_pk_fma_f32 v[16:17], v[16:17], v[0:1], v[4:5]
	v_pk_fma_f32 v[14:15], v[14:15], v[2:3], v[6:7]
	v_cndmask_b32_e64 v17, v17, v232, s[6:7]
	v_cndmask_b32_e64 v16, v16, v232, s[6:7]
	v_cndmask_b32_e64 v15, v15, v232, s[6:7]
	v_cndmask_b32_e64 v14, v14, v232, s[6:7]
	v_pk_mul_f32 v[34:35], v[114:115], v[16:17]
	v_pk_mul_f32 v[18:19], v[142:143], v[14:15]
	v_add_f32_e32 v33, s100, v34
	v_add_f32_e32 v34, s100, v35
	v_add_f32_e32 v18, s100, v18
	v_add_f32_e32 v19, s100, v19
	v_pk_fma_f32 v[22:23], v[22:23], v[0:1], v[4:5]
	v_pk_fma_f32 v[20:21], v[20:21], v[2:3], v[6:7]
	v_cndmask_b32_e64 v23, v23, v232, s[6:7]
	v_cndmask_b32_e64 v22, v22, v232, s[6:7]
	v_perm_b32 v19, v19, v33, s85
	v_cndmask_b32_e64 v21, v21, v232, s[6:7]
	v_cndmask_b32_e64 v20, v20, v232, s[6:7]
	v_pk_mul_f32 v[32:33], v[44:45], v[22:23]
	v_perm_b32 v18, v18, v34, s101
	v_or_b32_e32 v18, v19, v18
	v_pk_mul_f32 v[34:35], v[146:147], v[20:21]
	v_add_f32_e32 v33, s100, v33
	v_add_f32_e32 v19, s100, v35
	v_add_f32_e32 v34, s100, v34
	v_add_f32_e32 v32, s100, v32
	v_perm_b32 v19, v19, v32, s85
	v_perm_b32 v33, v34, v33, s101
	v_or_b32_e32 v19, v19, v33
	v_lshl_add_u64 v[32:33], v[96:97], 0, v[12:13]
	v_cvt_pk_f16_f32 v15, v14, v15
	v_cvt_pk_f16_f32 v14, v16, v17
	v_cvt_pk_f16_f32 v17, v20, v21
	v_cvt_pk_f16_f32 v16, v22, v23
	s_nop 1
	v_permlane16_swap_b32_e32 v14, v16
	v_permlane16_swap_b32_e32 v15, v17
	v_lshl_add_u64 v[20:21], v[32:33], 1, s[60:61]
	global_store_dwordx4 v[20:21], v[14:17], off
	v_permlane16_swap_b32_e32 v18, v19
	s_nop 0
	v_lshl_add_u64 v[14:15], s[72:73], 0, v[32:33]
	v_sub_f32_e32 v17, v25, v98
	v_sub_f32_e32 v16, v24, v98
	global_store_dwordx2 v[14:15], v[18:19], off
	v_sub_f32_e32 v15, v27, v98
	v_sub_f32_e32 v14, v26, v98
	v_pk_mul_f32 v[16:17], v[156:157], v[16:17]
	v_pk_mul_f32 v[14:15], v[120:121], v[14:15]
	v_pk_fma_f32 v[16:17], v[16:17], v[0:1], v[4:5]
	v_pk_fma_f32 v[14:15], v[14:15], v[2:3], v[6:7]
	v_cndmask_b32_e64 v17, v17, v232, s[6:7]
	v_cndmask_b32_e64 v16, v16, v232, s[6:7]
	v_cndmask_b32_e64 v15, v15, v232, s[6:7]
	v_cndmask_b32_e64 v14, v14, v232, s[6:7]
	v_pk_mul_f32 v[20:21], v[148:149], v[16:17]
	v_pk_mul_f32 v[18:19], v[122:123], v[14:15]
	v_add_f32_e32 v21, s100, v21
	v_add_f32_e32 v20, s100, v20
	v_add_f32_e32 v18, s100, v18
	v_add_f32_e32 v19, s100, v19
	v_perm_b32 v19, v19, v20, s85
	v_perm_b32 v18, v18, v21, s101
	v_or_b32_e32 v18, v19, v18
	v_sub_f32_e32 v21, v31, v46
	v_sub_f32_e32 v20, v30, v46
	v_sub_f32_e32 v23, v29, v46
	v_sub_f32_e32 v22, v28, v46
	v_pk_mul_f32 v[20:21], v[154:155], v[20:21]
	v_pk_mul_f32 v[22:23], v[104:105], v[22:23]
	v_pk_fma_f32 v[20:21], v[20:21], v[0:1], v[4:5]
	v_pk_fma_f32 v[22:23], v[22:23], v[2:3], v[6:7]
	v_cndmask_b32_e64 v21, v21, v232, s[6:7]
	v_cndmask_b32_e64 v20, v20, v232, s[6:7]
	v_cndmask_b32_e64 v23, v23, v232, s[6:7]
	v_cndmask_b32_e64 v22, v22, v232, s[6:7]
	v_pk_mul_f32 v[24:25], v[108:109], v[20:21]
	v_pk_mul_f32 v[26:27], v[106:107], v[22:23]
	v_add_f32_e32 v25, s100, v25
	v_add_f32_e32 v19, s100, v27
	v_add_f32_e32 v26, s100, v26
	v_add_f32_e32 v24, s100, v24
	v_perm_b32 v19, v19, v24, s85
	v_perm_b32 v25, v26, v25, s101
	v_or_b32_e32 v19, v19, v25
	v_lshl_add_u64 v[24:25], v[124:125], 0, v[12:13]
	v_cvt_pk_f16_f32 v15, v14, v15
	v_cvt_pk_f16_f32 v14, v16, v17
	v_cvt_pk_f16_f32 v17, v22, v23
	v_cvt_pk_f16_f32 v16, v20, v21
	s_nop 1
	v_permlane16_swap_b32_e32 v14, v16
	v_permlane16_swap_b32_e32 v15, v17
	v_lshl_add_u64 v[20:21], v[24:25], 1, s[60:61]
	global_store_dwordx4 v[20:21], v[14:17], off
	v_permlane16_swap_b32_e32 v18, v19
	s_nop 0
	v_lshl_add_u64 v[14:15], s[72:73], 0, v[24:25]
	v_sub_f32_e32 v17, v81, v126
	v_sub_f32_e32 v16, v80, v126
	global_store_dwordx2 v[14:15], v[18:19], off
	v_sub_f32_e32 v15, v83, v126
	v_sub_f32_e32 v14, v82, v126
	v_pk_mul_f32 v[16:17], v[152:153], v[16:17]
	v_pk_mul_f32 v[14:15], v[88:89], v[14:15]
	v_pk_fma_f32 v[16:17], v[16:17], v[0:1], v[4:5]
	v_pk_fma_f32 v[14:15], v[14:15], v[2:3], v[6:7]
	v_cndmask_b32_e64 v17, v17, v232, s[6:7]
	v_cndmask_b32_e64 v16, v16, v232, s[6:7]
	v_cndmask_b32_e64 v15, v15, v232, s[6:7]
	v_cndmask_b32_e64 v14, v14, v232, s[6:7]
	v_pk_mul_f32 v[20:21], v[150:151], v[16:17]
	v_pk_mul_f32 v[18:19], v[90:91], v[14:15]
	v_add_f32_e32 v21, s100, v21
	v_add_f32_e32 v20, s100, v20
	v_add_f32_e32 v18, s100, v18
	v_add_f32_e32 v19, s100, v19
	v_perm_b32 v19, v19, v20, s85
	v_perm_b32 v18, v18, v21, s101
	v_or_b32_e32 v18, v19, v18
	v_sub_f32_e32 v21, v65, v110
	v_sub_f32_e32 v20, v64, v110
	v_sub_f32_e32 v23, v67, v110
	v_sub_f32_e32 v22, v66, v110
	v_pk_mul_f32 v[20:21], v[130:131], v[20:21]
	v_pk_mul_f32 v[22:23], v[72:73], v[22:23]
	v_pk_fma_f32 v[20:21], v[20:21], v[0:1], v[4:5]
	v_pk_fma_f32 v[22:23], v[22:23], v[2:3], v[6:7]
	v_cndmask_b32_e64 v21, v21, v232, s[6:7]
	v_cndmask_b32_e64 v20, v20, v232, s[6:7]
	v_cndmask_b32_e64 v23, v23, v232, s[6:7]
	v_cndmask_b32_e64 v22, v22, v232, s[6:7]
	v_pk_mul_f32 v[24:25], v[76:77], v[20:21]
	v_pk_mul_f32 v[26:27], v[74:75], v[22:23]
	v_add_f32_e32 v25, s100, v25
	v_add_f32_e32 v19, s100, v27
	v_add_f32_e32 v26, s100, v26
	v_add_f32_e32 v24, s100, v24
	v_perm_b32 v19, v19, v24, s85
	v_perm_b32 v25, v26, v25, s101
	v_or_b32_e32 v19, v19, v25
	v_lshl_add_u64 v[24:25], v[92:93], 0, v[12:13]
	v_cvt_pk_f16_f32 v15, v14, v15
	v_cvt_pk_f16_f32 v14, v16, v17
	v_cvt_pk_f16_f32 v17, v22, v23
	v_cvt_pk_f16_f32 v16, v20, v21
	s_nop 1
	v_permlane16_swap_b32_e32 v14, v16
	v_permlane16_swap_b32_e32 v15, v17
	v_lshl_add_u64 v[20:21], v[24:25], 1, s[60:61]
	v_pk_fma_f32 v[8:9], v[8:9], v[0:1], v[4:5]
	global_store_dwordx4 v[20:21], v[14:17], off
	v_permlane16_swap_b32_e32 v18, v19
	s_nop 0
	v_lshl_add_u64 v[14:15], s[72:73], 0, v[24:25]
	v_pk_fma_f32 v[10:11], v[10:11], v[2:3], v[6:7]
	v_cndmask_b32_e64 v9, v9, v232, s[6:7]
	v_cndmask_b32_e64 v8, v8, v232, s[6:7]
	global_store_dwordx2 v[14:15], v[18:19], off
	v_cndmask_b32_e64 v11, v11, v232, s[6:7]
	v_cndmask_b32_e64 v10, v10, v232, s[6:7]
	v_pk_mul_f32 v[14:15], v[128:129], v[8:9] op_sel_hi:[0,1]
	v_pk_mul_f32 v[16:17], v[128:129], v[10:11] op_sel_hi:[0,1]
	v_add_f32_e32 v15, s100, v15
	v_add_f32_e32 v17, s100, v17
	v_add_f32_e32 v16, s100, v16
	v_add_f32_e32 v14, s100, v14
	v_perm_b32 v14, v17, v14, s85
	v_perm_b32 v15, v16, v15, s101
	v_or_b32_e32 v15, v14, v15
	v_sub_f32_e32 v17, v49, v78
	v_sub_f32_e32 v16, v48, v78
	v_sub_f32_e32 v19, v51, v78
	v_sub_f32_e32 v18, v50, v78
	v_pk_mul_f32 v[16:17], v[78:79], v[16:17] op_sel:[1,0]
	v_pk_mul_f32 v[18:19], v[78:79], v[18:19] op_sel:[1,0]
	v_pk_fma_f32 v[0:1], v[16:17], v[0:1], v[4:5]
	v_pk_fma_f32 v[2:3], v[18:19], v[2:3], v[6:7]
	v_cndmask_b32_e64 v5, v1, v232, s[6:7]
	v_cndmask_b32_e64 v4, v0, v232, s[6:7]
	v_cndmask_b32_e64 v3, v3, v232, s[6:7]
	v_cndmask_b32_e64 v2, v2, v232, s[6:7]
	v_pk_mul_f32 v[0:1], v[60:61], v[4:5] op_sel_hi:[0,1]
	v_pk_mul_f32 v[6:7], v[60:61], v[2:3] op_sel_hi:[0,1]
	v_add_f32_e32 v1, s100, v1
	v_add_f32_e32 v7, s100, v7
	v_add_f32_e32 v6, s100, v6
	v_add_f32_e32 v0, s100, v0
	v_perm_b32 v0, v7, v0, s85
	v_perm_b32 v14, v6, v1, s101
	v_or_b32_e32 v14, v0, v14
	v_lshl_add_u64 v[6:7], v[62:63], 0, v[12:13]
	v_cvt_pk_f16_f32 v1, v2, v3
	v_cvt_pk_f16_f32 v0, v4, v5
	v_cvt_pk_f16_f32 v3, v10, v11
	v_cvt_pk_f16_f32 v2, v8, v9
	s_nop 1
	v_permlane16_swap_b32_e32 v0, v2
	v_permlane16_swap_b32_e32 v1, v3
	v_lshl_add_u64 v[4:5], v[6:7], 1, s[60:61]
	global_store_dwordx4 v[4:5], v[0:3], off
	v_permlane16_swap_b32_e32 v14, v15
	s_nop 0
	v_lshl_add_u64 v[0:1], s[72:73], 0, v[6:7]
	global_store_dwordx2 v[0:1], v[14:15], off
